# v25 + write-through (sc1) stores for the layer-0 mixers and norm0 as well (all stores of phases 3,5,7 write-through)
# baseline (speedup 1.0000x reference)
.LBB0_147:
	s_or_b64 exec, exec, s[0:1]
	v_readlane_b32 s48, v247, 2
	v_lshlrev_b32_e32 v24, 2, v205
	v_mov_b32_e32 v25, v155
	v_readlane_b32 s56, v247, 10
	v_readlane_b32 s57, v247, 11
	s_mov_b64 s[0:1], 0x1000
	global_load_dwordx4 v[80:83], v[64:65], off offset:2048
	v_lshl_add_u64 v[28:29], s[56:57], 0, v[24:25]
	v_add_co_u32_e32 v26, vcc, s69, v28
	v_lshl_add_u64 v[30:31], v[28:29], 0, s[0:1]
	s_nop 0
	v_addc_co_u32_e32 v27, vcc, 0, v29, vcc
	global_load_dwordx4 v[40:43], v[26:27], off offset:-4096
	global_load_dwordx4 v[36:39], v24, s[56:57]
	global_load_dwordx4 v[44:47], v[26:27], off
	s_nop 0
	global_load_dwordx4 v[24:27], v24, s[56:57] offset:16
	v_lshl_add_u64 v[28:29], v[28:29], 0, s[72:73]
	global_load_dwordx4 v[32:35], v[30:31], off offset:16
	v_add_co_u32_e32 v66, vcc, 0x2000, v64
	global_load_dwordx4 v[28:31], v[28:29], off offset:16
	s_nop 0
	v_addc_co_u32_e32 v67, vcc, 0, v65, vcc
	global_load_dwordx4 v[88:91], v[66:67], off offset:2176
	v_add_co_u32_e32 v66, vcc, 0x4000, v64
	s_mov_b64 s[40:41], vcc
	v_add_co_u32_e32 v68, vcc, 0x6000, v64
	s_mov_b64 s[42:43], vcc
	v_addc_co_u32_e64 v67, vcc, 0, v65, s[40:41]
	v_add_co_u32_e32 v70, vcc, 0x8000, v64
	s_mov_b64 s[40:41], vcc
	v_addc_co_u32_e64 v69, vcc, 0, v65, s[42:43]
	global_load_dwordx4 v[92:95], v[66:67], off offset:2304
	global_load_dwordx4 v[96:99], v[68:69], off offset:2432
	v_add_co_u32_e32 v72, vcc, s11, v64
	s_mov_b64 s[42:43], vcc
	v_addc_co_u32_e64 v71, vcc, 0, v65, s[40:41]
	v_add_co_u32_e32 v66, vcc, s12, v64
	s_mov_b64 s[40:41], vcc
	v_addc_co_u32_e64 v73, vcc, 0, v65, s[42:43]
	global_load_dwordx4 v[76:79], v[70:71], off offset:2560
	s_nop 0
	global_load_dwordx4 v[72:75], v[72:73], off offset:2688
	v_add_co_u32_e32 v64, vcc, s13, v64
	v_addc_co_u32_e64 v67, s[40:41], 0, v65, s[40:41]
	s_nop 0
	v_addc_co_u32_e32 v65, vcc, 0, v65, vcc
	global_load_dwordx4 v[68:71], v[66:67], off offset:2816
	s_nop 0
	global_load_dwordx4 v[64:67], v[64:65], off offset:2944
	s_waitcnt vmcnt(14)
	v_lshlrev_b32_e32 v102, 16, v60
	v_and_b32_e32 v103, 0xffff0000, v60
	v_lshlrev_b32_e32 v100, 16, v52
	v_and_b32_e32 v101, 0xffff0000, v52
	v_lshlrev_b32_e32 v86, 16, v48
	v_and_b32_e32 v87, 0xffff0000, v48
	v_lshlrev_b32_e32 v60, 16, v61
	v_and_b32_e32 v61, 0xffff0000, v61
	v_lshlrev_b32_e32 v52, 16, v53
	v_and_b32_e32 v53, 0xffff0000, v53
	v_lshlrev_b32_e32 v106, 16, v62
	v_and_b32_e32 v107, 0xffff0000, v62
	v_lshlrev_b32_e32 v48, 16, v49
	v_and_b32_e32 v49, 0xffff0000, v49
	v_lshlrev_b32_e32 v104, 16, v54
	v_and_b32_e32 v105, 0xffff0000, v54
	v_lshlrev_b32_e32 v108, 16, v50
	v_and_b32_e32 v109, 0xffff0000, v50
	v_lshlrev_b32_e32 v62, 16, v63
	v_and_b32_e32 v63, 0xffff0000, v63
	v_lshlrev_b32_e32 v54, 16, v55
	v_and_b32_e32 v55, 0xffff0000, v55
	v_lshl_add_u64 v[84:85], s[38:39], 0, v[154:155]
	v_readlane_b32 s49, v247, 3
	v_readlane_b32 s50, v247, 4
	v_readlane_b32 s51, v247, 5
	v_readlane_b32 s52, v247, 6
	v_readlane_b32 s53, v247, 7
	v_readlane_b32 s54, v247, 8
	v_readlane_b32 s55, v247, 9
	v_readlane_b32 s58, v247, 12
	v_readlane_b32 s59, v247, 13
	s_waitcnt vmcnt(13)
	v_lshlrev_b32_e32 v110, 16, v80
	v_and_b32_e32 v111, 0xffff0000, v80
	v_lshlrev_b32_e32 v80, 16, v81
	v_and_b32_e32 v81, 0xffff0000, v81
	s_waitcnt vmcnt(12)
	v_pk_mul_f32 v[112:113], v[40:41], v[102:103]
	v_pk_mul_f32 v[114:115], v[42:43], v[60:61]
	s_waitcnt vmcnt(11)
	v_pk_fma_f32 v[100:101], v[36:37], v[100:101], v[112:113]
	v_pk_fma_f32 v[52:53], v[38:39], v[52:53], v[114:115]
	s_waitcnt vmcnt(10)
	v_pk_fma_f32 v[100:101], v[44:45], v[86:87], v[100:101]
	v_pk_fma_f32 v[52:53], v[46:47], v[48:49], v[52:53]
	v_pk_mul_f32 v[100:101], v[100:101], v[110:111]
	s_waitcnt vmcnt(8)
	v_pk_mul_f32 v[110:111], v[32:33], v[106:107]
	v_pk_mul_f32 v[52:53], v[52:53], v[80:81]
	v_pk_fma_f32 v[104:105], v[24:25], v[104:105], v[110:111]
	v_lshlrev_b32_e32 v80, 16, v82
	v_and_b32_e32 v81, 0xffff0000, v82
	s_waitcnt vmcnt(7)
	v_pk_fma_f32 v[104:105], v[28:29], v[108:109], v[104:105]
	v_lshlrev_b32_e32 v50, 16, v83
	v_pk_mul_f32 v[80:81], v[104:105], v[80:81]
	v_lshlrev_b32_e32 v104, 16, v51
	v_and_b32_e32 v105, 0xffff0000, v51
	v_and_b32_e32 v51, 0xffff0000, v83
	v_pk_mul_f32 v[82:83], v[34:35], v[62:63]
	v_readlane_b32 s60, v247, 14
	v_pk_fma_f32 v[54:55], v[26:27], v[54:55], v[82:83]
	v_mad_i64_i32 v[82:83], s[0:1], v204, s34, v[84:85]
	v_pk_fma_f32 v[54:55], v[30:31], v[104:105], v[54:55]
	v_readlane_b32 s61, v247, 15
	v_pk_mul_f32 v[54:55], v[54:55], v[50:51]
	v_cvt_pk_bf16_f32 v50, v100, v101
	v_cvt_pk_bf16_f32 v51, v52, v53
	v_cvt_pk_bf16_f32 v52, v80, v81
	v_cvt_pk_bf16_f32 v53, v54, v55
	global_store_dwordx4 v[82:83], v[50:53], off sc1
	v_lshlrev_b32_e32 v54, 16, v56
	v_and_b32_e32 v55, 0xffff0000, v56
	v_pk_mul_f32 v[52:53], v[40:41], v[86:87]
	v_pk_mul_f32 v[80:81], v[42:43], v[48:49]
	v_pk_fma_f32 v[52:53], v[36:37], v[102:103], v[52:53]
	s_waitcnt vmcnt(7)
	v_lshlrev_b32_e32 v50, 16, v88
	v_and_b32_e32 v51, 0xffff0000, v88
	v_pk_fma_f32 v[52:53], v[44:45], v[54:55], v[52:53]
	v_lshlrev_b32_e32 v56, 16, v57
	v_and_b32_e32 v57, 0xffff0000, v57
	v_pk_fma_f32 v[60:61], v[38:39], v[60:61], v[80:81]
	v_pk_mul_f32 v[50:51], v[52:53], v[50:51]
	v_lshlrev_b32_e32 v52, 16, v89
	v_and_b32_e32 v53, 0xffff0000, v89
	v_pk_fma_f32 v[60:61], v[46:47], v[56:57], v[60:61]
	v_pk_mul_f32 v[82:83], v[32:33], v[108:109]
	v_pk_mul_f32 v[52:53], v[60:61], v[52:53]
	v_lshlrev_b32_e32 v60, 16, v58
	v_and_b32_e32 v61, 0xffff0000, v58
	v_pk_fma_f32 v[82:83], v[24:25], v[106:107], v[82:83]
	v_pk_mul_f32 v[88:89], v[34:35], v[104:105]
	v_lshlrev_b32_e32 v80, 16, v90
	v_and_b32_e32 v81, 0xffff0000, v90
	v_pk_fma_f32 v[82:83], v[28:29], v[60:61], v[82:83]
	v_lshlrev_b32_e32 v58, 16, v59
	v_and_b32_e32 v59, 0xffff0000, v59
	v_pk_fma_f32 v[62:63], v[26:27], v[62:63], v[88:89]
	v_pk_mul_f32 v[80:81], v[82:83], v[80:81]
	v_lshlrev_b32_e32 v82, 16, v91
	v_and_b32_e32 v83, 0xffff0000, v91
	v_pk_fma_f32 v[62:63], v[30:31], v[58:59], v[62:63]
	v_cvt_pk_bf16_f32 v50, v50, v51
	v_pk_mul_f32 v[62:63], v[62:63], v[82:83]
	v_or_b32_e32 v82, 1, v204
	v_mad_i64_i32 v[82:83], s[0:1], v82, s34, v[84:85]
	v_cvt_pk_bf16_f32 v51, v52, v53
	v_cvt_pk_bf16_f32 v52, v80, v81
	v_cvt_pk_bf16_f32 v53, v62, v63
	v_pk_mul_f32 v[62:63], v[40:41], v[54:55]
	global_store_dwordx4 v[82:83], v[50:53], off sc1
	v_pk_fma_f32 v[62:63], v[36:37], v[86:87], v[62:63]
	v_pk_mul_f32 v[80:81], v[42:43], v[56:57]
	v_lshlrev_b32_e32 v50, 16, v16
	v_and_b32_e32 v51, 0xffff0000, v16
	s_waitcnt vmcnt(7)
	v_lshlrev_b32_e32 v52, 16, v92
	v_and_b32_e32 v53, 0xffff0000, v92
	v_pk_fma_f32 v[62:63], v[44:45], v[50:51], v[62:63]
	v_pk_fma_f32 v[48:49], v[38:39], v[48:49], v[80:81]
	v_pk_mul_f32 v[52:53], v[62:63], v[52:53]
	v_lshlrev_b32_e32 v62, 16, v17
	v_and_b32_e32 v63, 0xffff0000, v17
	v_pk_mul_f32 v[82:83], v[32:33], v[60:61]
	v_lshlrev_b32_e32 v16, 16, v93
	v_and_b32_e32 v17, 0xffff0000, v93
	v_pk_fma_f32 v[48:49], v[46:47], v[62:63], v[48:49]
	v_lshlrev_b32_e32 v80, 16, v18
	v_and_b32_e32 v81, 0xffff0000, v18
	v_pk_fma_f32 v[82:83], v[24:25], v[108:109], v[82:83]
	v_lshlrev_b32_e32 v86, 16, v19
	v_and_b32_e32 v87, 0xffff0000, v19
	v_pk_mul_f32 v[18:19], v[34:35], v[58:59]
	v_pk_mul_f32 v[48:49], v[48:49], v[16:17]
	v_lshlrev_b32_e32 v16, 16, v94
	v_and_b32_e32 v17, 0xffff0000, v94
	v_pk_fma_f32 v[82:83], v[28:29], v[80:81], v[82:83]
	v_pk_fma_f32 v[18:19], v[26:27], v[104:105], v[18:19]
	v_pk_mul_f32 v[82:83], v[82:83], v[16:17]
	v_lshlrev_b32_e32 v16, 16, v95
	v_and_b32_e32 v17, 0xffff0000, v95
	v_pk_fma_f32 v[18:19], v[30:31], v[86:87], v[18:19]
	v_readlane_b32 s62, v247, 16
	v_pk_mul_f32 v[88:89], v[18:19], v[16:17]
	v_or_b32_e32 v16, 2, v204
	v_mad_i64_i32 v[90:91], s[0:1], v16, s34, v[84:85]
	v_cvt_pk_bf16_f32 v16, v52, v53
	v_cvt_pk_bf16_f32 v17, v48, v49
	v_cvt_pk_bf16_f32 v18, v82, v83
	v_cvt_pk_bf16_f32 v19, v88, v89
	global_store_dwordx4 v[90:91], v[16:19], off sc1
	v_lshlrev_b32_e32 v48, 16, v20
	v_and_b32_e32 v49, 0xffff0000, v20
	v_pk_mul_f32 v[18:19], v[40:41], v[50:51]
	v_pk_mul_f32 v[52:53], v[42:43], v[62:63]
	v_pk_fma_f32 v[18:19], v[36:37], v[54:55], v[18:19]
	s_waitcnt vmcnt(7)
	v_lshlrev_b32_e32 v16, 16, v96
	v_and_b32_e32 v17, 0xffff0000, v96
	v_pk_fma_f32 v[18:19], v[44:45], v[48:49], v[18:19]
	v_lshlrev_b32_e32 v20, 16, v21
	v_and_b32_e32 v21, 0xffff0000, v21
	v_pk_fma_f32 v[52:53], v[38:39], v[56:57], v[52:53]
	v_pk_mul_f32 v[16:17], v[18:19], v[16:17]
	v_lshlrev_b32_e32 v18, 16, v97
	v_and_b32_e32 v19, 0xffff0000, v97
	v_pk_fma_f32 v[52:53], v[46:47], v[20:21], v[52:53]
	v_pk_mul_f32 v[56:57], v[32:33], v[80:81]
	v_pk_mul_f32 v[18:19], v[52:53], v[18:19]
	v_lshlrev_b32_e32 v52, 16, v22
	v_and_b32_e32 v53, 0xffff0000, v22
	v_pk_fma_f32 v[56:57], v[24:25], v[60:61], v[56:57]
	v_pk_mul_f32 v[60:61], v[34:35], v[86:87]
	v_lshlrev_b32_e32 v54, 16, v98
	v_and_b32_e32 v55, 0xffff0000, v98
	v_pk_fma_f32 v[56:57], v[28:29], v[52:53], v[56:57]
	v_lshlrev_b32_e32 v22, 16, v23
	v_and_b32_e32 v23, 0xffff0000, v23
	v_pk_fma_f32 v[58:59], v[26:27], v[58:59], v[60:61]
	v_pk_mul_f32 v[54:55], v[56:57], v[54:55]
	v_lshlrev_b32_e32 v56, 16, v99
	v_and_b32_e32 v57, 0xffff0000, v99
	v_pk_fma_f32 v[58:59], v[30:31], v[22:23], v[58:59]
	v_cvt_pk_bf16_f32 v16, v16, v17
	v_pk_mul_f32 v[56:57], v[58:59], v[56:57]
	v_or_b32_e32 v58, 3, v204
	v_mad_i64_i32 v[58:59], s[0:1], v58, s34, v[84:85]
	v_cvt_pk_bf16_f32 v17, v18, v19
	v_cvt_pk_bf16_f32 v18, v54, v55
	v_cvt_pk_bf16_f32 v19, v56, v57
	v_pk_mul_f32 v[54:55], v[40:41], v[48:49]
	global_store_dwordx4 v[58:59], v[16:19], off sc1
	v_pk_fma_f32 v[50:51], v[36:37], v[50:51], v[54:55]
	v_pk_mul_f32 v[54:55], v[42:43], v[20:21]
	v_lshlrev_b32_e32 v16, 16, v8
	v_and_b32_e32 v17, 0xffff0000, v8
	s_waitcnt vmcnt(7)
	v_lshlrev_b32_e32 v18, 16, v76
	v_and_b32_e32 v19, 0xffff0000, v76
	v_pk_fma_f32 v[50:51], v[44:45], v[16:17], v[50:51]
	v_pk_fma_f32 v[54:55], v[38:39], v[62:63], v[54:55]
	v_pk_mul_f32 v[18:19], v[50:51], v[18:19]
	v_lshlrev_b32_e32 v50, 16, v9
	v_and_b32_e32 v51, 0xffff0000, v9
	v_pk_mul_f32 v[58:59], v[32:33], v[52:53]
	v_lshlrev_b32_e32 v8, 16, v77
	v_and_b32_e32 v9, 0xffff0000, v77
	v_pk_fma_f32 v[54:55], v[46:47], v[50:51], v[54:55]
	v_lshlrev_b32_e32 v56, 16, v10
	v_and_b32_e32 v57, 0xffff0000, v10
	v_pk_fma_f32 v[58:59], v[24:25], v[80:81], v[58:59]
	v_lshlrev_b32_e32 v60, 16, v11
	v_and_b32_e32 v61, 0xffff0000, v11
	v_pk_mul_f32 v[10:11], v[34:35], v[22:23]
	v_pk_mul_f32 v[54:55], v[54:55], v[8:9]
	v_lshlrev_b32_e32 v8, 16, v78
	v_and_b32_e32 v9, 0xffff0000, v78
	v_pk_fma_f32 v[58:59], v[28:29], v[56:57], v[58:59]
	v_pk_fma_f32 v[10:11], v[26:27], v[86:87], v[10:11]
	v_pk_mul_f32 v[58:59], v[58:59], v[8:9]
	v_lshlrev_b32_e32 v8, 16, v79
	v_and_b32_e32 v9, 0xffff0000, v79
	v_pk_fma_f32 v[10:11], v[30:31], v[60:61], v[10:11]
	v_readlane_b32 s63, v247, 17
	v_pk_mul_f32 v[62:63], v[10:11], v[8:9]
	v_or_b32_e32 v8, 4, v204
	v_mad_i64_i32 v[76:77], s[0:1], v8, s34, v[84:85]
	v_cvt_pk_bf16_f32 v8, v18, v19
	v_cvt_pk_bf16_f32 v9, v54, v55
	v_cvt_pk_bf16_f32 v10, v58, v59
	v_cvt_pk_bf16_f32 v11, v62, v63
	global_store_dwordx4 v[76:77], v[8:11], off sc1
	v_lshlrev_b32_e32 v18, 16, v12
	v_and_b32_e32 v19, 0xffff0000, v12
	v_pk_mul_f32 v[10:11], v[40:41], v[16:17]
	s_waitcnt vmcnt(7)
	v_lshlrev_b32_e32 v8, 16, v72
	v_pk_fma_f32 v[10:11], v[36:37], v[48:49], v[10:11]
	v_pk_mul_f32 v[48:49], v[42:43], v[50:51]
	v_and_b32_e32 v9, 0xffff0000, v72
	v_pk_fma_f32 v[10:11], v[44:45], v[18:19], v[10:11]
	v_lshlrev_b32_e32 v12, 16, v13
	v_and_b32_e32 v13, 0xffff0000, v13
	v_pk_fma_f32 v[20:21], v[38:39], v[20:21], v[48:49]
	v_pk_mul_f32 v[8:9], v[10:11], v[8:9]
	v_lshlrev_b32_e32 v10, 16, v73
	v_and_b32_e32 v11, 0xffff0000, v73
	v_pk_fma_f32 v[20:21], v[46:47], v[12:13], v[20:21]
	v_pk_mul_f32 v[54:55], v[32:33], v[56:57]
	v_pk_mul_f32 v[10:11], v[20:21], v[10:11]
	v_lshlrev_b32_e32 v20, 16, v14
	v_and_b32_e32 v21, 0xffff0000, v14
	v_pk_fma_f32 v[52:53], v[24:25], v[52:53], v[54:55]
	v_pk_mul_f32 v[54:55], v[34:35], v[60:61]
	v_lshlrev_b32_e32 v48, 16, v74
	v_and_b32_e32 v49, 0xffff0000, v74
	v_pk_fma_f32 v[52:53], v[28:29], v[20:21], v[52:53]
	v_lshlrev_b32_e32 v14, 16, v15
	v_and_b32_e32 v15, 0xffff0000, v15
	v_pk_fma_f32 v[22:23], v[26:27], v[22:23], v[54:55]
	v_pk_mul_f32 v[48:49], v[52:53], v[48:49]
	v_lshlrev_b32_e32 v52, 16, v75
	v_and_b32_e32 v53, 0xffff0000, v75
	v_pk_fma_f32 v[22:23], v[30:31], v[14:15], v[22:23]
	v_cvt_pk_bf16_f32 v8, v8, v9
	v_pk_mul_f32 v[22:23], v[22:23], v[52:53]
	v_or_b32_e32 v52, 5, v204
	v_mad_i64_i32 v[52:53], s[0:1], v52, s34, v[84:85]
	v_cvt_pk_bf16_f32 v9, v10, v11
	v_cvt_pk_bf16_f32 v10, v48, v49
	v_cvt_pk_bf16_f32 v11, v22, v23
	v_pk_mul_f32 v[22:23], v[40:41], v[18:19]
	global_store_dwordx4 v[52:53], v[8:11], off sc1
	v_pk_fma_f32 v[16:17], v[36:37], v[16:17], v[22:23]
	v_pk_mul_f32 v[22:23], v[42:43], v[12:13]
	v_lshlrev_b32_e32 v8, 16, v0
	v_and_b32_e32 v9, 0xffff0000, v0
	s_waitcnt vmcnt(7)
	v_lshlrev_b32_e32 v10, 16, v68
	v_and_b32_e32 v11, 0xffff0000, v68
	v_pk_fma_f32 v[16:17], v[44:45], v[8:9], v[16:17]
	v_pk_fma_f32 v[22:23], v[38:39], v[50:51], v[22:23]
	v_pk_mul_f32 v[10:11], v[16:17], v[10:11]
	v_lshlrev_b32_e32 v16, 16, v1
	v_and_b32_e32 v17, 0xffff0000, v1
	v_pk_mul_f32 v[50:51], v[32:33], v[20:21]
	v_lshlrev_b32_e32 v0, 16, v69
	v_and_b32_e32 v1, 0xffff0000, v69
	v_pk_fma_f32 v[22:23], v[46:47], v[16:17], v[22:23]
	v_lshlrev_b32_e32 v48, 16, v2
	v_and_b32_e32 v49, 0xffff0000, v2
	v_pk_fma_f32 v[50:51], v[24:25], v[56:57], v[50:51]
	v_lshlrev_b32_e32 v52, 16, v3
	v_and_b32_e32 v53, 0xffff0000, v3
	v_pk_mul_f32 v[2:3], v[34:35], v[14:15]
	v_pk_mul_f32 v[22:23], v[22:23], v[0:1]
	v_lshlrev_b32_e32 v0, 16, v70
	v_and_b32_e32 v1, 0xffff0000, v70
	v_pk_fma_f32 v[50:51], v[28:29], v[48:49], v[50:51]
	v_pk_fma_f32 v[2:3], v[26:27], v[60:61], v[2:3]
	v_pk_mul_f32 v[50:51], v[50:51], v[0:1]
	v_lshlrev_b32_e32 v0, 16, v71
	v_and_b32_e32 v1, 0xffff0000, v71
	v_pk_fma_f32 v[2:3], v[30:31], v[52:53], v[2:3]
	v_pk_mul_f32 v[8:9], v[40:41], v[8:9]
	v_pk_mul_f32 v[54:55], v[2:3], v[0:1]
	v_or_b32_e32 v0, 6, v204
	v_mad_i64_i32 v[56:57], s[0:1], v0, s34, v[84:85]
	v_cvt_pk_bf16_f32 v0, v10, v11
	v_cvt_pk_bf16_f32 v1, v22, v23
	v_cvt_pk_bf16_f32 v2, v50, v51
	v_cvt_pk_bf16_f32 v3, v54, v55
	global_store_dwordx4 v[56:57], v[0:3], off sc1
	v_pk_fma_f32 v[8:9], v[36:37], v[18:19], v[8:9]
	v_pk_mul_f32 v[10:11], v[32:33], v[48:49]
	v_lshlrev_b32_e32 v0, 16, v4
	v_and_b32_e32 v1, 0xffff0000, v4
	s_waitcnt vmcnt(7)
	v_lshlrev_b32_e32 v2, 16, v64
	v_and_b32_e32 v3, 0xffff0000, v64
	v_pk_fma_f32 v[0:1], v[44:45], v[0:1], v[8:9]
	v_pk_mul_f32 v[8:9], v[42:43], v[16:17]
	v_pk_mul_f32 v[0:1], v[0:1], v[2:3]
	v_lshlrev_b32_e32 v2, 16, v5
	v_and_b32_e32 v3, 0xffff0000, v5
	v_pk_fma_f32 v[8:9], v[38:39], v[12:13], v[8:9]
	v_lshlrev_b32_e32 v4, 16, v65
	v_and_b32_e32 v5, 0xffff0000, v65
	v_pk_fma_f32 v[2:3], v[46:47], v[2:3], v[8:9]
	v_pk_fma_f32 v[10:11], v[24:25], v[20:21], v[10:11]
	v_pk_mul_f32 v[2:3], v[2:3], v[4:5]
	v_lshlrev_b32_e32 v4, 16, v6
	v_and_b32_e32 v5, 0xffff0000, v6
	v_pk_fma_f32 v[4:5], v[28:29], v[4:5], v[10:11]
	v_pk_mul_f32 v[10:11], v[34:35], v[52:53]
	v_lshlrev_b32_e32 v8, 16, v66
	v_and_b32_e32 v9, 0xffff0000, v66
	v_lshlrev_b32_e32 v6, 16, v7
	v_and_b32_e32 v7, 0xffff0000, v7
	v_pk_fma_f32 v[10:11], v[26:27], v[14:15], v[10:11]
	v_pk_mul_f32 v[4:5], v[4:5], v[8:9]
	v_lshlrev_b32_e32 v8, 16, v67
	v_and_b32_e32 v9, 0xffff0000, v67
	v_pk_fma_f32 v[6:7], v[30:31], v[6:7], v[10:11]
	v_cvt_pk_bf16_f32 v0, v0, v1
	v_pk_mul_f32 v[6:7], v[6:7], v[8:9]
	v_or_b32_e32 v8, 7, v204
	v_mad_i64_i32 v[8:9], s[0:1], v8, s34, v[84:85]
	v_cvt_pk_bf16_f32 v1, v2, v3
	v_cvt_pk_bf16_f32 v2, v4, v5
	v_cvt_pk_bf16_f32 v3, v6, v7
	global_store_dwordx4 v[8:9], v[0:3], off sc1

.LBB0_181:
	s_or_b64 exec, exec, s[4:5]
	v_add_co_u32_e32 v28, vcc, 0x2000, v126
	s_waitcnt vmcnt(1)
	v_lshlrev_b32_e32 v110, 16, v48
	v_addc_co_u32_e32 v29, vcc, 0, v127, vcc
	global_load_dwordx4 v[134:137], v[126:127], off offset:2048
	global_load_dwordx4 v[76:79], v[28:29], off offset:2176
	v_add_co_u32_e32 v28, vcc, 0x4000, v126
	v_and_b32_e32 v111, 0xffff0000, v48
	v_lshlrev_b32_e32 v108, 16, v49
	v_and_b32_e32 v109, 0xffff0000, v49
	v_min_u32_e32 v48, s2, v128
	v_sub_u32_e64 v49, v206, 4 clamp
	v_addc_co_u32_e32 v29, vcc, 0, v127, vcc
	v_sub_u32_e32 v48, v48, v49
	v_add_co_u32_e32 v30, vcc, 0x6000, v126
	v_cvt_f32_i32_e32 v48, v48
	s_nop 0
	v_addc_co_u32_e32 v31, vcc, 0, v127, vcc
	global_load_dwordx4 v[72:75], v[28:29], off offset:2304
	global_load_dwordx4 v[60:63], v[30:31], off offset:2432
	v_add_co_u32_e32 v28, vcc, 0x8000, v126
	v_div_scale_f32 v49, s[4:5], v48, v48, 1.0
	s_nop 0
	v_addc_co_u32_e32 v29, vcc, 0, v127, vcc
	v_add_co_u32_e32 v30, vcc, s11, v126
	v_lshlrev_b32_e32 v104, 16, v50
	s_nop 0
	v_addc_co_u32_e32 v31, vcc, 0, v127, vcc
	v_and_b32_e32 v105, 0xffff0000, v50
	v_rcp_f32_e32 v50, v49
	v_add_co_u32_e32 v116, vcc, s12, v126
	v_lshlrev_b32_e32 v90, 16, v38
	s_nop 0
	v_addc_co_u32_e32 v117, vcc, 0, v127, vcc
	v_add_co_u32_e32 v118, vcc, s13, v126
	v_and_b32_e32 v91, 0xffff0000, v38
	v_lshlrev_b32_e32 v96, 16, v39
	v_and_b32_e32 v97, 0xffff0000, v39
	v_min_u32_e32 v38, s2, v123
	v_sub_u32_e64 v39, v114, 4 clamp
	v_addc_co_u32_e32 v119, vcc, 0, v127, vcc
	v_lshlrev_b32_e32 v102, 16, v51
	v_and_b32_e32 v103, 0xffff0000, v51
	v_fma_f32 v51, -v49, v50, 1.0
	v_sub_u32_e32 v38, v38, v39
	v_fmac_f32_e32 v50, v51, v50
	v_div_scale_f32 v51, vcc, 1.0, v48, 1.0
	v_cvt_f32_i32_e32 v38, v38
	v_lshlrev_b32_e32 v98, 16, v64
	v_and_b32_e32 v99, 0xffff0000, v64
	v_mul_f32_e32 v64, v51, v50
	v_lshlrev_b32_e32 v94, 16, v65
	v_and_b32_e32 v95, 0xffff0000, v65
	v_fma_f32 v65, -v49, v64, v51
	v_fmac_f32_e32 v64, v65, v50
	v_fma_f32 v49, -v49, v64, v51
	v_div_scale_f32 v39, s[4:5], v38, v38, 1.0
	v_lshlrev_b32_e32 v92, 16, v66
	v_and_b32_e32 v93, 0xffff0000, v66
	v_lshlrev_b32_e32 v88, 16, v67
	v_and_b32_e32 v89, 0xffff0000, v67
	v_div_fmas_f32 v49, v49, v50, v64
	s_waitcnt vmcnt(4)
	v_lshlrev_b32_e32 v66, 16, v52
	v_and_b32_e32 v67, 0xffff0000, v52
	v_lshlrev_b32_e32 v64, 16, v56
	v_and_b32_e32 v65, 0xffff0000, v56
	v_lshlrev_b32_e32 v80, 16, v53
	v_and_b32_e32 v81, 0xffff0000, v53
	v_lshlrev_b32_e32 v52, 16, v57
	v_and_b32_e32 v53, 0xffff0000, v57
	v_lshlrev_b32_e32 v56, 16, v58
	v_and_b32_e32 v57, 0xffff0000, v58
	v_rcp_f32_e32 v58, v39
	v_lshlrev_b32_e32 v100, 16, v68
	v_and_b32_e32 v101, 0xffff0000, v68
	v_lshlrev_b32_e32 v106, 16, v69
	v_and_b32_e32 v107, 0xffff0000, v69
	v_lshlrev_b32_e32 v68, 16, v54
	v_and_b32_e32 v69, 0xffff0000, v54
	v_lshlrev_b32_e32 v82, 16, v55
	v_and_b32_e32 v83, 0xffff0000, v55
	v_lshlrev_b32_e32 v54, 16, v59
	v_and_b32_e32 v55, 0xffff0000, v59
	v_fma_f32 v59, -v39, v58, 1.0
	v_fmac_f32_e32 v58, v59, v58
	v_div_scale_f32 v59, vcc, 1.0, v38, 1.0
	v_mul_f32_e32 v114, v59, v58
	v_fma_f32 v115, -v39, v114, v59
	v_fmac_f32_e32 v114, v115, v58
	v_fma_f32 v39, -v39, v114, v59
	v_div_fmas_f32 v39, v39, v58, v114
	v_div_fixup_f32 v144, v39, v38, 1.0
	v_lshlrev_b32_e32 v38, 16, v12
	v_and_b32_e32 v39, 0xffff0000, v12
	v_pk_add_f32 v[58:59], v[38:39], 0 op_sel_hi:[1,0]
	v_lshlrev_b32_e32 v84, 16, v36
	v_pk_add_f32 v[58:59], v[58:59], v[110:111]
	v_and_b32_e32 v85, 0xffff0000, v36
	v_pk_add_f32 v[58:59], v[58:59], v[98:99]
	v_div_fixup_f32 v120, v49, v48, 1.0
	v_pk_add_f32 v[58:59], v[58:59], v[84:85]
	v_lshlrev_b32_e32 v48, 16, v44
	v_pk_add_f32 v[58:59], v[58:59], v[66:67]
	v_and_b32_e32 v49, 0xffff0000, v44
	v_pk_add_f32 v[58:59], v[58:59], v[64:65]
	s_waitcnt vmcnt(3)
	v_lshlrev_b32_e32 v138, 16, v134
	v_pk_add_f32 v[58:59], v[58:59], v[48:49]
	v_and_b32_e32 v139, 0xffff0000, v134
	v_pk_add_f32 v[114:115], v[58:59], v[100:101]
	v_lshlrev_b32_e32 v12, 16, v13
	v_pk_fma_f32 v[58:59], v[120:121], v[114:115], v[66:67] op_sel_hi:[0,1,1] neg_lo:[0,0,1] neg_hi:[0,0,1]
	v_pk_mul_f32 v[58:59], v[58:59], v[138:139]
	v_and_b32_e32 v13, 0xffff0000, v13
	v_cvt_pk_bf16_f32 v134, v58, v59
	v_lshlrev_b32_e32 v58, 16, v32
	v_and_b32_e32 v59, 0xffff0000, v32
	v_pk_add_f32 v[38:39], v[58:59], v[38:39] neg_lo:[0,1] neg_hi:[0,1]
	v_lshlrev_b32_e32 v86, 16, v37
	v_pk_add_f32 v[138:139], v[114:115], v[38:39]
	s_waitcnt vmcnt(2)
	v_lshlrev_b32_e32 v38, 16, v76
	v_and_b32_e32 v39, 0xffff0000, v76
	v_pk_fma_f32 v[114:115], v[144:145], v[138:139], v[64:65] op_sel_hi:[0,1,1] neg_lo:[0,0,1] neg_hi:[0,0,1]
	v_pk_mul_f32 v[146:147], v[114:115], v[38:39]
	v_pk_add_f32 v[38:39], v[12:13], 0 op_sel_hi:[1,0]
	v_and_b32_e32 v87, 0xffff0000, v37
	v_pk_add_f32 v[38:39], v[38:39], v[108:109]
	v_lshlrev_b32_e32 v44, 16, v45
	v_pk_add_f32 v[38:39], v[38:39], v[94:95]
	v_and_b32_e32 v45, 0xffff0000, v45
	v_pk_add_f32 v[38:39], v[38:39], v[86:87]
	v_lshlrev_b32_e32 v36, 16, v135
	v_pk_add_f32 v[38:39], v[38:39], v[80:81]
	v_and_b32_e32 v37, 0xffff0000, v135
	v_pk_add_f32 v[38:39], v[38:39], v[52:53]
	v_lshlrev_b32_e32 v50, 16, v46
	v_pk_add_f32 v[38:39], v[38:39], v[44:45]
	v_and_b32_e32 v51, 0xffff0000, v46
	v_pk_add_f32 v[38:39], v[38:39], v[106:107]
	v_lshlrev_b32_e32 v112, 16, v70
	v_pk_fma_f32 v[114:115], v[120:121], v[38:39], v[80:81] op_sel_hi:[0,1,1] neg_lo:[0,0,1] neg_hi:[0,0,1]
	v_pk_mul_f32 v[36:37], v[114:115], v[36:37]
	v_lshlrev_b32_e32 v114, 16, v33
	v_and_b32_e32 v115, 0xffff0000, v33
	v_pk_add_f32 v[12:13], v[114:115], v[12:13] neg_lo:[0,1] neg_hi:[0,1]
	v_and_b32_e32 v113, 0xffff0000, v70
	v_pk_add_f32 v[148:149], v[38:39], v[12:13]
	v_lshlrev_b32_e32 v12, 16, v77
	v_and_b32_e32 v13, 0xffff0000, v77
	v_pk_fma_f32 v[32:33], v[144:145], v[148:149], v[52:53] op_sel_hi:[0,1,1] neg_lo:[0,0,1] neg_hi:[0,0,1]
	v_pk_mul_f32 v[150:151], v[32:33], v[12:13]
	v_lshlrev_b32_e32 v32, 16, v14
	v_and_b32_e32 v33, 0xffff0000, v14
	v_pk_add_f32 v[12:13], v[32:33], 0 op_sel_hi:[1,0]
	v_lshlrev_b32_e32 v140, 16, v136
	v_pk_add_f32 v[12:13], v[12:13], v[104:105]
	v_and_b32_e32 v141, 0xffff0000, v136
	v_pk_add_f32 v[12:13], v[12:13], v[92:93]
	v_lshlrev_b32_e32 v156, 16, v15
	v_pk_add_f32 v[12:13], v[12:13], v[90:91]
	v_and_b32_e32 v157, 0xffff0000, v15
	v_pk_add_f32 v[12:13], v[12:13], v[68:69]
	global_load_dwordx4 v[40:43], v[28:29], off offset:2560
	s_nop 0
	global_load_dwordx4 v[28:31], v[30:31], off offset:2688
	v_pk_add_f32 v[12:13], v[12:13], v[56:57]
	v_cvt_pk_bf16_f32 v135, v36, v37
	v_pk_add_f32 v[12:13], v[12:13], v[50:51]
	v_lshlrev_b32_e32 v46, 16, v47
	v_pk_add_f32 v[158:159], v[12:13], v[112:113]
	v_and_b32_e32 v47, 0xffff0000, v47
	v_pk_fma_f32 v[12:13], v[120:121], v[158:159], v[68:69] op_sel_hi:[0,1,1] neg_lo:[0,0,1] neg_hi:[0,0,1]
	v_pk_mul_f32 v[76:77], v[12:13], v[140:141]
	global_load_dwordx4 v[36:39], v[116:117], off offset:2816
	global_load_dwordx4 v[12:15], v[118:119], off offset:2944
	v_cvt_pk_bf16_f32 v136, v76, v77
	v_lshlrev_b32_e32 v76, 16, v34
	v_and_b32_e32 v77, 0xffff0000, v34
	v_pk_add_f32 v[32:33], v[76:77], v[32:33] neg_lo:[0,1] neg_hi:[0,1]
	v_lshlrev_b32_e32 v70, 16, v71
	v_pk_add_f32 v[118:119], v[158:159], v[32:33]
	v_pk_add_f32 v[32:33], v[156:157], 0 op_sel_hi:[1,0]
	v_and_b32_e32 v71, 0xffff0000, v71
	v_pk_add_f32 v[32:33], v[32:33], v[102:103]
	v_sub_u32_e64 v131, v131, 4 clamp
	v_pk_add_f32 v[32:33], v[32:33], v[88:89]
	v_lshlrev_b32_e32 v142, 16, v137
	v_pk_add_f32 v[32:33], v[32:33], v[96:97]
	v_and_b32_e32 v143, 0xffff0000, v137
	v_pk_add_f32 v[32:33], v[32:33], v[82:83]
	s_nop 0
	v_pk_add_f32 v[32:33], v[32:33], v[54:55]
	s_nop 0
	v_pk_add_f32 v[32:33], v[32:33], v[46:47]
	s_nop 0
	v_pk_add_f32 v[140:141], v[32:33], v[70:71]
	s_nop 0
	v_pk_fma_f32 v[32:33], v[120:121], v[140:141], v[82:83] op_sel_hi:[0,1,1] neg_lo:[0,0,1] neg_hi:[0,0,1]
	v_min_u32_e32 v120, s2, v122
	v_sub_u32_e32 v120, v120, v131
	v_pk_mul_f32 v[116:117], v[32:33], v[142:143]
	v_mov_b64_e32 v[32:33], s[38:39]
	v_cvt_f32_i32_e32 v120, v120
	v_cvt_pk_bf16_f32 v137, v116, v117
	v_mad_i64_i32 v[116:117], s[4:5], v204, s34, v[32:33]
	v_lshl_add_u64 v[116:117], v[116:117], 0, v[154:155]
	global_store_dwordx4 v[116:117], v[134:137], off offset:2048 sc1
	v_lshlrev_b32_e32 v116, 16, v78
	v_and_b32_e32 v117, 0xffff0000, v78
	v_pk_fma_f32 v[134:135], v[144:145], v[118:119], v[56:57] op_sel_hi:[0,1,1] neg_lo:[0,0,1] neg_hi:[0,0,1]
	v_pk_mul_f32 v[136:137], v[134:135], v[116:117]
	v_lshlrev_b32_e32 v116, 16, v35
	v_and_b32_e32 v117, 0xffff0000, v35
	v_div_scale_f32 v131, s[4:5], v120, v120, 1.0
	v_pk_add_f32 v[34:35], v[116:117], v[156:157] neg_lo:[0,1] neg_hi:[0,1]
	v_rcp_f32_e32 v142, v131
	v_pk_add_f32 v[140:141], v[140:141], v[34:35]
	v_lshlrev_b32_e32 v34, 16, v79
	v_and_b32_e32 v35, 0xffff0000, v79
	v_pk_fma_f32 v[78:79], v[144:145], v[140:141], v[54:55] op_sel_hi:[0,1,1] neg_lo:[0,0,1] neg_hi:[0,0,1]
	v_pk_mul_f32 v[34:35], v[78:79], v[34:35]
	v_or_b32_e32 v78, 1, v204
	v_cvt_pk_bf16_f32 v136, v136, v137
	v_cvt_pk_bf16_f32 v137, v34, v35
	v_fma_f32 v34, -v131, v142, 1.0
	v_mad_i64_i32 v[78:79], s[4:5], v78, s34, v[32:33]
	v_fmac_f32_e32 v142, v34, v142
	v_div_scale_f32 v34, vcc, 1.0, v120, 1.0
	v_lshl_add_u64 v[78:79], v[78:79], 0, v[154:155]
	v_cvt_pk_bf16_f32 v134, v146, v147
	v_cvt_pk_bf16_f32 v135, v150, v151
	v_mul_f32_e32 v35, v34, v142
	global_store_dwordx4 v[78:79], v[134:137], off offset:2048 sc1
	v_fma_f32 v78, -v131, v35, v34
	v_fmac_f32_e32 v35, v78, v142
	v_fma_f32 v34, -v131, v35, v34
	v_div_fmas_f32 v34, v34, v142, v35
	v_div_fixup_f32 v120, v34, v120, 1.0
	v_lshlrev_b32_e32 v34, 16, v24
	v_and_b32_e32 v35, 0xffff0000, v24
	v_pk_add_f32 v[78:79], v[34:35], v[110:111] neg_lo:[0,1] neg_hi:[0,1]
	s_nop 0
	v_pk_add_f32 v[134:135], v[138:139], v[78:79]
	s_waitcnt vmcnt(7)
	v_lshlrev_b32_e32 v78, 16, v72
	v_and_b32_e32 v79, 0xffff0000, v72
	v_pk_fma_f32 v[110:111], v[120:121], v[134:135], v[48:49] op_sel_hi:[0,1,1] neg_lo:[0,0,1] neg_hi:[0,0,1]
	v_pk_mul_f32 v[136:137], v[110:111], v[78:79]
	v_lshlrev_b32_e32 v110, 16, v25
	v_and_b32_e32 v111, 0xffff0000, v25
	v_pk_add_f32 v[24:25], v[110:111], v[108:109] neg_lo:[0,1] neg_hi:[0,1]
	v_lshlrev_b32_e32 v108, 16, v26
	v_pk_add_f32 v[138:139], v[148:149], v[24:25]
	v_lshlrev_b32_e32 v24, 16, v73
	v_and_b32_e32 v25, 0xffff0000, v73
	v_pk_fma_f32 v[72:73], v[120:121], v[138:139], v[44:45] op_sel_hi:[0,1,1] neg_lo:[0,0,1] neg_hi:[0,0,1]
	v_and_b32_e32 v109, 0xffff0000, v26
	v_pk_mul_f32 v[72:73], v[72:73], v[24:25]
	v_pk_add_f32 v[24:25], v[108:109], v[104:105] neg_lo:[0,1] neg_hi:[0,1]
	s_nop 0
	v_pk_add_f32 v[104:105], v[118:119], v[24:25]
	v_lshlrev_b32_e32 v24, 16, v74
	v_and_b32_e32 v25, 0xffff0000, v74
	v_pk_fma_f32 v[78:79], v[120:121], v[104:105], v[50:51] op_sel_hi:[0,1,1] neg_lo:[0,0,1] neg_hi:[0,0,1]
	v_pk_mul_f32 v[118:119], v[78:79], v[24:25]
	v_lshlrev_b32_e32 v78, 16, v27
	v_and_b32_e32 v79, 0xffff0000, v27
	v_pk_add_f32 v[24:25], v[78:79], v[102:103] neg_lo:[0,1] neg_hi:[0,1]
	s_nop 0
	v_pk_add_f32 v[102:103], v[140:141], v[24:25]
	v_lshlrev_b32_e32 v24, 16, v75
	v_and_b32_e32 v25, 0xffff0000, v75
	v_pk_fma_f32 v[26:27], v[120:121], v[102:103], v[46:47] op_sel_hi:[0,1,1] neg_lo:[0,0,1] neg_hi:[0,0,1]
	v_pk_mul_f32 v[74:75], v[26:27], v[24:25]
	v_or_b32_e32 v24, 2, v204
	v_mad_i64_i32 v[24:25], s[4:5], v24, s34, v[32:33]
	v_lshl_add_u64 v[140:141], v[24:25], 0, v[154:155]
	v_min_u32_e32 v24, s2, v121
	v_sub_u32_e64 v25, v129, 4 clamp
	v_sub_u32_e32 v24, v24, v25
	v_cvt_f32_i32_e32 v120, v24
	v_cvt_pk_bf16_f32 v25, v72, v73
	v_cvt_pk_bf16_f32 v24, v136, v137
	v_cvt_pk_bf16_f32 v26, v118, v119
	v_div_scale_f32 v72, s[4:5], v120, v120, 1.0
	v_rcp_f32_e32 v73, v72
	v_cvt_pk_bf16_f32 v27, v74, v75
	global_store_dwordx4 v[140:141], v[24:27], off offset:2048 sc1
	s_nop 1
	v_fma_f32 v24, -v72, v73, 1.0
	v_fmac_f32_e32 v73, v24, v73
	v_div_scale_f32 v24, vcc, 1.0, v120, 1.0
	v_mul_f32_e32 v25, v24, v73
	v_fma_f32 v26, -v72, v25, v24
	v_fmac_f32_e32 v25, v26, v73
	v_fma_f32 v24, -v72, v25, v24
	v_lshlrev_b32_e32 v26, 16, v20
	v_and_b32_e32 v27, 0xffff0000, v20
	v_div_fmas_f32 v24, v24, v73, v25
	v_pk_add_f32 v[72:73], v[26:27], v[98:99] neg_lo:[0,1] neg_hi:[0,1]
	v_div_fixup_f32 v24, v24, v120, 1.0
	v_pk_add_f32 v[98:99], v[134:135], v[72:73]
	s_waitcnt vmcnt(7)
	v_lshlrev_b32_e32 v72, 16, v60
	v_and_b32_e32 v73, 0xffff0000, v60
	v_pk_fma_f32 v[74:75], v[24:25], v[98:99], v[100:101] op_sel_hi:[0,1,1] neg_lo:[0,0,1] neg_hi:[0,0,1]
	v_pk_mul_f32 v[100:101], v[74:75], v[72:73]
	v_lshlrev_b32_e32 v74, 16, v21
	v_and_b32_e32 v75, 0xffff0000, v21
	v_pk_add_f32 v[20:21], v[74:75], v[94:95] neg_lo:[0,1] neg_hi:[0,1]
	v_lshlrev_b32_e32 v72, 16, v22
	v_pk_add_f32 v[94:95], v[138:139], v[20:21]
	v_lshlrev_b32_e32 v20, 16, v61
	v_and_b32_e32 v21, 0xffff0000, v61
	v_pk_fma_f32 v[60:61], v[24:25], v[94:95], v[106:107] op_sel_hi:[0,1,1] neg_lo:[0,0,1] neg_hi:[0,0,1]
	v_and_b32_e32 v73, 0xffff0000, v22
	v_pk_mul_f32 v[106:107], v[60:61], v[20:21]
	v_pk_add_f32 v[20:21], v[72:73], v[92:93] neg_lo:[0,1] neg_hi:[0,1]
	s_nop 0
	v_pk_add_f32 v[92:93], v[104:105], v[20:21]
	v_lshlrev_b32_e32 v20, 16, v62
	v_and_b32_e32 v21, 0xffff0000, v62
	v_pk_fma_f32 v[60:61], v[24:25], v[92:93], v[112:113] op_sel_hi:[0,1,1] neg_lo:[0,0,1] neg_hi:[0,0,1]
	v_pk_mul_f32 v[104:105], v[60:61], v[20:21]
	v_lshlrev_b32_e32 v60, 16, v23
	v_and_b32_e32 v61, 0xffff0000, v23
	v_pk_add_f32 v[20:21], v[60:61], v[88:89] neg_lo:[0,1] neg_hi:[0,1]
	s_nop 0
	v_pk_add_f32 v[88:89], v[102:103], v[20:21]
	v_lshlrev_b32_e32 v20, 16, v63
	v_and_b32_e32 v21, 0xffff0000, v63
	v_pk_fma_f32 v[22:23], v[24:25], v[88:89], v[70:71] op_sel_hi:[0,1,1] neg_lo:[0,0,1] neg_hi:[0,0,1]
	v_pk_mul_f32 v[24:25], v[22:23], v[20:21]
	v_or_b32_e32 v20, 3, v204
	v_mad_i64_i32 v[20:21], s[4:5], v20, s34, v[32:33]
	v_lshl_add_u64 v[62:63], v[20:21], 0, v[154:155]
	v_min_u32_e32 v20, s2, v133
	v_sub_u32_e32 v20, v20, v128
	v_add_u32_e32 v20, 4, v20
	v_cvt_f32_i32_e32 v70, v20
	v_cvt_pk_bf16_f32 v20, v100, v101
	v_cvt_pk_bf16_f32 v21, v106, v107
	v_cvt_pk_bf16_f32 v22, v104, v105
	v_div_scale_f32 v71, s[4:5], v70, v70, 1.0
	v_rcp_f32_e32 v100, v71
	v_cvt_pk_bf16_f32 v23, v24, v25
	global_store_dwordx4 v[62:63], v[20:23], off offset:2048 sc1
	s_nop 1
	v_fma_f32 v20, -v71, v100, 1.0
	v_fmac_f32_e32 v100, v20, v100
	v_div_scale_f32 v20, vcc, 1.0, v70, 1.0
	v_mul_f32_e32 v21, v20, v100
	v_fma_f32 v22, -v71, v21, v20
	v_fmac_f32_e32 v21, v22, v100
	v_fma_f32 v20, -v71, v21, v20
	v_div_fmas_f32 v20, v20, v100, v21
	v_div_fixup_f32 v62, v20, v70, 1.0
	v_lshlrev_b32_e32 v20, 16, v16
	v_and_b32_e32 v21, 0xffff0000, v16
	v_pk_add_f32 v[22:23], v[20:21], v[84:85] neg_lo:[0,1] neg_hi:[0,1]
	s_nop 0
	v_pk_add_f32 v[70:71], v[98:99], v[22:23]
	s_waitcnt vmcnt(7)
	v_lshlrev_b32_e32 v22, 16, v40
	v_and_b32_e32 v23, 0xffff0000, v40
	v_pk_fma_f32 v[24:25], v[62:63], v[70:71], v[58:59] op_sel_hi:[0,1,1] neg_lo:[0,0,1] neg_hi:[0,0,1]
	v_pk_mul_f32 v[58:59], v[24:25], v[22:23]
	v_lshlrev_b32_e32 v24, 16, v17
	v_and_b32_e32 v25, 0xffff0000, v17
	v_pk_add_f32 v[16:17], v[24:25], v[86:87] neg_lo:[0,1] neg_hi:[0,1]
	s_nop 0
	v_pk_add_f32 v[84:85], v[94:95], v[16:17]
	v_lshlrev_b32_e32 v16, 16, v41
	v_and_b32_e32 v17, 0xffff0000, v41
	v_pk_fma_f32 v[22:23], v[62:63], v[84:85], v[114:115] op_sel_hi:[0,1,1] neg_lo:[0,0,1] neg_hi:[0,0,1]
	v_pk_mul_f32 v[86:87], v[22:23], v[16:17]
	v_lshlrev_b32_e32 v22, 16, v18
	v_and_b32_e32 v23, 0xffff0000, v18
	v_pk_add_f32 v[16:17], v[22:23], v[90:91] neg_lo:[0,1] neg_hi:[0,1]
	s_nop 0
	v_pk_add_f32 v[90:91], v[92:93], v[16:17]
	v_lshlrev_b32_e32 v16, 16, v42
	v_and_b32_e32 v17, 0xffff0000, v42
	v_pk_fma_f32 v[40:41], v[62:63], v[90:91], v[76:77] op_sel_hi:[0,1,1] neg_lo:[0,0,1] neg_hi:[0,0,1]
	v_pk_mul_f32 v[76:77], v[40:41], v[16:17]
	v_lshlrev_b32_e32 v16, 16, v19
	v_and_b32_e32 v17, 0xffff0000, v19
	v_pk_add_f32 v[18:19], v[16:17], v[96:97] neg_lo:[0,1] neg_hi:[0,1]
	v_lshlrev_b32_e32 v40, 16, v43
	v_pk_add_f32 v[18:19], v[88:89], v[18:19]
	v_and_b32_e32 v41, 0xffff0000, v43
	v_pk_fma_f32 v[42:43], v[62:63], v[18:19], v[116:117] op_sel_hi:[0,1,1] neg_lo:[0,0,1] neg_hi:[0,0,1]
	v_pk_mul_f32 v[62:63], v[42:43], v[40:41]
	v_or_b32_e32 v40, 4, v204
	v_mad_i64_i32 v[40:41], s[4:5], v40, s34, v[32:33]
	v_lshl_add_u64 v[88:89], v[40:41], 0, v[154:155]
	v_min_u32_e32 v40, s2, v132
	v_sub_u32_e32 v40, v40, v123
	v_add_u32_e32 v40, 4, v40
	v_cvt_f32_i32_e32 v92, v40
	v_cvt_pk_bf16_f32 v40, v58, v59
	v_cvt_pk_bf16_f32 v41, v86, v87
	v_cvt_pk_bf16_f32 v42, v76, v77
	v_div_scale_f32 v58, s[4:5], v92, v92, 1.0
	v_rcp_f32_e32 v59, v58
	v_cvt_pk_bf16_f32 v43, v62, v63
	global_store_dwordx4 v[88:89], v[40:43], off offset:2048 sc1
	s_nop 1
	v_fma_f32 v40, -v58, v59, 1.0
	v_fmac_f32_e32 v59, v40, v59
	v_div_scale_f32 v40, vcc, 1.0, v92, 1.0
	v_mul_f32_e32 v41, v40, v59
	v_fma_f32 v42, -v58, v41, v40
	v_fmac_f32_e32 v41, v42, v59
	v_fma_f32 v40, -v58, v41, v40
	v_lshlrev_b32_e32 v42, 16, v8
	v_and_b32_e32 v43, 0xffff0000, v8
	v_div_fmas_f32 v40, v40, v59, v41
	v_pk_add_f32 v[42:43], v[42:43], v[66:67] neg_lo:[0,1] neg_hi:[0,1]
	v_div_fixup_f32 v40, v40, v92, 1.0
	v_pk_add_f32 v[42:43], v[70:71], v[42:43]
	v_lshlrev_b32_e32 v8, 16, v9
	v_and_b32_e32 v9, 0xffff0000, v9
	s_waitcnt vmcnt(7)
	v_lshlrev_b32_e32 v58, 16, v28
	v_and_b32_e32 v59, 0xffff0000, v28
	v_pk_fma_f32 v[34:35], v[40:41], v[42:43], v[34:35] op_sel_hi:[0,1,1] neg_lo:[0,0,1] neg_hi:[0,0,1]
	v_pk_add_f32 v[8:9], v[8:9], v[80:81] neg_lo:[0,1] neg_hi:[0,1]
	v_pk_mul_f32 v[34:35], v[34:35], v[58:59]
	v_pk_add_f32 v[58:59], v[84:85], v[8:9]
	v_lshlrev_b32_e32 v8, 16, v29
	v_and_b32_e32 v9, 0xffff0000, v29
	v_pk_fma_f32 v[28:29], v[40:41], v[58:59], v[110:111] op_sel_hi:[0,1,1] neg_lo:[0,0,1] neg_hi:[0,0,1]
	v_pk_mul_f32 v[28:29], v[28:29], v[8:9]
	v_lshlrev_b32_e32 v8, 16, v10
	v_and_b32_e32 v9, 0xffff0000, v10
	v_pk_add_f32 v[8:9], v[8:9], v[68:69] neg_lo:[0,1] neg_hi:[0,1]
	s_nop 0
	v_pk_add_f32 v[62:63], v[90:91], v[8:9]
	v_lshlrev_b32_e32 v8, 16, v30
	v_and_b32_e32 v9, 0xffff0000, v30
	v_pk_fma_f32 v[66:67], v[40:41], v[62:63], v[108:109] op_sel_hi:[0,1,1] neg_lo:[0,0,1] neg_hi:[0,0,1]
	v_pk_mul_f32 v[66:67], v[66:67], v[8:9]
	v_lshlrev_b32_e32 v8, 16, v11
	v_and_b32_e32 v9, 0xffff0000, v11
	v_pk_add_f32 v[8:9], v[8:9], v[82:83] neg_lo:[0,1] neg_hi:[0,1]
	s_nop 0
	v_pk_add_f32 v[18:19], v[18:19], v[8:9]
	v_lshlrev_b32_e32 v8, 16, v31
	v_and_b32_e32 v9, 0xffff0000, v31
	v_pk_fma_f32 v[10:11], v[40:41], v[18:19], v[78:79] op_sel_hi:[0,1,1] neg_lo:[0,0,1] neg_hi:[0,0,1]
	v_pk_mul_f32 v[30:31], v[10:11], v[8:9]
	v_or_b32_e32 v8, 5, v204
	v_mad_i64_i32 v[8:9], s[4:5], v8, s34, v[32:33]
	v_lshl_add_u64 v[40:41], v[8:9], 0, v[154:155]
	v_min_u32_e32 v8, s2, v130
	v_sub_u32_e32 v8, v8, v122
	v_add_u32_e32 v8, 4, v8
	v_cvt_f32_i32_e32 v68, v8
	v_cvt_pk_bf16_f32 v9, v28, v29
	v_cvt_pk_bf16_f32 v8, v34, v35
	v_cvt_pk_bf16_f32 v10, v66, v67
	v_div_scale_f32 v28, s[4:5], v68, v68, 1.0
	v_rcp_f32_e32 v29, v28
	v_cvt_pk_bf16_f32 v11, v30, v31
	global_store_dwordx4 v[40:41], v[8:11], off offset:2048 sc1
	s_nop 1
	v_fma_f32 v8, -v28, v29, 1.0
	v_fmac_f32_e32 v29, v8, v29
	v_div_scale_f32 v8, vcc, 1.0, v68, 1.0
	v_mul_f32_e32 v9, v8, v29
	v_fma_f32 v10, -v28, v9, v8
	v_fmac_f32_e32 v9, v10, v29
	v_fma_f32 v8, -v28, v9, v8
	v_lshlrev_b32_e32 v10, 16, v4
	v_and_b32_e32 v11, 0xffff0000, v4
	v_div_fmas_f32 v8, v8, v29, v9
	v_pk_add_f32 v[10:11], v[10:11], v[64:65] neg_lo:[0,1] neg_hi:[0,1]
	v_div_fixup_f32 v8, v8, v68, 1.0
	v_pk_add_f32 v[10:11], v[42:43], v[10:11]
	v_lshlrev_b32_e32 v4, 16, v5
	v_and_b32_e32 v5, 0xffff0000, v5
	s_waitcnt vmcnt(7)
	v_lshlrev_b32_e32 v28, 16, v36
	v_and_b32_e32 v29, 0xffff0000, v36
	v_pk_fma_f32 v[26:27], v[8:9], v[10:11], v[26:27] op_sel_hi:[0,1,1] neg_lo:[0,0,1] neg_hi:[0,0,1]
	v_pk_add_f32 v[4:5], v[4:5], v[52:53] neg_lo:[0,1] neg_hi:[0,1]
	v_pk_mul_f32 v[26:27], v[26:27], v[28:29]
	v_pk_add_f32 v[28:29], v[58:59], v[4:5]
	v_lshlrev_b32_e32 v4, 16, v37
	v_and_b32_e32 v5, 0xffff0000, v37
	v_pk_fma_f32 v[30:31], v[8:9], v[28:29], v[74:75] op_sel_hi:[0,1,1] neg_lo:[0,0,1] neg_hi:[0,0,1]
	v_pk_mul_f32 v[30:31], v[30:31], v[4:5]
	v_lshlrev_b32_e32 v4, 16, v6
	v_and_b32_e32 v5, 0xffff0000, v6
	v_pk_add_f32 v[4:5], v[4:5], v[56:57] neg_lo:[0,1] neg_hi:[0,1]
	s_nop 0
	v_pk_add_f32 v[34:35], v[62:63], v[4:5]
	v_lshlrev_b32_e32 v4, 16, v38
	v_and_b32_e32 v5, 0xffff0000, v38
	v_pk_fma_f32 v[36:37], v[8:9], v[34:35], v[72:73] op_sel_hi:[0,1,1] neg_lo:[0,0,1] neg_hi:[0,0,1]
	v_pk_mul_f32 v[36:37], v[36:37], v[4:5]
	v_lshlrev_b32_e32 v4, 16, v7
	v_and_b32_e32 v5, 0xffff0000, v7
	v_pk_add_f32 v[4:5], v[4:5], v[54:55] neg_lo:[0,1] neg_hi:[0,1]
	s_nop 0
	v_pk_add_f32 v[18:19], v[18:19], v[4:5]
	v_lshlrev_b32_e32 v4, 16, v39
	v_and_b32_e32 v5, 0xffff0000, v39
	v_pk_fma_f32 v[6:7], v[8:9], v[18:19], v[60:61] op_sel_hi:[0,1,1] neg_lo:[0,0,1] neg_hi:[0,0,1]
	v_pk_mul_f32 v[8:9], v[6:7], v[4:5]
	v_or_b32_e32 v4, 6, v204
	v_mad_i64_i32 v[4:5], s[4:5], v4, s34, v[32:33]
	v_lshl_add_u64 v[38:39], v[4:5], 0, v[154:155]
	v_add_u32_e32 v4, 11, v206
	v_min_u32_e32 v4, s2, v4
	v_sub_u32_e32 v4, v4, v121
	v_add_u32_e32 v4, 4, v4
	v_cvt_f32_i32_e32 v40, v4
	v_cvt_pk_bf16_f32 v4, v26, v27
	v_cvt_pk_bf16_f32 v5, v30, v31
	v_cvt_pk_bf16_f32 v6, v36, v37
	v_div_scale_f32 v26, s[4:5], v40, v40, 1.0
	v_rcp_f32_e32 v27, v26
	v_cvt_pk_bf16_f32 v7, v8, v9
	global_store_dwordx4 v[38:39], v[4:7], off offset:2048 sc1
	s_waitcnt vmcnt(7)
	v_lshlrev_b32_e32 v8, 16, v12
	v_and_b32_e32 v9, 0xffff0000, v12
	v_fma_f32 v4, -v26, v27, 1.0
	v_fmac_f32_e32 v27, v4, v27
	v_div_scale_f32 v4, vcc, 1.0, v40, 1.0
	v_mul_f32_e32 v5, v4, v27
	v_fma_f32 v6, -v26, v5, v4
	v_fmac_f32_e32 v5, v6, v27
	v_fma_f32 v4, -v26, v5, v4
	v_lshlrev_b32_e32 v6, 16, v0
	v_and_b32_e32 v7, 0xffff0000, v0
	v_div_fmas_f32 v4, v4, v27, v5
	v_pk_add_f32 v[6:7], v[6:7], v[48:49] neg_lo:[0,1] neg_hi:[0,1]
	v_lshlrev_b32_e32 v0, 16, v1
	v_and_b32_e32 v1, 0xffff0000, v1
	v_div_fixup_f32 v4, v4, v40, 1.0
	v_pk_add_f32 v[6:7], v[10:11], v[6:7]
	v_pk_add_f32 v[0:1], v[0:1], v[44:45] neg_lo:[0,1] neg_hi:[0,1]
	v_pk_fma_f32 v[6:7], v[4:5], v[6:7], v[20:21] op_sel_hi:[0,1,1] neg_lo:[0,0,1] neg_hi:[0,0,1]
	v_pk_add_f32 v[0:1], v[28:29], v[0:1]
	v_pk_mul_f32 v[6:7], v[6:7], v[8:9]
	v_lshlrev_b32_e32 v8, 16, v13
	v_and_b32_e32 v9, 0xffff0000, v13
	v_pk_fma_f32 v[0:1], v[4:5], v[0:1], v[24:25] op_sel_hi:[0,1,1] neg_lo:[0,0,1] neg_hi:[0,0,1]
	v_pk_mul_f32 v[8:9], v[0:1], v[8:9]
	v_lshlrev_b32_e32 v0, 16, v2
	v_and_b32_e32 v1, 0xffff0000, v2
	v_pk_add_f32 v[0:1], v[0:1], v[50:51] neg_lo:[0,1] neg_hi:[0,1]
	v_lshlrev_b32_e32 v10, 16, v14
	v_pk_add_f32 v[0:1], v[34:35], v[0:1]
	v_and_b32_e32 v11, 0xffff0000, v14
	v_pk_fma_f32 v[0:1], v[4:5], v[0:1], v[22:23] op_sel_hi:[0,1,1] neg_lo:[0,0,1] neg_hi:[0,0,1]
	v_pk_mul_f32 v[10:11], v[0:1], v[10:11]
	v_lshlrev_b32_e32 v0, 16, v3
	v_and_b32_e32 v1, 0xffff0000, v3
	v_pk_add_f32 v[0:1], v[0:1], v[46:47] neg_lo:[0,1] neg_hi:[0,1]
	v_lshlrev_b32_e32 v2, 16, v15
	v_pk_add_f32 v[0:1], v[18:19], v[0:1]
	v_and_b32_e32 v3, 0xffff0000, v15
	v_pk_fma_f32 v[0:1], v[4:5], v[0:1], v[16:17] op_sel_hi:[0,1,1] neg_lo:[0,0,1] neg_hi:[0,0,1]
	v_pk_mul_f32 v[4:5], v[0:1], v[2:3]
	v_or_b32_e32 v0, 7, v204
	v_mad_i64_i32 v[0:1], s[4:5], v0, s34, v[32:33]
	v_lshl_add_u64 v[12:13], v[0:1], 0, v[154:155]
	v_cvt_pk_bf16_f32 v0, v6, v7
	v_cvt_pk_bf16_f32 v1, v8, v9
	v_cvt_pk_bf16_f32 v2, v10, v11
	v_cvt_pk_bf16_f32 v3, v4, v5
	s_mov_b64 s[4:5], 0
	global_store_dwordx4 v[12:13], v[0:3], off offset:2048 sc1

.LBB0_204:
	s_or_b64 exec, exec, s[6:7]
	global_load_dwordx4 v[68:71], v[126:127], off offset:2048
	v_add_co_u32_e32 v20, vcc, 0x2000, v126
	s_mov_b64 s[40:41], vcc
	v_min_u32_e32 v21, s2, v96
	v_sub_u32_e64 v23, v206, 2 clamp
	v_add_co_u32_e32 v22, vcc, 0x4000, v126
	s_mov_b64 s[42:43], vcc
	v_sub_u32_e32 v23, v21, v23
	v_addc_co_u32_e64 v21, vcc, 0, v127, s[40:41]
	global_load_dwordx4 v[98:101], v[20:21], off offset:2176
	s_waitcnt vmcnt(2)
	v_lshlrev_b32_e32 v74, 16, v44
	v_and_b32_e32 v75, 0xffff0000, v44
	v_add_co_u32_e32 v40, vcc, 0x6000, v126
	v_cvt_f32_i32_e32 v44, v23
	s_mov_b64 s[40:41], vcc
	v_addc_co_u32_e64 v23, vcc, 0, v127, s[42:43]
	v_add_co_u32_e32 v20, vcc, 0x8000, v126
	s_mov_b64 s[42:43], vcc
	v_addc_co_u32_e64 v41, vcc, 0, v127, s[40:41]
	v_lshlrev_b32_e32 v88, 16, v36
	v_and_b32_e32 v89, 0xffff0000, v36
	v_lshlrev_b32_e32 v72, 16, v48
	v_and_b32_e32 v73, 0xffff0000, v48
	v_add_co_u32_e32 v42, vcc, s11, v126
	v_div_scale_f32 v48, s[6:7], v44, v44, 1.0
	v_lshlrev_b32_e32 v76, 16, v32
	v_and_b32_e32 v77, 0xffff0000, v32
	v_lshlrev_b32_e32 v80, 16, v33
	v_and_b32_e32 v81, 0xffff0000, v33
	v_pk_add_f32 v[32:33], v[88:89], 0 op_sel_hi:[1,0]
	s_mov_b64 s[40:41], vcc
	v_addc_co_u32_e64 v21, vcc, 0, v127, s[42:43]
	v_rcp_f32_e32 v82, v48
	v_pk_add_f32 v[32:33], v[32:33], v[76:77]
	global_load_dwordx4 v[64:67], v[22:23], off offset:2304
	global_load_dwordx4 v[60:63], v[40:41], off offset:2432
	v_add_co_u32_e32 v22, vcc, s12, v126
	v_pk_add_f32 v[32:33], v[32:33], v[74:75]
	s_mov_b64 s[42:43], vcc
	v_addc_co_u32_e64 v43, vcc, 0, v127, s[40:41]
	v_pk_add_f32 v[104:105], v[32:33], v[72:73]
	v_add_co_u32_e32 v32, vcc, s13, v126
	v_addc_co_u32_e64 v23, s[42:43], 0, v127, s[42:43]
	global_load_dwordx4 v[56:59], v[20:21], off offset:2560
	global_load_dwordx4 v[52:55], v[42:43], off offset:2688
	v_addc_co_u32_e32 v33, vcc, 0, v127, vcc
	global_load_dwordx4 v[40:43], v[22:23], off offset:2816
	s_nop 0
	global_load_dwordx4 v[20:23], v[32:33], off offset:2944
	v_fma_f32 v32, -v48, v82, 1.0
	v_div_scale_f32 v79, s[40:41], 1.0, v44, 1.0
	v_fmac_f32_e32 v82, v32, v82
	v_mul_f32_e32 v32, v79, v82
	v_fma_f32 v33, -v48, v32, v79
	v_fmac_f32_e32 v32, v33, v82
	v_fma_f32 v33, -v48, v32, v79
	s_mov_b64 vcc, s[40:41]
	v_div_fmas_f32 v32, v33, v82, v32
	v_lshlrev_b32_e32 v102, 16, v37
	v_and_b32_e32 v103, 0xffff0000, v37
	v_div_fixup_f32 v32, v32, v44, 1.0
	v_pk_add_f32 v[36:37], v[102:103], 0 op_sel_hi:[1,0]
	v_pk_fma_f32 v[82:83], v[32:33], v[104:105], v[74:75] op_sel_hi:[0,1,1] neg_lo:[0,0,1] neg_hi:[0,0,1]
	v_pk_add_f32 v[36:37], v[36:37], v[80:81]
	v_lshlrev_b32_e32 v108, 16, v38
	v_and_b32_e32 v109, 0xffff0000, v38
	v_lshlrev_b32_e32 v110, 16, v34
	v_and_b32_e32 v111, 0xffff0000, v34
	s_waitcnt vmcnt(7)
	v_lshlrev_b32_e32 v84, 16, v68
	v_and_b32_e32 v85, 0xffff0000, v68
	v_pk_mul_f32 v[106:107], v[82:83], v[84:85]
	v_lshlrev_b32_e32 v82, 16, v45
	v_and_b32_e32 v83, 0xffff0000, v45
	v_pk_add_f32 v[44:45], v[36:37], v[82:83]
	v_lshlrev_b32_e32 v36, 16, v49
	v_and_b32_e32 v37, 0xffff0000, v49
	v_pk_add_f32 v[48:49], v[44:45], v[36:37]
	v_lshlrev_b32_e32 v44, 16, v69
	v_and_b32_e32 v45, 0xffff0000, v69
	v_pk_fma_f32 v[68:69], v[32:33], v[48:49], v[82:83] op_sel_hi:[0,1,1] neg_lo:[0,0,1] neg_hi:[0,0,1]
	v_pk_mul_f32 v[68:69], v[68:69], v[44:45]
	v_pk_add_f32 v[44:45], v[108:109], 0 op_sel_hi:[1,0]
	v_lshlrev_b32_e32 v84, 16, v46
	v_pk_add_f32 v[44:45], v[44:45], v[110:111]
	v_and_b32_e32 v85, 0xffff0000, v46
	v_lshlrev_b32_e32 v112, 16, v39
	v_and_b32_e32 v113, 0xffff0000, v39
	v_pk_add_f32 v[38:39], v[44:45], v[84:85]
	v_lshlrev_b32_e32 v114, 16, v35
	v_and_b32_e32 v115, 0xffff0000, v35
	v_lshlrev_b32_e32 v34, 16, v50
	v_and_b32_e32 v35, 0xffff0000, v50
	v_pk_add_f32 v[116:117], v[38:39], v[34:35]
	v_lshlrev_b32_e32 v38, 16, v70
	v_and_b32_e32 v39, 0xffff0000, v70
	v_pk_fma_f32 v[44:45], v[32:33], v[116:117], v[84:85] op_sel_hi:[0,1,1] neg_lo:[0,0,1] neg_hi:[0,0,1]
	v_lshlrev_b32_e32 v86, 16, v47
	v_and_b32_e32 v87, 0xffff0000, v47
	v_pk_mul_f32 v[46:47], v[44:45], v[38:39]
	v_pk_add_f32 v[44:45], v[112:113], 0 op_sel_hi:[1,0]
	v_lshlrev_b32_e32 v38, 16, v51
	v_pk_add_f32 v[44:45], v[44:45], v[114:115]
	v_and_b32_e32 v39, 0xffff0000, v51
	v_pk_add_f32 v[44:45], v[44:45], v[86:87]
	v_cvt_pk_bf16_f32 v46, v46, v47
	v_pk_add_f32 v[118:119], v[44:45], v[38:39]
	v_lshlrev_b32_e32 v44, 16, v71
	v_and_b32_e32 v45, 0xffff0000, v71
	v_pk_fma_f32 v[32:33], v[32:33], v[118:119], v[86:87] op_sel_hi:[0,1,1] neg_lo:[0,0,1] neg_hi:[0,0,1]
	v_pk_mul_f32 v[50:51], v[32:33], v[44:45]
	v_mov_b64_e32 v[32:33], s[38:39]
	v_mad_i64_i32 v[44:45], s[6:7], v204, s34, v[32:33]
	v_lshl_add_u64 v[70:71], v[44:45], 0, v[154:155]
	v_min_u32_e32 v44, s2, v95
	v_sub_u32_e64 v45, v78, 2 clamp
	v_sub_u32_e32 v44, v44, v45
	v_cvt_f32_i32_e32 v78, v44
	v_cvt_pk_bf16_f32 v45, v68, v69
	v_cvt_pk_bf16_f32 v44, v106, v107
	v_cvt_pk_bf16_f32 v47, v50, v51
	v_div_scale_f32 v68, s[6:7], v78, v78, 1.0
	v_rcp_f32_e32 v69, v68
	global_store_dwordx4 v[70:71], v[44:47], off offset:2048 sc1
	v_and_b32_e32 v79, 0xffff0000, v28
	v_lshlrev_b32_e32 v70, 16, v29
	v_fma_f32 v44, -v68, v69, 1.0
	v_fmac_f32_e32 v69, v44, v69
	v_div_scale_f32 v44, vcc, 1.0, v78, 1.0
	v_mul_f32_e32 v45, v44, v69
	v_fma_f32 v46, -v68, v45, v44
	v_fmac_f32_e32 v45, v46, v69
	v_fma_f32 v44, -v68, v45, v44
	v_div_fmas_f32 v44, v44, v69, v45
	v_div_fixup_f32 v44, v44, v78, 1.0
	v_lshlrev_b32_e32 v78, 16, v28
	v_pk_add_f32 v[46:47], v[78:79], v[88:89] neg_lo:[0,1] neg_hi:[0,1]
	v_and_b32_e32 v71, 0xffff0000, v29
	v_pk_add_f32 v[46:47], v[104:105], v[46:47]
	v_pk_add_f32 v[28:29], v[70:71], v[102:103] neg_lo:[0,1] neg_hi:[0,1]
	s_waitcnt vmcnt(7)
	v_lshlrev_b32_e32 v50, 16, v98
	v_and_b32_e32 v51, 0xffff0000, v98
	v_pk_fma_f32 v[68:69], v[44:45], v[46:47], v[72:73] op_sel_hi:[0,1,1] neg_lo:[0,0,1] neg_hi:[0,0,1]
	v_pk_add_f32 v[102:103], v[48:49], v[28:29]
	v_pk_mul_f32 v[88:89], v[68:69], v[50:51]
	v_lshlrev_b32_e32 v28, 16, v99
	v_and_b32_e32 v29, 0xffff0000, v99
	v_pk_fma_f32 v[48:49], v[44:45], v[102:103], v[36:37] op_sel_hi:[0,1,1] neg_lo:[0,0,1] neg_hi:[0,0,1]
	v_lshlrev_b32_e32 v68, 16, v30
	v_and_b32_e32 v69, 0xffff0000, v30
	v_pk_mul_f32 v[48:49], v[48:49], v[28:29]
	v_pk_add_f32 v[28:29], v[68:69], v[108:109] neg_lo:[0,1] neg_hi:[0,1]
	s_nop 0
	v_pk_add_f32 v[98:99], v[116:117], v[28:29]
	v_lshlrev_b32_e32 v28, 16, v100
	v_and_b32_e32 v29, 0xffff0000, v100
	v_pk_fma_f32 v[50:51], v[44:45], v[98:99], v[34:35] op_sel_hi:[0,1,1] neg_lo:[0,0,1] neg_hi:[0,0,1]
	v_pk_mul_f32 v[104:105], v[50:51], v[28:29]
	v_lshlrev_b32_e32 v50, 16, v31
	v_and_b32_e32 v51, 0xffff0000, v31
	v_pk_add_f32 v[28:29], v[50:51], v[112:113] neg_lo:[0,1] neg_hi:[0,1]
	s_nop 0
	v_pk_add_f32 v[106:107], v[118:119], v[28:29]
	v_lshlrev_b32_e32 v28, 16, v101
	v_and_b32_e32 v29, 0xffff0000, v101
	v_pk_fma_f32 v[30:31], v[44:45], v[106:107], v[38:39] op_sel_hi:[0,1,1] neg_lo:[0,0,1] neg_hi:[0,0,1]
	v_pk_mul_f32 v[44:45], v[30:31], v[28:29]
	v_or_b32_e32 v28, 1, v204
	v_mad_i64_i32 v[28:29], s[6:7], v28, s34, v[32:33]
	v_lshl_add_u64 v[100:101], v[28:29], 0, v[154:155]
	v_min_u32_e32 v28, s2, v94
	v_sub_u32_e32 v28, v28, v96
	v_add_u32_e32 v28, 2, v28
	v_cvt_f32_i32_e32 v96, v28
	v_cvt_pk_bf16_f32 v29, v48, v49
	v_cvt_pk_bf16_f32 v28, v88, v89
	v_cvt_pk_bf16_f32 v30, v104, v105
	v_div_scale_f32 v48, s[6:7], v96, v96, 1.0
	v_rcp_f32_e32 v49, v48
	v_cvt_pk_bf16_f32 v31, v44, v45
	global_store_dwordx4 v[100:101], v[28:31], off offset:2048 sc1
	s_nop 1
	v_fma_f32 v28, -v48, v49, 1.0
	v_fmac_f32_e32 v49, v28, v49
	v_div_scale_f32 v28, vcc, 1.0, v96, 1.0
	v_mul_f32_e32 v29, v28, v49
	v_fma_f32 v30, -v48, v29, v28
	v_fmac_f32_e32 v29, v30, v49
	v_fma_f32 v28, -v48, v29, v28
	v_div_fmas_f32 v28, v28, v49, v29
	v_lshlrev_b32_e32 v48, 16, v24
	v_and_b32_e32 v49, 0xffff0000, v24
	v_pk_add_f32 v[30:31], v[48:49], v[76:77] neg_lo:[0,1] neg_hi:[0,1]
	v_div_fixup_f32 v28, v28, v96, 1.0
	v_pk_add_f32 v[76:77], v[46:47], v[30:31]
	v_lshlrev_b32_e32 v46, 16, v25
	v_and_b32_e32 v47, 0xffff0000, v25
	v_pk_add_f32 v[24:25], v[46:47], v[80:81] neg_lo:[0,1] neg_hi:[0,1]
	s_waitcnt vmcnt(7)
	v_lshlrev_b32_e32 v30, 16, v64
	v_and_b32_e32 v31, 0xffff0000, v64
	v_pk_fma_f32 v[44:45], v[28:29], v[76:77], v[78:79] op_sel_hi:[0,1,1] neg_lo:[0,0,1] neg_hi:[0,0,1]
	v_pk_add_f32 v[80:81], v[102:103], v[24:25]
	v_pk_mul_f32 v[88:89], v[44:45], v[30:31]
	v_lshlrev_b32_e32 v24, 16, v65
	v_and_b32_e32 v25, 0xffff0000, v65
	v_pk_fma_f32 v[30:31], v[28:29], v[80:81], v[70:71] op_sel_hi:[0,1,1] neg_lo:[0,0,1] neg_hi:[0,0,1]
	v_lshlrev_b32_e32 v44, 16, v26
	v_and_b32_e32 v45, 0xffff0000, v26
	v_pk_mul_f32 v[64:65], v[30:31], v[24:25]
	v_pk_add_f32 v[24:25], v[44:45], v[110:111] neg_lo:[0,1] neg_hi:[0,1]
	s_nop 0
	v_pk_add_f32 v[96:97], v[98:99], v[24:25]
	v_lshlrev_b32_e32 v24, 16, v66
	v_and_b32_e32 v25, 0xffff0000, v66
	v_pk_fma_f32 v[30:31], v[28:29], v[96:97], v[68:69] op_sel_hi:[0,1,1] neg_lo:[0,0,1] neg_hi:[0,0,1]
	v_pk_mul_f32 v[98:99], v[30:31], v[24:25]
	v_lshlrev_b32_e32 v30, 16, v27
	v_and_b32_e32 v31, 0xffff0000, v27
	v_pk_add_f32 v[24:25], v[30:31], v[114:115] neg_lo:[0,1] neg_hi:[0,1]
	s_nop 0
	v_pk_add_f32 v[100:101], v[106:107], v[24:25]
	v_lshlrev_b32_e32 v24, 16, v67
	v_and_b32_e32 v25, 0xffff0000, v67
	v_pk_fma_f32 v[26:27], v[28:29], v[100:101], v[50:51] op_sel_hi:[0,1,1] neg_lo:[0,0,1] neg_hi:[0,0,1]
	v_pk_mul_f32 v[28:29], v[26:27], v[24:25]
	v_or_b32_e32 v24, 2, v204
	v_mad_i64_i32 v[24:25], s[6:7], v24, s34, v[32:33]
	v_lshl_add_u64 v[66:67], v[24:25], 0, v[154:155]
	v_min_u32_e32 v24, s2, v92
	v_sub_u32_e32 v24, v24, v95
	v_add_u32_e32 v24, 2, v24
	v_cvt_f32_i32_e32 v95, v24
	v_cvt_pk_bf16_f32 v25, v64, v65
	v_cvt_pk_bf16_f32 v24, v88, v89
	v_cvt_pk_bf16_f32 v26, v98, v99
	v_div_scale_f32 v64, s[6:7], v95, v95, 1.0
	v_rcp_f32_e32 v65, v64
	v_cvt_pk_bf16_f32 v27, v28, v29
	global_store_dwordx4 v[66:67], v[24:27], off offset:2048 sc1
	v_lshlrev_b32_e32 v28, 16, v16
	v_and_b32_e32 v29, 0xffff0000, v16
	v_fma_f32 v24, -v64, v65, 1.0
	v_fmac_f32_e32 v65, v24, v65
	v_div_scale_f32 v24, vcc, 1.0, v95, 1.0
	v_mul_f32_e32 v25, v24, v65
	v_fma_f32 v26, -v64, v25, v24
	v_fmac_f32_e32 v25, v26, v65
	v_fma_f32 v24, -v64, v25, v24
	v_div_fmas_f32 v24, v24, v65, v25
	v_div_fixup_f32 v64, v24, v95, 1.0
	v_pk_add_f32 v[24:25], v[28:29], v[74:75] neg_lo:[0,1] neg_hi:[0,1]
	s_nop 0
	v_pk_add_f32 v[66:67], v[76:77], v[24:25]
	s_waitcnt vmcnt(7)
	v_lshlrev_b32_e32 v24, 16, v60
	v_and_b32_e32 v25, 0xffff0000, v60
	v_pk_fma_f32 v[26:27], v[64:65], v[66:67], v[48:49] op_sel_hi:[0,1,1] neg_lo:[0,0,1] neg_hi:[0,0,1]
	v_pk_mul_f32 v[74:75], v[26:27], v[24:25]
	v_lshlrev_b32_e32 v26, 16, v17
	v_and_b32_e32 v27, 0xffff0000, v17
	v_pk_add_f32 v[16:17], v[26:27], v[82:83] neg_lo:[0,1] neg_hi:[0,1]
	s_nop 0
	v_pk_add_f32 v[76:77], v[80:81], v[16:17]
	v_lshlrev_b32_e32 v16, 16, v61
	v_and_b32_e32 v17, 0xffff0000, v61
	v_pk_fma_f32 v[24:25], v[64:65], v[76:77], v[46:47] op_sel_hi:[0,1,1] neg_lo:[0,0,1] neg_hi:[0,0,1]
	v_pk_mul_f32 v[80:81], v[24:25], v[16:17]
	v_lshlrev_b32_e32 v24, 16, v18
	v_and_b32_e32 v25, 0xffff0000, v18
	v_pk_add_f32 v[16:17], v[24:25], v[84:85] neg_lo:[0,1] neg_hi:[0,1]
	s_nop 0
	v_pk_add_f32 v[82:83], v[96:97], v[16:17]
	v_lshlrev_b32_e32 v16, 16, v62
	v_and_b32_e32 v17, 0xffff0000, v62
	v_pk_fma_f32 v[60:61], v[64:65], v[82:83], v[44:45] op_sel_hi:[0,1,1] neg_lo:[0,0,1] neg_hi:[0,0,1]
	v_pk_mul_f32 v[84:85], v[60:61], v[16:17]
	v_lshlrev_b32_e32 v16, 16, v19
	v_and_b32_e32 v17, 0xffff0000, v19
	v_pk_add_f32 v[18:19], v[16:17], v[86:87] neg_lo:[0,1] neg_hi:[0,1]
	v_lshlrev_b32_e32 v60, 16, v63
	v_pk_add_f32 v[18:19], v[100:101], v[18:19]
	v_and_b32_e32 v61, 0xffff0000, v63
	v_pk_fma_f32 v[62:63], v[64:65], v[18:19], v[30:31] op_sel_hi:[0,1,1] neg_lo:[0,0,1] neg_hi:[0,0,1]
	v_pk_mul_f32 v[64:65], v[62:63], v[60:61]
	v_or_b32_e32 v60, 3, v204
	v_mad_i64_i32 v[60:61], s[6:7], v60, s34, v[32:33]
	v_lshl_add_u64 v[86:87], v[60:61], 0, v[154:155]
	v_min_u32_e32 v60, s2, v91
	v_sub_u32_e32 v60, v60, v94
	v_add_u32_e32 v60, 2, v60
	v_cvt_f32_i32_e32 v88, v60
	v_cvt_pk_bf16_f32 v60, v74, v75
	v_cvt_pk_bf16_f32 v61, v80, v81
	v_cvt_pk_bf16_f32 v62, v84, v85
	v_div_scale_f32 v74, s[6:7], v88, v88, 1.0
	v_rcp_f32_e32 v75, v74
	v_cvt_pk_bf16_f32 v63, v64, v65
	global_store_dwordx4 v[86:87], v[60:63], off offset:2048 sc1
	v_lshlrev_b32_e32 v80, 16, v15
	v_and_b32_e32 v81, 0xffff0000, v15
	v_fma_f32 v60, -v74, v75, 1.0
	v_fmac_f32_e32 v75, v60, v75
	v_div_scale_f32 v60, vcc, 1.0, v88, 1.0
	v_mul_f32_e32 v61, v60, v75
	v_fma_f32 v62, -v74, v61, v60
	v_fmac_f32_e32 v61, v62, v75
	v_fma_f32 v60, -v74, v61, v60
	v_lshlrev_b32_e32 v62, 16, v12
	v_and_b32_e32 v63, 0xffff0000, v12
	v_div_fmas_f32 v60, v60, v75, v61
	v_pk_add_f32 v[64:65], v[62:63], v[72:73] neg_lo:[0,1] neg_hi:[0,1]
	v_div_fixup_f32 v60, v60, v88, 1.0
	v_pk_add_f32 v[64:65], v[66:67], v[64:65]
	s_waitcnt vmcnt(7)
	v_lshlrev_b32_e32 v66, 16, v56
	v_and_b32_e32 v67, 0xffff0000, v56
	v_pk_fma_f32 v[72:73], v[60:61], v[64:65], v[28:29] op_sel_hi:[0,1,1] neg_lo:[0,0,1] neg_hi:[0,0,1]
	v_pk_mul_f32 v[66:67], v[72:73], v[66:67]
	v_lshlrev_b32_e32 v72, 16, v13
	v_and_b32_e32 v73, 0xffff0000, v13
	v_pk_add_f32 v[12:13], v[72:73], v[36:37] neg_lo:[0,1] neg_hi:[0,1]
	v_lshlrev_b32_e32 v74, 16, v14
	v_pk_add_f32 v[36:37], v[76:77], v[12:13]
	v_lshlrev_b32_e32 v12, 16, v57
	v_and_b32_e32 v13, 0xffff0000, v57
	v_pk_fma_f32 v[56:57], v[60:61], v[36:37], v[26:27] op_sel_hi:[0,1,1] neg_lo:[0,0,1] neg_hi:[0,0,1]
	v_and_b32_e32 v75, 0xffff0000, v14
	v_pk_mul_f32 v[56:57], v[56:57], v[12:13]
	v_pk_add_f32 v[12:13], v[74:75], v[34:35] neg_lo:[0,1] neg_hi:[0,1]
	s_nop 0
	v_pk_add_f32 v[34:35], v[82:83], v[12:13]
	v_lshlrev_b32_e32 v12, 16, v58
	v_and_b32_e32 v13, 0xffff0000, v58
	v_pk_fma_f32 v[76:77], v[60:61], v[34:35], v[24:25] op_sel_hi:[0,1,1] neg_lo:[0,0,1] neg_hi:[0,0,1]
	v_pk_mul_f32 v[76:77], v[76:77], v[12:13]
	v_pk_add_f32 v[12:13], v[80:81], v[38:39] neg_lo:[0,1] neg_hi:[0,1]
	s_nop 0
	v_pk_add_f32 v[18:19], v[18:19], v[12:13]
	v_lshlrev_b32_e32 v12, 16, v59
	v_and_b32_e32 v13, 0xffff0000, v59
	v_pk_fma_f32 v[14:15], v[60:61], v[18:19], v[16:17] op_sel_hi:[0,1,1] neg_lo:[0,0,1] neg_hi:[0,0,1]
	v_pk_mul_f32 v[38:39], v[14:15], v[12:13]
	v_or_b32_e32 v12, 4, v204
	v_mad_i64_i32 v[12:13], s[6:7], v12, s34, v[32:33]
	v_lshl_add_u64 v[58:59], v[12:13], 0, v[154:155]
	v_min_u32_e32 v12, s2, v90
	v_sub_u32_e32 v12, v12, v92
	v_add_u32_e32 v12, 2, v12
	v_cvt_f32_i32_e32 v60, v12
	v_cvt_pk_bf16_f32 v13, v56, v57
	v_cvt_pk_bf16_f32 v12, v66, v67
	v_cvt_pk_bf16_f32 v14, v76, v77
	v_div_scale_f32 v56, s[6:7], v60, v60, 1.0
	v_rcp_f32_e32 v57, v56
	v_cvt_pk_bf16_f32 v15, v38, v39
	global_store_dwordx4 v[58:59], v[12:15], off offset:2048 sc1
	v_and_b32_e32 v61, 0xffff0000, v10
	s_nop 0
	v_fma_f32 v12, -v56, v57, 1.0
	v_fmac_f32_e32 v57, v12, v57
	v_div_scale_f32 v12, vcc, 1.0, v60, 1.0
	v_mul_f32_e32 v13, v12, v57
	v_fma_f32 v14, -v56, v13, v12
	v_fmac_f32_e32 v13, v14, v57
	v_fma_f32 v12, -v56, v13, v12
	v_lshlrev_b32_e32 v14, 16, v8
	v_and_b32_e32 v15, 0xffff0000, v8
	v_div_fmas_f32 v12, v12, v57, v13
	v_pk_add_f32 v[38:39], v[14:15], v[78:79] neg_lo:[0,1] neg_hi:[0,1]
	v_div_fixup_f32 v12, v12, v60, 1.0
	v_pk_add_f32 v[38:39], v[64:65], v[38:39]
	s_waitcnt vmcnt(7)
	v_lshlrev_b32_e32 v56, 16, v52
	v_and_b32_e32 v57, 0xffff0000, v52
	v_pk_fma_f32 v[58:59], v[12:13], v[38:39], v[62:63] op_sel_hi:[0,1,1] neg_lo:[0,0,1] neg_hi:[0,0,1]
	v_pk_mul_f32 v[56:57], v[58:59], v[56:57]
	v_lshlrev_b32_e32 v58, 16, v9
	v_and_b32_e32 v59, 0xffff0000, v9
	v_pk_add_f32 v[8:9], v[58:59], v[70:71] neg_lo:[0,1] neg_hi:[0,1]
	v_lshlrev_b32_e32 v60, 16, v10
	v_pk_add_f32 v[36:37], v[36:37], v[8:9]
	v_lshlrev_b32_e32 v8, 16, v53
	v_and_b32_e32 v9, 0xffff0000, v53
	v_pk_fma_f32 v[52:53], v[12:13], v[36:37], v[72:73] op_sel_hi:[0,1,1] neg_lo:[0,0,1] neg_hi:[0,0,1]
	v_pk_mul_f32 v[52:53], v[52:53], v[8:9]
	v_pk_add_f32 v[8:9], v[60:61], v[68:69] neg_lo:[0,1] neg_hi:[0,1]
	v_lshlrev_b32_e32 v64, 16, v11
	v_pk_add_f32 v[34:35], v[34:35], v[8:9]
	v_lshlrev_b32_e32 v8, 16, v54
	v_and_b32_e32 v9, 0xffff0000, v54
	v_pk_fma_f32 v[62:63], v[12:13], v[34:35], v[74:75] op_sel_hi:[0,1,1] neg_lo:[0,0,1] neg_hi:[0,0,1]
	v_and_b32_e32 v65, 0xffff0000, v11
	v_pk_mul_f32 v[62:63], v[62:63], v[8:9]
	v_pk_add_f32 v[8:9], v[64:65], v[50:51] neg_lo:[0,1] neg_hi:[0,1]
	s_nop 0
	v_pk_add_f32 v[18:19], v[18:19], v[8:9]
	v_lshlrev_b32_e32 v8, 16, v55
	v_and_b32_e32 v9, 0xffff0000, v55
	v_pk_fma_f32 v[10:11], v[12:13], v[18:19], v[80:81] op_sel_hi:[0,1,1] neg_lo:[0,0,1] neg_hi:[0,0,1]
	v_pk_mul_f32 v[12:13], v[10:11], v[8:9]
	v_or_b32_e32 v8, 5, v204
	v_mad_i64_i32 v[8:9], s[6:7], v8, s34, v[32:33]
	v_lshl_add_u64 v[50:51], v[8:9], 0, v[154:155]
	v_min_u32_e32 v8, s2, v93
	v_sub_u32_e32 v8, v8, v91
	v_add_u32_e32 v8, 2, v8
	v_cvt_f32_i32_e32 v54, v8
	v_cvt_pk_bf16_f32 v9, v52, v53
	v_cvt_pk_bf16_f32 v8, v56, v57
	v_cvt_pk_bf16_f32 v10, v62, v63
	v_div_scale_f32 v52, s[6:7], v54, v54, 1.0
	v_rcp_f32_e32 v53, v52
	v_cvt_pk_bf16_f32 v11, v12, v13
	global_store_dwordx4 v[50:51], v[8:11], off offset:2048 sc1
	s_nop 1
	v_fma_f32 v8, -v52, v53, 1.0
	v_fmac_f32_e32 v53, v8, v53
	v_div_scale_f32 v8, vcc, 1.0, v54, 1.0
	v_mul_f32_e32 v9, v8, v53
	v_fma_f32 v10, -v52, v9, v8
	v_fmac_f32_e32 v9, v10, v53
	v_fma_f32 v8, -v52, v9, v8
	v_lshlrev_b32_e32 v10, 16, v4
	v_and_b32_e32 v11, 0xffff0000, v4
	v_div_fmas_f32 v8, v8, v53, v9
	v_pk_add_f32 v[12:13], v[10:11], v[48:49] neg_lo:[0,1] neg_hi:[0,1]
	v_div_fixup_f32 v8, v8, v54, 1.0
	v_pk_add_f32 v[12:13], v[38:39], v[12:13]
	s_waitcnt vmcnt(7)
	v_lshlrev_b32_e32 v38, 16, v40
	v_and_b32_e32 v39, 0xffff0000, v40
	v_pk_fma_f32 v[14:15], v[8:9], v[12:13], v[14:15] op_sel_hi:[0,1,1] neg_lo:[0,0,1] neg_hi:[0,0,1]
	v_pk_mul_f32 v[14:15], v[14:15], v[38:39]
	v_lshlrev_b32_e32 v38, 16, v5
	v_and_b32_e32 v39, 0xffff0000, v5
	v_pk_add_f32 v[4:5], v[38:39], v[46:47] neg_lo:[0,1] neg_hi:[0,1]
	v_lshlrev_b32_e32 v46, 16, v6
	v_pk_add_f32 v[36:37], v[36:37], v[4:5]
	v_lshlrev_b32_e32 v4, 16, v41
	v_and_b32_e32 v5, 0xffff0000, v41
	v_pk_fma_f32 v[40:41], v[8:9], v[36:37], v[58:59] op_sel_hi:[0,1,1] neg_lo:[0,0,1] neg_hi:[0,0,1]
	v_and_b32_e32 v47, 0xffff0000, v6
	v_pk_mul_f32 v[40:41], v[40:41], v[4:5]
	v_pk_add_f32 v[4:5], v[46:47], v[44:45] neg_lo:[0,1] neg_hi:[0,1]
	v_lshlrev_b32_e32 v48, 16, v7
	v_pk_add_f32 v[34:35], v[34:35], v[4:5]
	v_lshlrev_b32_e32 v4, 16, v42
	v_and_b32_e32 v5, 0xffff0000, v42
	v_pk_fma_f32 v[44:45], v[8:9], v[34:35], v[60:61] op_sel_hi:[0,1,1] neg_lo:[0,0,1] neg_hi:[0,0,1]
	v_and_b32_e32 v49, 0xffff0000, v7
	v_pk_mul_f32 v[44:45], v[44:45], v[4:5]
	v_pk_add_f32 v[4:5], v[48:49], v[30:31] neg_lo:[0,1] neg_hi:[0,1]
	s_nop 0
	v_pk_add_f32 v[18:19], v[18:19], v[4:5]
	v_lshlrev_b32_e32 v4, 16, v43
	v_and_b32_e32 v5, 0xffff0000, v43
	v_pk_fma_f32 v[6:7], v[8:9], v[18:19], v[64:65] op_sel_hi:[0,1,1] neg_lo:[0,0,1] neg_hi:[0,0,1]
	v_pk_mul_f32 v[8:9], v[6:7], v[4:5]
	v_or_b32_e32 v4, 6, v204
	v_mad_i64_i32 v[4:5], s[6:7], v4, s34, v[32:33]
	v_lshl_add_u64 v[30:31], v[4:5], 0, v[154:155]
	v_add_u32_e32 v4, 9, v206
	v_min_u32_e32 v4, s2, v4
	v_sub_u32_e32 v4, v4, v90
	v_add_u32_e32 v4, 2, v4
	v_cvt_f32_i32_e32 v42, v4
	v_cvt_pk_bf16_f32 v4, v14, v15
	v_cvt_pk_bf16_f32 v5, v40, v41
	v_cvt_pk_bf16_f32 v6, v44, v45
	v_div_scale_f32 v14, s[6:7], v42, v42, 1.0
	v_rcp_f32_e32 v15, v14
	v_cvt_pk_bf16_f32 v7, v8, v9
	global_store_dwordx4 v[30:31], v[4:7], off offset:2048 sc1
	s_waitcnt vmcnt(7)
	v_lshlrev_b32_e32 v8, 16, v20
	v_and_b32_e32 v9, 0xffff0000, v20
	v_fma_f32 v4, -v14, v15, 1.0
	v_fmac_f32_e32 v15, v4, v15
	v_div_scale_f32 v4, vcc, 1.0, v42, 1.0
	v_mul_f32_e32 v5, v4, v15
	v_fma_f32 v6, -v14, v5, v4
	v_fmac_f32_e32 v5, v6, v15
	v_fma_f32 v4, -v14, v5, v4
	v_lshlrev_b32_e32 v6, 16, v0
	v_and_b32_e32 v7, 0xffff0000, v0
	v_div_fmas_f32 v4, v4, v15, v5
	v_pk_add_f32 v[6:7], v[6:7], v[28:29] neg_lo:[0,1] neg_hi:[0,1]
	v_lshlrev_b32_e32 v0, 16, v1
	v_and_b32_e32 v1, 0xffff0000, v1
	v_div_fixup_f32 v4, v4, v42, 1.0
	v_pk_add_f32 v[6:7], v[12:13], v[6:7]
	v_pk_add_f32 v[0:1], v[0:1], v[26:27] neg_lo:[0,1] neg_hi:[0,1]
	v_pk_fma_f32 v[6:7], v[4:5], v[6:7], v[10:11] op_sel_hi:[0,1,1] neg_lo:[0,0,1] neg_hi:[0,0,1]
	v_pk_add_f32 v[0:1], v[36:37], v[0:1]
	v_pk_mul_f32 v[6:7], v[6:7], v[8:9]
	v_lshlrev_b32_e32 v8, 16, v21
	v_and_b32_e32 v9, 0xffff0000, v21
	v_pk_fma_f32 v[0:1], v[4:5], v[0:1], v[38:39] op_sel_hi:[0,1,1] neg_lo:[0,0,1] neg_hi:[0,0,1]
	v_pk_mul_f32 v[8:9], v[0:1], v[8:9]
	v_lshlrev_b32_e32 v0, 16, v2
	v_and_b32_e32 v1, 0xffff0000, v2
	v_pk_add_f32 v[0:1], v[0:1], v[24:25] neg_lo:[0,1] neg_hi:[0,1]
	v_lshlrev_b32_e32 v10, 16, v22
	v_pk_add_f32 v[0:1], v[34:35], v[0:1]
	v_and_b32_e32 v11, 0xffff0000, v22
	v_pk_fma_f32 v[0:1], v[4:5], v[0:1], v[46:47] op_sel_hi:[0,1,1] neg_lo:[0,0,1] neg_hi:[0,0,1]
	v_pk_mul_f32 v[10:11], v[0:1], v[10:11]
	v_lshlrev_b32_e32 v0, 16, v3
	v_and_b32_e32 v1, 0xffff0000, v3
	v_pk_add_f32 v[0:1], v[0:1], v[16:17] neg_lo:[0,1] neg_hi:[0,1]
	v_lshlrev_b32_e32 v2, 16, v23
	v_pk_add_f32 v[0:1], v[18:19], v[0:1]
	v_and_b32_e32 v3, 0xffff0000, v23
	v_pk_fma_f32 v[0:1], v[4:5], v[0:1], v[48:49] op_sel_hi:[0,1,1] neg_lo:[0,0,1] neg_hi:[0,0,1]
	v_pk_mul_f32 v[4:5], v[0:1], v[2:3]
	v_or_b32_e32 v0, 7, v204
	v_mad_i64_i32 v[0:1], s[6:7], v0, s34, v[32:33]
	v_lshl_add_u64 v[12:13], v[0:1], 0, v[154:155]
	v_cvt_pk_bf16_f32 v0, v6, v7
	v_cvt_pk_bf16_f32 v1, v8, v9
	v_cvt_pk_bf16_f32 v2, v10, v11
	v_cvt_pk_bf16_f32 v3, v4, v5
	global_store_dwordx4 v[12:13], v[0:3], off offset:2048 sc1

.LBB0_251:
	s_or_b64 exec, exec, s[0:1]
	v_add_co_u32_e32 v8, vcc, 0x2000, v126
	s_waitcnt vmcnt(1)
	v_lshlrev_b32_e32 v158, 16, v56
	v_addc_co_u32_e32 v9, vcc, 0, v127, vcc
	global_load_dwordx4 v[120:123], v[126:127], off offset:2048
	global_load_dwordx4 v[100:103], v[8:9], off offset:2176
	v_and_b32_e32 v159, 0xffff0000, v56
	v_pk_add_f32 v[128:129], v[158:159], 0 op_sel_hi:[1,0]
	v_lshlrev_b32_e32 v146, 16, v52
	v_and_b32_e32 v147, 0xffff0000, v52
	v_pk_add_f32 v[128:129], v[128:129], v[146:147]
	v_lshlrev_b32_e32 v138, 16, v76
	v_and_b32_e32 v139, 0xffff0000, v76
	v_pk_add_f32 v[128:129], v[128:129], v[138:139]
	v_lshlrev_b32_e32 v134, 16, v72
	v_and_b32_e32 v135, 0xffff0000, v72
	v_pk_add_f32 v[128:129], v[128:129], v[134:135]
	v_lshlrev_b32_e32 v132, 16, v92
	v_and_b32_e32 v133, 0xffff0000, v92
	v_pk_add_f32 v[128:129], v[128:129], v[132:133]
	v_lshlrev_b32_e32 v130, 16, v88
	v_and_b32_e32 v131, 0xffff0000, v88
	v_pk_add_f32 v[136:137], v[128:129], v[130:131]
	v_lshlrev_b32_e32 v128, 16, v108
	v_and_b32_e32 v129, 0xffff0000, v108
	v_lshlrev_b32_e32 v164, 16, v57
	v_and_b32_e32 v165, 0xffff0000, v57
	v_pk_add_f32 v[136:137], v[136:137], v[128:129]
	v_lshlrev_b32_e32 v140, 16, v104
	v_and_b32_e32 v141, 0xffff0000, v104
	v_pk_add_f32 v[56:57], v[164:165], 0 op_sel_hi:[1,0]
	v_lshlrev_b32_e32 v148, 16, v53
	v_and_b32_e32 v149, 0xffff0000, v53
	v_pk_add_f32 v[184:185], v[136:137], v[140:141]
	v_pk_add_f32 v[52:53], v[56:57], v[148:149]
	v_lshlrev_b32_e32 v140, 16, v77
	v_and_b32_e32 v141, 0xffff0000, v77
	v_pk_add_f32 v[52:53], v[52:53], v[140:141]
	v_lshlrev_b32_e32 v136, 16, v73
	v_and_b32_e32 v137, 0xffff0000, v73
	v_pk_add_f32 v[52:53], v[52:53], v[136:137]
	v_lshlrev_b32_e32 v92, 16, v93
	v_and_b32_e32 v93, 0xffff0000, v93
	v_pk_add_f32 v[52:53], v[52:53], v[92:93]
	v_lshlrev_b32_e32 v72, 16, v89
	v_and_b32_e32 v73, 0xffff0000, v89
	v_pk_add_f32 v[56:57], v[52:53], v[72:73]
	v_lshlrev_b32_e32 v52, 16, v109
	v_and_b32_e32 v53, 0xffff0000, v109
	v_pk_add_f32 v[56:57], v[56:57], v[52:53]
	v_lshlrev_b32_e32 v76, 16, v105
	v_and_b32_e32 v77, 0xffff0000, v105
	v_lshlrev_b32_e32 v170, 16, v58
	v_and_b32_e32 v171, 0xffff0000, v58
	v_pk_add_f32 v[190:191], v[56:57], v[76:77]
	v_pk_add_f32 v[56:57], v[170:171], 0 op_sel_hi:[1,0]
	v_lshlrev_b32_e32 v150, 16, v54
	v_and_b32_e32 v151, 0xffff0000, v54
	v_pk_add_f32 v[56:57], v[56:57], v[150:151]
	v_lshlrev_b32_e32 v142, 16, v78
	v_and_b32_e32 v143, 0xffff0000, v78
	v_pk_add_f32 v[56:57], v[56:57], v[142:143]
	v_lshlrev_b32_e32 v104, 16, v74
	v_and_b32_e32 v105, 0xffff0000, v74
	v_pk_add_f32 v[56:57], v[56:57], v[104:105]
	v_lshlrev_b32_e32 v88, 16, v94
	v_and_b32_e32 v89, 0xffff0000, v94
	v_pk_add_f32 v[56:57], v[56:57], v[88:89]
	v_lshlrev_b32_e32 v76, 16, v90
	v_and_b32_e32 v77, 0xffff0000, v90
	v_pk_add_f32 v[108:109], v[56:57], v[76:77]
	v_lshlrev_b32_e32 v56, 16, v110
	v_and_b32_e32 v57, 0xffff0000, v110
	v_lshlrev_b32_e32 v172, 16, v59
	v_and_b32_e32 v173, 0xffff0000, v59
	v_pk_add_f32 v[108:109], v[108:109], v[56:57]
	v_lshlrev_b32_e32 v144, 16, v106
	v_and_b32_e32 v145, 0xffff0000, v106
	v_pk_add_f32 v[58:59], v[172:173], 0 op_sel_hi:[1,0]
	v_lshlrev_b32_e32 v156, 16, v55
	v_and_b32_e32 v157, 0xffff0000, v55
	v_pk_add_f32 v[168:169], v[108:109], v[144:145]
	v_pk_add_f32 v[54:55], v[58:59], v[156:157]
	v_lshlrev_b32_e32 v144, 16, v79
	v_and_b32_e32 v145, 0xffff0000, v79
	v_pk_add_f32 v[54:55], v[54:55], v[144:145]
	v_lshlrev_b32_e32 v108, 16, v75
	v_and_b32_e32 v109, 0xffff0000, v75
	v_pk_add_f32 v[54:55], v[54:55], v[108:109]
	v_lshlrev_b32_e32 v78, 16, v95
	v_and_b32_e32 v79, 0xffff0000, v95
	v_pk_add_f32 v[54:55], v[54:55], v[78:79]
	v_lshlrev_b32_e32 v58, 16, v91
	v_and_b32_e32 v59, 0xffff0000, v91
	v_pk_add_f32 v[74:75], v[54:55], v[58:59]
	v_lshlrev_b32_e32 v54, 16, v111
	v_and_b32_e32 v55, 0xffff0000, v111
	v_pk_add_f32 v[74:75], v[74:75], v[54:55]
	v_lshlrev_b32_e32 v90, 16, v107
	v_and_b32_e32 v91, 0xffff0000, v107
	v_add_co_u32_e32 v8, vcc, 0x4000, v126
	v_pk_add_f32 v[176:177], v[74:75], v[90:91]
	v_min_u32_e32 v74, s2, v160
	v_sub_u32_e64 v75, v206, 8 clamp
	v_addc_co_u32_e32 v9, vcc, 0, v127, vcc
	v_sub_u32_e32 v74, v74, v75
	v_add_co_u32_e32 v10, vcc, 0x6000, v126
	v_cvt_f32_i32_e32 v74, v74
	s_nop 0
	v_addc_co_u32_e32 v11, vcc, 0, v127, vcc
	global_load_dwordx4 v[60:63], v[8:9], off offset:2304
	global_load_dwordx4 v[40:43], v[10:11], off offset:2432
	v_add_co_u32_e32 v8, vcc, 0x8000, v126
	v_div_scale_f32 v75, s[0:1], v74, v74, 1.0
	s_nop 0
	v_addc_co_u32_e32 v9, vcc, 0, v127, vcc
	v_add_co_u32_e32 v10, vcc, s11, v126
	v_rcp_f32_e32 v90, v75
	s_nop 0
	v_addc_co_u32_e32 v11, vcc, 0, v127, vcc
	global_load_dwordx4 v[36:39], v[8:9], off offset:2560
	global_load_dwordx4 v[28:31], v[10:11], off offset:2688
	v_add_co_u32_e32 v8, vcc, s12, v126
	v_fma_f32 v91, -v75, v90, 1.0
	s_nop 0
	v_addc_co_u32_e32 v9, vcc, 0, v127, vcc
	v_add_co_u32_e32 v10, vcc, s13, v126
	v_fmac_f32_e32 v90, v91, v90
	s_nop 0
	v_addc_co_u32_e32 v11, vcc, 0, v127, vcc
	v_div_scale_f32 v91, vcc, 1.0, v74, 1.0
	v_mul_f32_e32 v94, v91, v90
	v_fma_f32 v95, -v75, v94, v91
	v_fmac_f32_e32 v94, v95, v90
	v_fma_f32 v75, -v75, v94, v91
	v_div_fmas_f32 v75, v75, v90, v94
	s_waitcnt vmcnt(6)
	v_lshlrev_b32_e32 v110, 16, v48
	v_and_b32_e32 v111, 0xffff0000, v48
	v_lshlrev_b32_e32 v182, 16, v116
	v_and_b32_e32 v183, 0xffff0000, v116
	v_div_fixup_f32 v186, v75, v74, 1.0
	v_pk_add_f32 v[74:75], v[184:185], v[110:111]
	v_lshlrev_b32_e32 v166, 16, v112
	v_and_b32_e32 v167, 0xffff0000, v112
	v_pk_add_f32 v[74:75], v[74:75], v[182:183]
	v_lshlrev_b32_e32 v162, 16, v113
	v_and_b32_e32 v163, 0xffff0000, v113
	v_pk_add_f32 v[74:75], v[74:75], v[166:167]
	v_lshlrev_b32_e32 v112, 16, v68
	v_and_b32_e32 v113, 0xffff0000, v68
	v_pk_add_f32 v[74:75], v[74:75], v[112:113]
	v_lshlrev_b32_e32 v106, 16, v64
	v_and_b32_e32 v107, 0xffff0000, v64
	v_pk_add_f32 v[74:75], v[74:75], v[106:107]
	v_lshlrev_b32_e32 v94, 16, v84
	v_and_b32_e32 v95, 0xffff0000, v84
	v_pk_add_f32 v[74:75], v[74:75], v[94:95]
	v_lshlrev_b32_e32 v90, 16, v80
	v_and_b32_e32 v91, 0xffff0000, v80
	v_lshlrev_b32_e32 v180, 16, v117
	v_and_b32_e32 v181, 0xffff0000, v117
	v_pk_add_f32 v[116:117], v[74:75], v[90:91]
	v_lshlrev_b32_e32 v74, 16, v96
	v_and_b32_e32 v75, 0xffff0000, v96
	v_pk_add_f32 v[184:185], v[116:117], v[74:75]
	s_waitcnt vmcnt(5)
	v_lshlrev_b32_e32 v116, 16, v120
	v_and_b32_e32 v117, 0xffff0000, v120
	v_pk_fma_f32 v[110:111], v[186:187], v[184:185], v[110:111] op_sel_hi:[0,1,1] neg_lo:[0,0,1] neg_hi:[0,0,1]
	v_pk_mul_f32 v[188:189], v[110:111], v[116:117]
	v_lshlrev_b32_e32 v116, 16, v49
	v_and_b32_e32 v117, 0xffff0000, v49
	v_pk_add_f32 v[48:49], v[190:191], v[116:117]
	v_lshlrev_b32_e32 v178, 16, v118
	v_pk_add_f32 v[48:49], v[48:49], v[180:181]
	v_and_b32_e32 v179, 0xffff0000, v118
	v_lshlrev_b32_e32 v174, 16, v119
	v_and_b32_e32 v175, 0xffff0000, v119
	v_pk_add_f32 v[48:49], v[48:49], v[162:163]
	v_lshlrev_b32_e32 v118, 16, v69
	v_and_b32_e32 v119, 0xffff0000, v69
	v_pk_add_f32 v[48:49], v[48:49], v[118:119]
	v_lshlrev_b32_e32 v110, 16, v65
	v_and_b32_e32 v111, 0xffff0000, v65
	v_pk_add_f32 v[48:49], v[48:49], v[110:111]
	v_lshlrev_b32_e32 v84, 16, v85
	v_and_b32_e32 v85, 0xffff0000, v85
	v_pk_add_f32 v[48:49], v[48:49], v[84:85]
	v_lshlrev_b32_e32 v68, 16, v81
	v_and_b32_e32 v69, 0xffff0000, v81
	v_pk_add_f32 v[64:65], v[48:49], v[68:69]
	v_lshlrev_b32_e32 v48, 16, v97
	v_and_b32_e32 v49, 0xffff0000, v97
	v_pk_add_f32 v[190:191], v[64:65], v[48:49]
	v_lshlrev_b32_e32 v64, 16, v121
	v_and_b32_e32 v65, 0xffff0000, v121
	v_pk_fma_f32 v[80:81], v[186:187], v[190:191], v[116:117] op_sel_hi:[0,1,1] neg_lo:[0,0,1] neg_hi:[0,0,1]
	v_lshlrev_b32_e32 v120, 16, v50
	v_and_b32_e32 v121, 0xffff0000, v50
	v_pk_mul_f32 v[194:195], v[80:81], v[64:65]
	v_pk_add_f32 v[64:65], v[168:169], v[120:121]
	v_lshlrev_b32_e32 v160, 16, v114
	v_and_b32_e32 v161, 0xffff0000, v114
	v_pk_add_f32 v[64:65], v[64:65], v[178:179]
	v_lshlrev_b32_e32 v168, 16, v70
	v_pk_add_f32 v[64:65], v[64:65], v[160:161]
	v_and_b32_e32 v169, 0xffff0000, v70
	v_pk_add_f32 v[64:65], v[64:65], v[168:169]
	v_lshlrev_b32_e32 v116, 16, v66
	v_and_b32_e32 v117, 0xffff0000, v66
	v_pk_add_f32 v[64:65], v[64:65], v[116:117]
	v_lshlrev_b32_e32 v96, 16, v86
	v_and_b32_e32 v97, 0xffff0000, v86
	v_pk_add_f32 v[64:65], v[64:65], v[96:97]
	v_lshlrev_b32_e32 v80, 16, v82
	v_and_b32_e32 v81, 0xffff0000, v82
	v_lshlrev_b32_e32 v220, 16, v51
	v_and_b32_e32 v221, 0xffff0000, v51
	v_pk_add_f32 v[192:193], v[64:65], v[80:81]
	v_lshlrev_b32_e32 v64, 16, v98
	v_and_b32_e32 v65, 0xffff0000, v98
	v_pk_add_f32 v[50:51], v[176:177], v[220:221]
	v_lshlrev_b32_e32 v114, 16, v115
	v_and_b32_e32 v115, 0xffff0000, v115
	v_pk_add_f32 v[192:193], v[192:193], v[64:65]
	v_pk_add_f32 v[50:51], v[50:51], v[174:175]
	v_lshlrev_b32_e32 v196, 16, v122
	v_and_b32_e32 v197, 0xffff0000, v122
	v_pk_fma_f32 v[120:121], v[186:187], v[192:193], v[120:121] op_sel_hi:[0,1,1] neg_lo:[0,0,1] neg_hi:[0,0,1]
	v_pk_add_f32 v[50:51], v[50:51], v[114:115]
	v_lshlrev_b32_e32 v176, 16, v71
	v_and_b32_e32 v177, 0xffff0000, v71
	v_pk_mul_f32 v[196:197], v[120:121], v[196:197]
	v_pk_add_f32 v[50:51], v[50:51], v[176:177]
	v_lshlrev_b32_e32 v120, 16, v67
	v_and_b32_e32 v121, 0xffff0000, v67
	v_pk_add_f32 v[50:51], v[50:51], v[120:121]
	v_lshlrev_b32_e32 v86, 16, v87
	v_and_b32_e32 v87, 0xffff0000, v87
	v_pk_add_f32 v[50:51], v[50:51], v[86:87]
	v_lshlrev_b32_e32 v66, 16, v83
	v_and_b32_e32 v67, 0xffff0000, v83
	v_pk_add_f32 v[70:71], v[50:51], v[66:67]
	v_lshlrev_b32_e32 v50, 16, v99
	v_and_b32_e32 v51, 0xffff0000, v99
	v_pk_add_f32 v[82:83], v[70:71], v[50:51]
	v_sub_u32_e64 v216, v216, 8 clamp
	v_pk_fma_f32 v[98:99], v[186:187], v[82:83], v[220:221] op_sel_hi:[0,1,1] neg_lo:[0,0,1] neg_hi:[0,0,1]
	v_min_u32_e32 v186, s2, v219
	v_sub_u32_e32 v186, v186, v216
	v_cvt_f32_i32_e32 v186, v186
	v_cvt_pk_bf16_f32 v220, v188, v189
	v_lshlrev_b32_e32 v70, 16, v123
	v_and_b32_e32 v71, 0xffff0000, v123
	v_div_scale_f32 v188, s[0:1], v186, v186, 1.0
	v_rcp_f32_e32 v189, v188
	v_pk_mul_f32 v[98:99], v[98:99], v[70:71]
	v_mov_b64_e32 v[70:71], s[38:39]
	v_cvt_pk_bf16_f32 v223, v98, v99
	v_fma_f32 v98, -v188, v189, 1.0
	v_mad_i64_i32 v[122:123], s[0:1], v204, s34, v[70:71]
	v_fmac_f32_e32 v189, v98, v189
	v_div_scale_f32 v98, vcc, 1.0, v186, 1.0
	v_lshl_add_u64 v[122:123], v[122:123], 0, v[154:155]
	v_cvt_pk_bf16_f32 v221, v194, v195
	v_cvt_pk_bf16_f32 v222, v196, v197
	v_mul_f32_e32 v99, v98, v189
	global_load_dwordx4 v[16:19], v[8:9], off offset:2816
	s_nop 0
	global_load_dwordx4 v[8:11], v[10:11], off offset:2944
	s_nop 0
	global_store_dwordx4 v[122:123], v[220:223], off offset:2048 sc1
	v_fma_f32 v122, -v188, v99, v98
	v_fmac_f32_e32 v99, v122, v189
	v_fma_f32 v98, -v188, v99, v98
	v_lshlrev_b32_e32 v122, 16, v44
	v_and_b32_e32 v123, 0xffff0000, v44
	v_lshlrev_b32_e32 v44, 16, v45
	v_and_b32_e32 v45, 0xffff0000, v45
	v_div_fmas_f32 v98, v98, v189, v99
	v_pk_add_f32 v[44:45], v[44:45], v[164:165] neg_lo:[0,1] neg_hi:[0,1]
	v_div_fixup_f32 v98, v98, v186, 1.0
	v_pk_add_f32 v[164:165], v[190:191], v[44:45]
	v_pk_add_f32 v[122:123], v[122:123], v[158:159] neg_lo:[0,1] neg_hi:[0,1]
	s_waitcnt vmcnt(7)
	v_lshlrev_b32_e32 v158, 16, v100
	v_and_b32_e32 v159, 0xffff0000, v100
	v_lshlrev_b32_e32 v44, 16, v101
	v_and_b32_e32 v45, 0xffff0000, v101
	v_pk_fma_f32 v[100:101], v[98:99], v[164:165], v[180:181] op_sel_hi:[0,1,1] neg_lo:[0,0,1] neg_hi:[0,0,1]
	v_pk_mul_f32 v[100:101], v[100:101], v[44:45]
	v_lshlrev_b32_e32 v44, 16, v46
	v_and_b32_e32 v45, 0xffff0000, v46
	v_pk_add_f32 v[44:45], v[44:45], v[170:171] neg_lo:[0,1] neg_hi:[0,1]
	v_pk_add_f32 v[122:123], v[184:185], v[122:123]
	v_pk_add_f32 v[170:171], v[192:193], v[44:45]
	v_lshlrev_b32_e32 v44, 16, v102
	v_and_b32_e32 v45, 0xffff0000, v102
	v_pk_fma_f32 v[178:179], v[98:99], v[170:171], v[178:179] op_sel_hi:[0,1,1] neg_lo:[0,0,1] neg_hi:[0,0,1]
	v_pk_mul_f32 v[178:179], v[178:179], v[44:45]
	v_lshlrev_b32_e32 v44, 16, v47
	v_and_b32_e32 v45, 0xffff0000, v47
	v_pk_add_f32 v[44:45], v[44:45], v[172:173] neg_lo:[0,1] neg_hi:[0,1]
	v_pk_fma_f32 v[182:183], v[98:99], v[122:123], v[182:183] op_sel_hi:[0,1,1] neg_lo:[0,0,1] neg_hi:[0,0,1]
	v_pk_add_f32 v[82:83], v[82:83], v[44:45]
	v_lshlrev_b32_e32 v44, 16, v103
	v_and_b32_e32 v45, 0xffff0000, v103
	v_pk_fma_f32 v[46:47], v[98:99], v[82:83], v[174:175] op_sel_hi:[0,1,1] neg_lo:[0,0,1] neg_hi:[0,0,1]
	v_pk_mul_f32 v[98:99], v[46:47], v[44:45]
	v_or_b32_e32 v44, 1, v204
	v_mad_i64_i32 v[44:45], s[0:1], v44, s34, v[70:71]
	v_lshl_add_u64 v[102:103], v[44:45], 0, v[154:155]
	v_min_u32_e32 v44, s2, v218
	v_sub_u32_e64 v45, v212, 8 clamp
	v_sub_u32_e32 v44, v44, v45
	v_cvt_f32_i32_e32 v172, v44
	v_cvt_pk_bf16_f32 v45, v100, v101
	v_pk_mul_f32 v[158:159], v[182:183], v[158:159]
	v_cvt_pk_bf16_f32 v46, v178, v179
	v_div_scale_f32 v100, s[0:1], v172, v172, 1.0
	v_rcp_f32_e32 v101, v100
	v_cvt_pk_bf16_f32 v44, v158, v159
	v_cvt_pk_bf16_f32 v47, v98, v99
	global_store_dwordx4 v[102:103], v[44:47], off offset:2048 sc1
	s_waitcnt vmcnt(7)
	v_lshlrev_b32_e32 v98, 16, v60
	v_and_b32_e32 v99, 0xffff0000, v60
	v_fma_f32 v44, -v100, v101, 1.0
	v_fmac_f32_e32 v101, v44, v101
	v_div_scale_f32 v44, vcc, 1.0, v172, 1.0
	v_mul_f32_e32 v45, v44, v101
	v_fma_f32 v46, -v100, v45, v44
	v_fmac_f32_e32 v45, v46, v101
	v_fma_f32 v44, -v100, v45, v44
	v_lshlrev_b32_e32 v46, 16, v32
	v_and_b32_e32 v47, 0xffff0000, v32
	v_div_fmas_f32 v44, v44, v101, v45
	v_pk_add_f32 v[46:47], v[46:47], v[146:147] neg_lo:[0,1] neg_hi:[0,1]
	v_div_fixup_f32 v44, v44, v172, 1.0
	v_pk_add_f32 v[46:47], v[122:123], v[46:47]
	v_lshlrev_b32_e32 v32, 16, v33
	v_and_b32_e32 v33, 0xffff0000, v33
	v_pk_fma_f32 v[100:101], v[44:45], v[46:47], v[166:167] op_sel_hi:[0,1,1] neg_lo:[0,0,1] neg_hi:[0,0,1]
	v_pk_add_f32 v[32:33], v[32:33], v[148:149] neg_lo:[0,1] neg_hi:[0,1]
	v_pk_mul_f32 v[98:99], v[100:101], v[98:99]
	v_pk_add_f32 v[100:101], v[164:165], v[32:33]
	v_lshlrev_b32_e32 v32, 16, v61
	v_and_b32_e32 v33, 0xffff0000, v61
	v_pk_fma_f32 v[60:61], v[44:45], v[100:101], v[162:163] op_sel_hi:[0,1,1] neg_lo:[0,0,1] neg_hi:[0,0,1]
	v_pk_mul_f32 v[60:61], v[60:61], v[32:33]
	v_lshlrev_b32_e32 v32, 16, v34
	v_and_b32_e32 v33, 0xffff0000, v34
	v_pk_add_f32 v[32:33], v[32:33], v[150:151] neg_lo:[0,1] neg_hi:[0,1]
	s_nop 0
	v_pk_add_f32 v[102:103], v[170:171], v[32:33]
	v_lshlrev_b32_e32 v32, 16, v62
	v_and_b32_e32 v33, 0xffff0000, v62
	v_pk_fma_f32 v[122:123], v[44:45], v[102:103], v[160:161] op_sel_hi:[0,1,1] neg_lo:[0,0,1] neg_hi:[0,0,1]
	v_pk_mul_f32 v[122:123], v[122:123], v[32:33]
	v_lshlrev_b32_e32 v32, 16, v35
	v_and_b32_e32 v33, 0xffff0000, v35
	v_pk_add_f32 v[32:33], v[32:33], v[156:157] neg_lo:[0,1] neg_hi:[0,1]
	s_nop 0
	v_pk_add_f32 v[82:83], v[82:83], v[32:33]
	v_lshlrev_b32_e32 v32, 16, v63
	v_and_b32_e32 v33, 0xffff0000, v63
	v_pk_fma_f32 v[34:35], v[44:45], v[82:83], v[114:115] op_sel_hi:[0,1,1] neg_lo:[0,0,1] neg_hi:[0,0,1]
	v_pk_mul_f32 v[44:45], v[34:35], v[32:33]
	v_or_b32_e32 v32, 2, v204
	v_mad_i64_i32 v[32:33], s[0:1], v32, s34, v[70:71]
	v_lshl_add_u64 v[62:63], v[32:33], 0, v[154:155]
	v_min_u32_e32 v32, s2, v217
	v_sub_u32_e64 v33, v211, 8 clamp
	v_sub_u32_e32 v32, v32, v33
	v_cvt_f32_i32_e32 v114, v32
	v_cvt_pk_bf16_f32 v33, v60, v61
	v_cvt_pk_bf16_f32 v32, v98, v99
	v_cvt_pk_bf16_f32 v34, v122, v123
	v_div_scale_f32 v60, s[0:1], v114, v114, 1.0
	v_rcp_f32_e32 v61, v60
	v_cvt_pk_bf16_f32 v35, v44, v45
	global_store_dwordx4 v[62:63], v[32:35], off offset:2048 sc1
	s_waitcnt vmcnt(7)
	v_lshlrev_b32_e32 v44, 16, v40
	v_and_b32_e32 v45, 0xffff0000, v40
	v_fma_f32 v32, -v60, v61, 1.0
	v_fmac_f32_e32 v61, v32, v61
	v_div_scale_f32 v32, vcc, 1.0, v114, 1.0
	v_mul_f32_e32 v33, v32, v61
	v_fma_f32 v34, -v60, v33, v32
	v_fmac_f32_e32 v33, v34, v61
	v_fma_f32 v32, -v60, v33, v32
	v_lshlrev_b32_e32 v34, 16, v24
	v_and_b32_e32 v35, 0xffff0000, v24
	v_div_fmas_f32 v32, v32, v61, v33
	v_pk_add_f32 v[34:35], v[34:35], v[138:139] neg_lo:[0,1] neg_hi:[0,1]
	v_div_fixup_f32 v32, v32, v114, 1.0
	v_pk_add_f32 v[34:35], v[46:47], v[34:35]
	v_lshlrev_b32_e32 v24, 16, v25
	v_and_b32_e32 v25, 0xffff0000, v25
	v_pk_fma_f32 v[46:47], v[32:33], v[34:35], v[112:113] op_sel_hi:[0,1,1] neg_lo:[0,0,1] neg_hi:[0,0,1]
	v_pk_add_f32 v[24:25], v[24:25], v[140:141] neg_lo:[0,1] neg_hi:[0,1]
	v_pk_mul_f32 v[44:45], v[46:47], v[44:45]
	v_pk_add_f32 v[46:47], v[100:101], v[24:25]
	v_lshlrev_b32_e32 v24, 16, v41
	v_and_b32_e32 v25, 0xffff0000, v41
	v_pk_fma_f32 v[40:41], v[32:33], v[46:47], v[118:119] op_sel_hi:[0,1,1] neg_lo:[0,0,1] neg_hi:[0,0,1]
	v_pk_mul_f32 v[40:41], v[40:41], v[24:25]
	v_lshlrev_b32_e32 v24, 16, v26
	v_and_b32_e32 v25, 0xffff0000, v26
	v_pk_add_f32 v[24:25], v[24:25], v[142:143] neg_lo:[0,1] neg_hi:[0,1]
	s_nop 0
	v_pk_add_f32 v[60:61], v[102:103], v[24:25]
	v_lshlrev_b32_e32 v24, 16, v42
	v_and_b32_e32 v25, 0xffff0000, v42
	v_pk_fma_f32 v[62:63], v[32:33], v[60:61], v[168:169] op_sel_hi:[0,1,1] neg_lo:[0,0,1] neg_hi:[0,0,1]
	v_pk_mul_f32 v[62:63], v[62:63], v[24:25]
	v_lshlrev_b32_e32 v24, 16, v27
	v_and_b32_e32 v25, 0xffff0000, v27
	v_pk_add_f32 v[24:25], v[24:25], v[144:145] neg_lo:[0,1] neg_hi:[0,1]
	s_nop 0
	v_pk_add_f32 v[82:83], v[82:83], v[24:25]
	v_lshlrev_b32_e32 v24, 16, v43
	v_and_b32_e32 v25, 0xffff0000, v43
	v_pk_fma_f32 v[26:27], v[32:33], v[82:83], v[176:177] op_sel_hi:[0,1,1] neg_lo:[0,0,1] neg_hi:[0,0,1]
	v_pk_mul_f32 v[32:33], v[26:27], v[24:25]
	v_or_b32_e32 v24, 3, v204
	v_mad_i64_i32 v[24:25], s[0:1], v24, s34, v[70:71]
	v_lshl_add_u64 v[42:43], v[24:25], 0, v[154:155]
	v_min_u32_e32 v24, s2, v215
	v_sub_u32_e64 v25, v210, 8 clamp
	v_sub_u32_e32 v24, v24, v25
	v_cvt_f32_i32_e32 v98, v24
	v_cvt_pk_bf16_f32 v25, v40, v41
	v_cvt_pk_bf16_f32 v24, v44, v45
	v_cvt_pk_bf16_f32 v26, v62, v63
	v_div_scale_f32 v40, s[0:1], v98, v98, 1.0
	v_rcp_f32_e32 v41, v40
	v_cvt_pk_bf16_f32 v27, v32, v33
	global_store_dwordx4 v[42:43], v[24:27], off offset:2048 sc1
	s_waitcnt vmcnt(7)
	v_lshlrev_b32_e32 v32, 16, v36
	v_and_b32_e32 v33, 0xffff0000, v36
	v_fma_f32 v24, -v40, v41, 1.0
	v_fmac_f32_e32 v41, v24, v41
	v_div_scale_f32 v24, vcc, 1.0, v98, 1.0
	v_mul_f32_e32 v25, v24, v41
	v_fma_f32 v26, -v40, v25, v24
	v_fmac_f32_e32 v25, v26, v41
	v_fma_f32 v24, -v40, v25, v24
	v_lshlrev_b32_e32 v26, 16, v20
	v_and_b32_e32 v27, 0xffff0000, v20
	v_div_fmas_f32 v24, v24, v41, v25
	v_pk_add_f32 v[26:27], v[26:27], v[134:135] neg_lo:[0,1] neg_hi:[0,1]
	v_div_fixup_f32 v24, v24, v98, 1.0
	v_pk_add_f32 v[26:27], v[34:35], v[26:27]
	v_lshlrev_b32_e32 v20, 16, v21
	v_and_b32_e32 v21, 0xffff0000, v21
	v_pk_fma_f32 v[34:35], v[24:25], v[26:27], v[106:107] op_sel_hi:[0,1,1] neg_lo:[0,0,1] neg_hi:[0,0,1]
	v_pk_add_f32 v[20:21], v[20:21], v[136:137] neg_lo:[0,1] neg_hi:[0,1]
	v_pk_mul_f32 v[32:33], v[34:35], v[32:33]
	v_pk_add_f32 v[34:35], v[46:47], v[20:21]
	v_lshlrev_b32_e32 v20, 16, v37
	v_and_b32_e32 v21, 0xffff0000, v37
	v_pk_fma_f32 v[36:37], v[24:25], v[34:35], v[110:111] op_sel_hi:[0,1,1] neg_lo:[0,0,1] neg_hi:[0,0,1]
	v_pk_mul_f32 v[36:37], v[36:37], v[20:21]
	v_lshlrev_b32_e32 v20, 16, v22
	v_and_b32_e32 v21, 0xffff0000, v22
	v_pk_add_f32 v[20:21], v[20:21], v[104:105] neg_lo:[0,1] neg_hi:[0,1]
	s_nop 0
	v_pk_add_f32 v[40:41], v[60:61], v[20:21]
	v_lshlrev_b32_e32 v20, 16, v38
	v_and_b32_e32 v21, 0xffff0000, v38
	v_pk_fma_f32 v[42:43], v[24:25], v[40:41], v[116:117] op_sel_hi:[0,1,1] neg_lo:[0,0,1] neg_hi:[0,0,1]
	v_pk_mul_f32 v[42:43], v[42:43], v[20:21]
	v_lshlrev_b32_e32 v20, 16, v23
	v_and_b32_e32 v21, 0xffff0000, v23
	v_pk_add_f32 v[20:21], v[20:21], v[108:109] neg_lo:[0,1] neg_hi:[0,1]
	s_nop 0
	v_pk_add_f32 v[44:45], v[82:83], v[20:21]
	v_lshlrev_b32_e32 v20, 16, v39
	v_and_b32_e32 v21, 0xffff0000, v39
	v_pk_fma_f32 v[22:23], v[24:25], v[44:45], v[120:121] op_sel_hi:[0,1,1] neg_lo:[0,0,1] neg_hi:[0,0,1]
	v_pk_mul_f32 v[24:25], v[22:23], v[20:21]
	v_or_b32_e32 v20, 4, v204
	v_mad_i64_i32 v[20:21], s[0:1], v20, s34, v[70:71]
	v_lshl_add_u64 v[38:39], v[20:21], 0, v[154:155]
	v_min_u32_e32 v20, s2, v214
	v_sub_u32_e64 v21, v209, 8 clamp
	v_sub_u32_e32 v20, v20, v21
	v_cvt_f32_i32_e32 v46, v20
	v_cvt_pk_bf16_f32 v20, v32, v33
	v_cvt_pk_bf16_f32 v21, v36, v37
	v_cvt_pk_bf16_f32 v22, v42, v43
	v_div_scale_f32 v32, s[0:1], v46, v46, 1.0
	v_rcp_f32_e32 v33, v32
	v_cvt_pk_bf16_f32 v23, v24, v25
	global_store_dwordx4 v[38:39], v[20:23], off offset:2048 sc1
	s_waitcnt vmcnt(7)
	v_lshlrev_b32_e32 v24, 16, v28
	v_and_b32_e32 v25, 0xffff0000, v28
	v_fma_f32 v20, -v32, v33, 1.0
	v_fmac_f32_e32 v33, v20, v33
	v_div_scale_f32 v20, vcc, 1.0, v46, 1.0
	v_mul_f32_e32 v21, v20, v33
	v_fma_f32 v22, -v32, v21, v20
	v_fmac_f32_e32 v21, v22, v33
	v_fma_f32 v20, -v32, v21, v20
	v_lshlrev_b32_e32 v22, 16, v12
	v_and_b32_e32 v23, 0xffff0000, v12
	v_div_fmas_f32 v20, v20, v33, v21
	v_pk_add_f32 v[22:23], v[22:23], v[132:133] neg_lo:[0,1] neg_hi:[0,1]
	v_div_fixup_f32 v20, v20, v46, 1.0
	v_pk_add_f32 v[22:23], v[26:27], v[22:23]
	v_lshlrev_b32_e32 v12, 16, v13
	v_and_b32_e32 v13, 0xffff0000, v13
	v_pk_fma_f32 v[26:27], v[20:21], v[22:23], v[94:95] op_sel_hi:[0,1,1] neg_lo:[0,0,1] neg_hi:[0,0,1]
	v_pk_add_f32 v[12:13], v[12:13], v[92:93] neg_lo:[0,1] neg_hi:[0,1]
	v_pk_mul_f32 v[24:25], v[26:27], v[24:25]
	v_pk_add_f32 v[26:27], v[34:35], v[12:13]
	v_lshlrev_b32_e32 v12, 16, v29
	v_and_b32_e32 v13, 0xffff0000, v29
	v_pk_fma_f32 v[28:29], v[20:21], v[26:27], v[84:85] op_sel_hi:[0,1,1] neg_lo:[0,0,1] neg_hi:[0,0,1]
	v_pk_mul_f32 v[28:29], v[28:29], v[12:13]
	v_lshlrev_b32_e32 v12, 16, v14
	v_and_b32_e32 v13, 0xffff0000, v14
	v_pk_add_f32 v[12:13], v[12:13], v[88:89] neg_lo:[0,1] neg_hi:[0,1]
	s_nop 0
	v_pk_add_f32 v[32:33], v[40:41], v[12:13]
	v_lshlrev_b32_e32 v12, 16, v30
	v_and_b32_e32 v13, 0xffff0000, v30
	v_pk_fma_f32 v[34:35], v[20:21], v[32:33], v[96:97] op_sel_hi:[0,1,1] neg_lo:[0,0,1] neg_hi:[0,0,1]
	v_pk_mul_f32 v[34:35], v[34:35], v[12:13]
	v_lshlrev_b32_e32 v12, 16, v15
	v_and_b32_e32 v13, 0xffff0000, v15
	v_pk_add_f32 v[12:13], v[12:13], v[78:79] neg_lo:[0,1] neg_hi:[0,1]
	s_nop 0
	v_pk_add_f32 v[36:37], v[44:45], v[12:13]
	v_lshlrev_b32_e32 v12, 16, v31
	v_and_b32_e32 v13, 0xffff0000, v31
	v_pk_fma_f32 v[14:15], v[20:21], v[36:37], v[86:87] op_sel_hi:[0,1,1] neg_lo:[0,0,1] neg_hi:[0,0,1]
	v_pk_mul_f32 v[20:21], v[14:15], v[12:13]
	v_or_b32_e32 v12, 5, v204
	v_mad_i64_i32 v[12:13], s[0:1], v12, s34, v[70:71]
	v_lshl_add_u64 v[30:31], v[12:13], 0, v[154:155]
	v_min_u32_e32 v12, s2, v213
	v_sub_u32_e64 v13, v208, 8 clamp
	v_sub_u32_e32 v12, v12, v13
	v_cvt_f32_i32_e32 v38, v12
	v_cvt_pk_bf16_f32 v12, v24, v25
	v_cvt_pk_bf16_f32 v13, v28, v29
	v_cvt_pk_bf16_f32 v14, v34, v35
	v_div_scale_f32 v24, s[0:1], v38, v38, 1.0
	v_rcp_f32_e32 v25, v24
	v_cvt_pk_bf16_f32 v15, v20, v21
	global_store_dwordx4 v[30:31], v[12:15], off offset:2048 sc1
	s_waitcnt vmcnt(7)
	v_lshlrev_b32_e32 v20, 16, v16
	v_and_b32_e32 v21, 0xffff0000, v16
	v_fma_f32 v12, -v24, v25, 1.0
	v_fmac_f32_e32 v25, v12, v25
	v_div_scale_f32 v12, vcc, 1.0, v38, 1.0
	v_mul_f32_e32 v13, v12, v25
	v_fma_f32 v14, -v24, v13, v12
	v_fmac_f32_e32 v13, v14, v25
	v_fma_f32 v12, -v24, v13, v12
	v_lshlrev_b32_e32 v14, 16, v4
	v_and_b32_e32 v15, 0xffff0000, v4
	v_div_fmas_f32 v12, v12, v25, v13
	v_pk_add_f32 v[14:15], v[14:15], v[130:131] neg_lo:[0,1] neg_hi:[0,1]
	v_div_fixup_f32 v12, v12, v38, 1.0
	v_pk_add_f32 v[14:15], v[22:23], v[14:15]
	v_lshlrev_b32_e32 v4, 16, v5
	v_and_b32_e32 v5, 0xffff0000, v5
	v_pk_fma_f32 v[22:23], v[12:13], v[14:15], v[90:91] op_sel_hi:[0,1,1] neg_lo:[0,0,1] neg_hi:[0,0,1]
	v_pk_add_f32 v[4:5], v[4:5], v[72:73] neg_lo:[0,1] neg_hi:[0,1]
	v_pk_mul_f32 v[20:21], v[22:23], v[20:21]
	v_pk_add_f32 v[22:23], v[26:27], v[4:5]
	v_lshlrev_b32_e32 v4, 16, v17
	v_and_b32_e32 v5, 0xffff0000, v17
	v_pk_fma_f32 v[16:17], v[12:13], v[22:23], v[68:69] op_sel_hi:[0,1,1] neg_lo:[0,0,1] neg_hi:[0,0,1]
	v_pk_mul_f32 v[16:17], v[16:17], v[4:5]
	v_lshlrev_b32_e32 v4, 16, v6
	v_and_b32_e32 v5, 0xffff0000, v6
	v_pk_add_f32 v[4:5], v[4:5], v[76:77] neg_lo:[0,1] neg_hi:[0,1]
	s_nop 0
	v_pk_add_f32 v[24:25], v[32:33], v[4:5]
	v_lshlrev_b32_e32 v4, 16, v18
	v_and_b32_e32 v5, 0xffff0000, v18
	v_pk_fma_f32 v[26:27], v[12:13], v[24:25], v[80:81] op_sel_hi:[0,1,1] neg_lo:[0,0,1] neg_hi:[0,0,1]
	v_pk_mul_f32 v[26:27], v[26:27], v[4:5]
	v_lshlrev_b32_e32 v4, 16, v7
	v_and_b32_e32 v5, 0xffff0000, v7
	v_pk_add_f32 v[4:5], v[4:5], v[58:59] neg_lo:[0,1] neg_hi:[0,1]
	s_nop 0
	v_pk_add_f32 v[28:29], v[36:37], v[4:5]
	v_lshlrev_b32_e32 v4, 16, v19
	v_and_b32_e32 v5, 0xffff0000, v19
	v_pk_fma_f32 v[6:7], v[12:13], v[28:29], v[66:67] op_sel_hi:[0,1,1] neg_lo:[0,0,1] neg_hi:[0,0,1]
	v_pk_mul_f32 v[12:13], v[6:7], v[4:5]
	v_or_b32_e32 v4, 6, v204
	v_mad_i64_i32 v[4:5], s[0:1], v4, s34, v[70:71]
	v_lshl_add_u64 v[18:19], v[4:5], 0, v[154:155]
	v_add_u32_e32 v4, 15, v206
	v_min_u32_e32 v4, s2, v4
	v_sub_u32_e64 v5, v207, 8 clamp
	v_sub_u32_e32 v4, v4, v5
	v_cvt_f32_i32_e32 v30, v4
	v_cvt_pk_bf16_f32 v5, v16, v17
	v_cvt_pk_bf16_f32 v4, v20, v21
	v_cvt_pk_bf16_f32 v6, v26, v27
	v_div_scale_f32 v16, s[0:1], v30, v30, 1.0
	v_rcp_f32_e32 v17, v16
	v_cvt_pk_bf16_f32 v7, v12, v13
	global_store_dwordx4 v[18:19], v[4:7], off offset:2048 sc1
	s_waitcnt vmcnt(7)
	v_lshlrev_b32_e32 v12, 16, v8
	v_and_b32_e32 v13, 0xffff0000, v8
	v_fma_f32 v4, -v16, v17, 1.0
	v_fmac_f32_e32 v17, v4, v17
	v_div_scale_f32 v4, vcc, 1.0, v30, 1.0
	v_mul_f32_e32 v5, v4, v17
	v_fma_f32 v6, -v16, v5, v4
	v_fmac_f32_e32 v5, v6, v17
	v_fma_f32 v4, -v16, v5, v4
	v_lshlrev_b32_e32 v6, 16, v0
	v_and_b32_e32 v7, 0xffff0000, v0
	v_lshlrev_b32_e32 v0, 16, v1
	v_and_b32_e32 v1, 0xffff0000, v1
	v_div_fmas_f32 v4, v4, v17, v5
	v_pk_add_f32 v[0:1], v[0:1], v[52:53] neg_lo:[0,1] neg_hi:[0,1]
	v_div_fixup_f32 v4, v4, v30, 1.0
	v_pk_add_f32 v[0:1], v[22:23], v[0:1]
	v_lshlrev_b32_e32 v8, 16, v9
	v_and_b32_e32 v9, 0xffff0000, v9
	v_pk_fma_f32 v[0:1], v[4:5], v[0:1], v[48:49] op_sel_hi:[0,1,1] neg_lo:[0,0,1] neg_hi:[0,0,1]
	v_pk_add_f32 v[6:7], v[6:7], v[128:129] neg_lo:[0,1] neg_hi:[0,1]
	v_pk_mul_f32 v[8:9], v[0:1], v[8:9]
	v_lshlrev_b32_e32 v0, 16, v2
	v_and_b32_e32 v1, 0xffff0000, v2
	v_pk_add_f32 v[6:7], v[14:15], v[6:7]
	v_pk_add_f32 v[0:1], v[0:1], v[56:57] neg_lo:[0,1] neg_hi:[0,1]
	v_pk_fma_f32 v[6:7], v[4:5], v[6:7], v[74:75] op_sel_hi:[0,1,1] neg_lo:[0,0,1] neg_hi:[0,0,1]
	v_pk_add_f32 v[0:1], v[24:25], v[0:1]
	v_pk_mul_f32 v[6:7], v[6:7], v[12:13]
	v_lshlrev_b32_e32 v12, 16, v10
	v_and_b32_e32 v13, 0xffff0000, v10
	v_pk_fma_f32 v[0:1], v[4:5], v[0:1], v[64:65] op_sel_hi:[0,1,1] neg_lo:[0,0,1] neg_hi:[0,0,1]
	v_pk_mul_f32 v[12:13], v[0:1], v[12:13]
	v_lshlrev_b32_e32 v0, 16, v3
	v_and_b32_e32 v1, 0xffff0000, v3
	v_pk_add_f32 v[0:1], v[0:1], v[54:55] neg_lo:[0,1] neg_hi:[0,1]
	v_lshlrev_b32_e32 v2, 16, v11
	v_pk_add_f32 v[0:1], v[28:29], v[0:1]
	v_and_b32_e32 v3, 0xffff0000, v11
	v_pk_fma_f32 v[0:1], v[4:5], v[0:1], v[50:51] op_sel_hi:[0,1,1] neg_lo:[0,0,1] neg_hi:[0,0,1]
	v_pk_mul_f32 v[4:5], v[0:1], v[2:3]
	v_or_b32_e32 v0, 7, v204
	v_mad_i64_i32 v[0:1], s[0:1], v0, s34, v[70:71]
	v_lshl_add_u64 v[10:11], v[0:1], 0, v[154:155]
	v_cvt_pk_bf16_f32 v0, v6, v7
	v_cvt_pk_bf16_f32 v1, v8, v9
	v_cvt_pk_bf16_f32 v2, v12, v13
	v_cvt_pk_bf16_f32 v3, v4, v5
	global_store_dwordx4 v[10:11], v[0:3], off offset:2048 sc1

.LBB0_291:
	s_or_b64 exec, exec, s[0:1]
	global_load_dwordx4 v[68:71], v[126:127], off offset:2048
	v_add_co_u32_e32 v20, vcc, 0x2000, v126
	s_mov_b64 s[40:41], vcc
	v_min_u32_e32 v21, s2, v66
	v_sub_u32_e64 v23, v206, 1 clamp
	v_add_co_u32_e32 v22, vcc, 0x4000, v126
	s_mov_b64 s[42:43], vcc
	v_sub_u32_e32 v23, v21, v23
	v_addc_co_u32_e64 v21, vcc, 0, v127, s[40:41]
	global_load_dwordx4 v[72:75], v[20:21], off offset:2176
	v_add_co_u32_e32 v42, vcc, 0x6000, v126
	s_mov_b64 s[40:41], vcc
	v_cvt_f32_i32_e32 v67, v23
	v_addc_co_u32_e64 v23, vcc, 0, v127, s[42:43]
	v_add_co_u32_e32 v20, vcc, 0x8000, v126
	s_mov_b64 s[42:43], vcc
	v_addc_co_u32_e64 v43, vcc, 0, v127, s[40:41]
	global_load_dwordx4 v[54:57], v[22:23], off offset:2304
	global_load_dwordx4 v[50:53], v[42:43], off offset:2432
	s_waitcnt vmcnt(5)
	v_lshlrev_b32_e32 v76, 16, v34
	v_and_b32_e32 v77, 0xffff0000, v34
	s_waitcnt vmcnt(4)
	v_lshlrev_b32_e32 v58, 16, v38
	v_and_b32_e32 v59, 0xffff0000, v38
	v_pk_add_f32 v[32:33], v[76:77], 0 op_sel_hi:[1,0]
	v_div_scale_f32 v81, s[0:1], v67, v67, 1.0
	v_pk_add_f32 v[82:83], v[32:33], v[58:59]
	v_add_co_u32_e32 v32, vcc, s11, v126
	s_mov_b64 s[40:41], vcc
	v_addc_co_u32_e64 v21, vcc, 0, v127, s[42:43]
	v_rcp_f32_e32 v89, v81
	v_add_co_u32_e32 v22, vcc, s12, v126
	v_lshlrev_b32_e32 v78, 16, v35
	v_and_b32_e32 v79, 0xffff0000, v35
	s_mov_b64 s[42:43], vcc
	v_addc_co_u32_e64 v33, vcc, 0, v127, s[40:41]
	v_lshlrev_b32_e32 v38, 16, v39
	v_and_b32_e32 v39, 0xffff0000, v39
	v_pk_add_f32 v[34:35], v[78:79], 0 op_sel_hi:[1,0]
	v_add_co_u32_e32 v86, vcc, s13, v126
	v_addc_co_u32_e64 v23, s[42:43], 0, v127, s[42:43]
	v_pk_add_f32 v[84:85], v[34:35], v[38:39]
	global_load_dwordx4 v[46:49], v[20:21], off offset:2560
	global_load_dwordx4 v[42:45], v[32:33], off offset:2688
	v_addc_co_u32_e32 v87, vcc, 0, v127, vcc
	global_load_dwordx4 v[32:35], v[22:23], off offset:2816
	s_nop 0
	global_load_dwordx4 v[20:23], v[86:87], off offset:2944
	v_fma_f32 v86, -v81, v89, 1.0
	v_div_scale_f32 v88, s[40:41], 1.0, v67, 1.0
	v_fmac_f32_e32 v89, v86, v89
	v_mul_f32_e32 v86, v88, v89
	v_fma_f32 v87, -v81, v86, v88
	v_fmac_f32_e32 v86, v87, v89
	v_fma_f32 v81, -v81, v86, v88
	s_mov_b64 vcc, s[40:41]
	v_div_fmas_f32 v81, v81, v89, v86
	v_div_fixup_f32 v86, v81, v67, 1.0
	v_min_u32_e32 v67, s2, v65
	v_lshlrev_b32_e32 v80, 16, v36
	v_pk_fma_f32 v[88:89], v[86:87], v[82:83], v[58:59] op_sel_hi:[0,1,1] neg_lo:[0,0,1] neg_hi:[0,0,1]
	v_pk_fma_f32 v[90:91], v[86:87], v[84:85], v[38:39] op_sel_hi:[0,1,1] neg_lo:[0,0,1] neg_hi:[0,0,1]
	v_and_b32_e32 v81, 0xffff0000, v36
	v_sub_u32_e32 v66, v67, v66
	v_add_u32_e32 v66, 1, v66
	v_cvt_f32_i32_e32 v100, v66
	s_waitcnt vmcnt(7)
	v_lshlrev_b32_e32 v92, 16, v68
	v_and_b32_e32 v93, 0xffff0000, v68
	v_lshlrev_b32_e32 v68, 16, v69
	v_and_b32_e32 v69, 0xffff0000, v69
	v_pk_mul_f32 v[88:89], v[88:89], v[92:93]
	v_pk_mul_f32 v[68:69], v[90:91], v[68:69]
	v_pk_add_f32 v[90:91], v[80:81], 0 op_sel_hi:[1,0]
	v_lshlrev_b32_e32 v92, 16, v40
	v_and_b32_e32 v93, 0xffff0000, v40
	v_pk_add_f32 v[90:91], v[90:91], v[92:93]
	v_lshlrev_b32_e32 v94, 16, v70
	v_and_b32_e32 v95, 0xffff0000, v70
	v_pk_fma_f32 v[96:97], v[86:87], v[90:91], v[92:93] op_sel_hi:[0,1,1] neg_lo:[0,0,1] neg_hi:[0,0,1]
	v_pk_mul_f32 v[94:95], v[96:97], v[94:95]
	v_lshlrev_b32_e32 v96, 16, v37
	v_and_b32_e32 v97, 0xffff0000, v37
	v_pk_add_f32 v[36:37], v[96:97], 0 op_sel_hi:[1,0]
	v_lshlrev_b32_e32 v40, 16, v41
	v_and_b32_e32 v41, 0xffff0000, v41
	v_pk_add_f32 v[98:99], v[36:37], v[40:41]
	v_cvt_pk_bf16_f32 v66, v88, v89
	v_div_scale_f32 v88, s[0:1], v100, v100, 1.0
	v_lshlrev_b32_e32 v36, 16, v71
	v_and_b32_e32 v37, 0xffff0000, v71
	v_pk_fma_f32 v[70:71], v[86:87], v[98:99], v[40:41] op_sel_hi:[0,1,1] neg_lo:[0,0,1] neg_hi:[0,0,1]
	v_rcp_f32_e32 v89, v88
	v_pk_mul_f32 v[70:71], v[70:71], v[36:37]
	v_mov_b64_e32 v[36:37], s[38:39]
	v_mad_i64_i32 v[86:87], s[0:1], v204, s34, v[36:37]
	v_lshl_add_u64 v[86:87], v[86:87], 0, v[154:155]
	v_cvt_pk_bf16_f32 v67, v68, v69
	v_cvt_pk_bf16_f32 v68, v94, v95
	v_cvt_pk_bf16_f32 v69, v70, v71
	global_store_dwordx4 v[86:87], v[66:69], off offset:2048 sc1
	s_nop 1
	v_fma_f32 v66, -v88, v89, 1.0
	v_fmac_f32_e32 v89, v66, v89
	v_div_scale_f32 v66, vcc, 1.0, v100, 1.0
	v_mul_f32_e32 v67, v66, v89
	v_fma_f32 v68, -v88, v67, v66
	v_fmac_f32_e32 v67, v68, v89
	v_fma_f32 v66, -v88, v67, v66
	v_lshlrev_b32_e32 v68, 16, v28
	v_and_b32_e32 v69, 0xffff0000, v28
	v_div_fmas_f32 v66, v66, v89, v67
	v_pk_add_f32 v[70:71], v[68:69], v[76:77] neg_lo:[0,1] neg_hi:[0,1]
	v_div_fixup_f32 v66, v66, v100, 1.0
	v_pk_add_f32 v[70:71], v[82:83], v[70:71]
	s_waitcnt vmcnt(7)
	v_lshlrev_b32_e32 v76, 16, v72
	v_and_b32_e32 v77, 0xffff0000, v72
	v_pk_fma_f32 v[82:83], v[66:67], v[70:71], v[68:69] op_sel_hi:[0,1,1] neg_lo:[0,0,1] neg_hi:[0,0,1]
	v_pk_mul_f32 v[76:77], v[82:83], v[76:77]
	v_lshlrev_b32_e32 v82, 16, v29
	v_and_b32_e32 v83, 0xffff0000, v29
	v_pk_add_f32 v[28:29], v[82:83], v[78:79] neg_lo:[0,1] neg_hi:[0,1]
	v_lshlrev_b32_e32 v88, 16, v31
	v_pk_add_f32 v[78:79], v[84:85], v[28:29]
	v_lshlrev_b32_e32 v28, 16, v73
	v_and_b32_e32 v29, 0xffff0000, v73
	v_pk_fma_f32 v[72:73], v[66:67], v[78:79], v[82:83] op_sel_hi:[0,1,1] neg_lo:[0,0,1] neg_hi:[0,0,1]
	v_lshlrev_b32_e32 v84, 16, v30
	v_and_b32_e32 v85, 0xffff0000, v30
	v_pk_mul_f32 v[72:73], v[72:73], v[28:29]
	v_pk_add_f32 v[28:29], v[84:85], v[80:81] neg_lo:[0,1] neg_hi:[0,1]
	v_and_b32_e32 v89, 0xffff0000, v31
	v_pk_add_f32 v[80:81], v[90:91], v[28:29]
	v_lshlrev_b32_e32 v28, 16, v74
	v_and_b32_e32 v29, 0xffff0000, v74
	v_pk_fma_f32 v[86:87], v[66:67], v[80:81], v[84:85] op_sel_hi:[0,1,1] neg_lo:[0,0,1] neg_hi:[0,0,1]
	v_pk_mul_f32 v[86:87], v[86:87], v[28:29]
	v_pk_add_f32 v[28:29], v[88:89], v[96:97] neg_lo:[0,1] neg_hi:[0,1]
	s_nop 0
	v_pk_add_f32 v[90:91], v[98:99], v[28:29]
	v_lshlrev_b32_e32 v28, 16, v75
	v_and_b32_e32 v29, 0xffff0000, v75
	v_pk_fma_f32 v[30:31], v[66:67], v[90:91], v[88:89] op_sel_hi:[0,1,1] neg_lo:[0,0,1] neg_hi:[0,0,1]
	v_pk_mul_f32 v[66:67], v[30:31], v[28:29]
	v_or_b32_e32 v28, 1, v204
	v_mad_i64_i32 v[28:29], s[0:1], v28, s34, v[36:37]
	v_lshl_add_u64 v[74:75], v[28:29], 0, v[154:155]
	v_min_u32_e32 v28, s2, v64
	v_sub_u32_e32 v28, v28, v65
	v_add_u32_e32 v28, 1, v28
	v_cvt_f32_i32_e32 v65, v28
	v_cvt_pk_bf16_f32 v29, v72, v73
	v_cvt_pk_bf16_f32 v28, v76, v77
	v_cvt_pk_bf16_f32 v30, v86, v87
	v_div_scale_f32 v72, s[0:1], v65, v65, 1.0
	v_rcp_f32_e32 v73, v72
	v_cvt_pk_bf16_f32 v31, v66, v67
	global_store_dwordx4 v[74:75], v[28:31], off offset:2048 sc1
	s_waitcnt vmcnt(7)
	v_lshlrev_b32_e32 v66, 16, v54
	v_and_b32_e32 v67, 0xffff0000, v54
	v_fma_f32 v28, -v72, v73, 1.0
	v_fmac_f32_e32 v73, v28, v73
	v_div_scale_f32 v28, vcc, 1.0, v65, 1.0
	v_mul_f32_e32 v29, v28, v73
	v_fma_f32 v30, -v72, v29, v28
	v_fmac_f32_e32 v29, v30, v73
	v_fma_f32 v28, -v72, v29, v28
	v_lshlrev_b32_e32 v30, 16, v24
	v_and_b32_e32 v31, 0xffff0000, v24
	v_div_fmas_f32 v28, v28, v73, v29
	v_pk_add_f32 v[58:59], v[30:31], v[58:59] neg_lo:[0,1] neg_hi:[0,1]
	v_div_fixup_f32 v28, v28, v65, 1.0
	v_pk_add_f32 v[58:59], v[70:71], v[58:59]
	v_lshlrev_b32_e32 v72, 16, v26
	v_pk_fma_f32 v[70:71], v[28:29], v[58:59], v[30:31] op_sel_hi:[0,1,1] neg_lo:[0,0,1] neg_hi:[0,0,1]
	v_pk_mul_f32 v[66:67], v[70:71], v[66:67]
	v_lshlrev_b32_e32 v70, 16, v25
	v_and_b32_e32 v71, 0xffff0000, v25
	v_pk_add_f32 v[24:25], v[70:71], v[38:39] neg_lo:[0,1] neg_hi:[0,1]
	v_and_b32_e32 v73, 0xffff0000, v26
	v_pk_add_f32 v[38:39], v[78:79], v[24:25]
	v_lshlrev_b32_e32 v24, 16, v55
	v_and_b32_e32 v25, 0xffff0000, v55
	v_pk_fma_f32 v[54:55], v[28:29], v[38:39], v[70:71] op_sel_hi:[0,1,1] neg_lo:[0,0,1] neg_hi:[0,0,1]
	v_pk_mul_f32 v[54:55], v[54:55], v[24:25]
	v_pk_add_f32 v[24:25], v[72:73], v[92:93] neg_lo:[0,1] neg_hi:[0,1]
	v_lshlrev_b32_e32 v78, 16, v27
	v_pk_add_f32 v[74:75], v[80:81], v[24:25]
	v_lshlrev_b32_e32 v24, 16, v56
	v_and_b32_e32 v25, 0xffff0000, v56
	v_pk_fma_f32 v[76:77], v[28:29], v[74:75], v[72:73] op_sel_hi:[0,1,1] neg_lo:[0,0,1] neg_hi:[0,0,1]
	v_and_b32_e32 v79, 0xffff0000, v27
	v_pk_mul_f32 v[76:77], v[76:77], v[24:25]
	v_pk_add_f32 v[24:25], v[78:79], v[40:41] neg_lo:[0,1] neg_hi:[0,1]
	s_nop 0
	v_pk_add_f32 v[40:41], v[90:91], v[24:25]
	v_lshlrev_b32_e32 v24, 16, v57
	v_and_b32_e32 v25, 0xffff0000, v57
	v_pk_fma_f32 v[26:27], v[28:29], v[40:41], v[78:79] op_sel_hi:[0,1,1] neg_lo:[0,0,1] neg_hi:[0,0,1]
	v_pk_mul_f32 v[28:29], v[26:27], v[24:25]
	v_or_b32_e32 v24, 2, v204
	v_mad_i64_i32 v[24:25], s[0:1], v24, s34, v[36:37]
	v_lshl_add_u64 v[56:57], v[24:25], 0, v[154:155]
	v_min_u32_e32 v24, s2, v63
	v_sub_u32_e32 v24, v24, v64
	v_add_u32_e32 v24, 1, v24
	v_cvt_f32_i32_e32 v64, v24
	v_cvt_pk_bf16_f32 v25, v54, v55
	v_cvt_pk_bf16_f32 v24, v66, v67
	v_cvt_pk_bf16_f32 v26, v76, v77
	v_div_scale_f32 v54, s[0:1], v64, v64, 1.0
	v_rcp_f32_e32 v55, v54
	v_cvt_pk_bf16_f32 v27, v28, v29
	global_store_dwordx4 v[56:57], v[24:27], off offset:2048 sc1
	s_nop 1
	v_fma_f32 v24, -v54, v55, 1.0
	v_fmac_f32_e32 v55, v24, v55
	v_div_scale_f32 v24, vcc, 1.0, v64, 1.0
	v_mul_f32_e32 v25, v24, v55
	v_fma_f32 v26, -v54, v25, v24
	v_fmac_f32_e32 v25, v26, v55
	v_fma_f32 v24, -v54, v25, v24
	v_lshlrev_b32_e32 v26, 16, v16
	v_and_b32_e32 v27, 0xffff0000, v16
	v_div_fmas_f32 v24, v24, v55, v25
	v_pk_add_f32 v[28:29], v[26:27], v[68:69] neg_lo:[0,1] neg_hi:[0,1]
	v_div_fixup_f32 v24, v24, v64, 1.0
	v_pk_add_f32 v[28:29], v[58:59], v[28:29]
	s_waitcnt vmcnt(7)
	v_lshlrev_b32_e32 v54, 16, v50
	v_and_b32_e32 v55, 0xffff0000, v50
	v_pk_fma_f32 v[56:57], v[24:25], v[28:29], v[26:27] op_sel_hi:[0,1,1] neg_lo:[0,0,1] neg_hi:[0,0,1]
	v_pk_mul_f32 v[54:55], v[56:57], v[54:55]
	v_lshlrev_b32_e32 v56, 16, v17
	v_and_b32_e32 v57, 0xffff0000, v17
	v_pk_add_f32 v[16:17], v[56:57], v[82:83] neg_lo:[0,1] neg_hi:[0,1]
	v_lshlrev_b32_e32 v58, 16, v18
	v_pk_add_f32 v[38:39], v[38:39], v[16:17]
	v_lshlrev_b32_e32 v16, 16, v51
	v_and_b32_e32 v17, 0xffff0000, v51
	v_pk_fma_f32 v[50:51], v[24:25], v[38:39], v[56:57] op_sel_hi:[0,1,1] neg_lo:[0,0,1] neg_hi:[0,0,1]
	v_and_b32_e32 v59, 0xffff0000, v18
	v_pk_mul_f32 v[50:51], v[50:51], v[16:17]
	v_pk_add_f32 v[16:17], v[58:59], v[84:85] neg_lo:[0,1] neg_hi:[0,1]
	v_lshlrev_b32_e32 v68, 16, v19
	v_pk_add_f32 v[64:65], v[74:75], v[16:17]
	v_lshlrev_b32_e32 v16, 16, v52
	v_and_b32_e32 v17, 0xffff0000, v52
	v_pk_fma_f32 v[66:67], v[24:25], v[64:65], v[58:59] op_sel_hi:[0,1,1] neg_lo:[0,0,1] neg_hi:[0,0,1]
	v_and_b32_e32 v69, 0xffff0000, v19
	v_pk_mul_f32 v[66:67], v[66:67], v[16:17]
	v_pk_add_f32 v[16:17], v[68:69], v[88:89] neg_lo:[0,1] neg_hi:[0,1]
	s_nop 0
	v_pk_add_f32 v[40:41], v[40:41], v[16:17]
	v_lshlrev_b32_e32 v16, 16, v53
	v_and_b32_e32 v17, 0xffff0000, v53
	v_pk_fma_f32 v[18:19], v[24:25], v[40:41], v[68:69] op_sel_hi:[0,1,1] neg_lo:[0,0,1] neg_hi:[0,0,1]
	v_pk_mul_f32 v[24:25], v[18:19], v[16:17]
	v_or_b32_e32 v16, 3, v204
	v_mad_i64_i32 v[16:17], s[0:1], v16, s34, v[36:37]
	v_lshl_add_u64 v[52:53], v[16:17], 0, v[154:155]
	v_min_u32_e32 v16, s2, v62
	v_sub_u32_e32 v16, v16, v63
	v_add_u32_e32 v16, 1, v16
	v_cvt_f32_i32_e32 v63, v16
	v_cvt_pk_bf16_f32 v17, v50, v51
	v_cvt_pk_bf16_f32 v16, v54, v55
	v_cvt_pk_bf16_f32 v18, v66, v67
	v_div_scale_f32 v50, s[0:1], v63, v63, 1.0
	v_rcp_f32_e32 v51, v50
	v_cvt_pk_bf16_f32 v19, v24, v25
	global_store_dwordx4 v[52:53], v[16:19], off offset:2048 sc1
	s_nop 1
	v_fma_f32 v16, -v50, v51, 1.0
	v_fmac_f32_e32 v51, v16, v51
	v_div_scale_f32 v16, vcc, 1.0, v63, 1.0
	v_mul_f32_e32 v17, v16, v51
	v_fma_f32 v18, -v50, v17, v16
	v_fmac_f32_e32 v17, v18, v51
	v_fma_f32 v16, -v50, v17, v16
	v_lshlrev_b32_e32 v18, 16, v12
	v_and_b32_e32 v19, 0xffff0000, v12
	v_div_fmas_f32 v16, v16, v51, v17
	v_pk_add_f32 v[24:25], v[18:19], v[30:31] neg_lo:[0,1] neg_hi:[0,1]
	v_div_fixup_f32 v16, v16, v63, 1.0
	v_pk_add_f32 v[24:25], v[28:29], v[24:25]
	s_waitcnt vmcnt(7)
	v_lshlrev_b32_e32 v28, 16, v46
	v_and_b32_e32 v29, 0xffff0000, v46
	v_pk_fma_f32 v[30:31], v[16:17], v[24:25], v[18:19] op_sel_hi:[0,1,1] neg_lo:[0,0,1] neg_hi:[0,0,1]
	v_pk_mul_f32 v[28:29], v[30:31], v[28:29]
	v_lshlrev_b32_e32 v30, 16, v13
	v_and_b32_e32 v31, 0xffff0000, v13
	v_pk_add_f32 v[12:13], v[30:31], v[70:71] neg_lo:[0,1] neg_hi:[0,1]
	v_lshlrev_b32_e32 v50, 16, v14
	v_pk_add_f32 v[38:39], v[38:39], v[12:13]
	v_lshlrev_b32_e32 v12, 16, v47
	v_and_b32_e32 v13, 0xffff0000, v47
	v_pk_fma_f32 v[46:47], v[16:17], v[38:39], v[30:31] op_sel_hi:[0,1,1] neg_lo:[0,0,1] neg_hi:[0,0,1]
	v_and_b32_e32 v51, 0xffff0000, v14
	v_pk_mul_f32 v[46:47], v[46:47], v[12:13]
	v_pk_add_f32 v[12:13], v[50:51], v[72:73] neg_lo:[0,1] neg_hi:[0,1]
	s_nop 0
	v_pk_add_f32 v[52:53], v[64:65], v[12:13]
	v_lshlrev_b32_e32 v12, 16, v48
	v_and_b32_e32 v13, 0xffff0000, v48
	v_pk_fma_f32 v[54:55], v[16:17], v[52:53], v[50:51] op_sel_hi:[0,1,1] neg_lo:[0,0,1] neg_hi:[0,0,1]
	v_lshlrev_b32_e32 v64, 16, v15
	v_and_b32_e32 v65, 0xffff0000, v15
	v_pk_mul_f32 v[54:55], v[54:55], v[12:13]
	v_pk_add_f32 v[12:13], v[64:65], v[78:79] neg_lo:[0,1] neg_hi:[0,1]
	s_nop 0
	v_pk_add_f32 v[40:41], v[40:41], v[12:13]
	v_lshlrev_b32_e32 v12, 16, v49
	v_and_b32_e32 v13, 0xffff0000, v49
	v_pk_fma_f32 v[14:15], v[16:17], v[40:41], v[64:65] op_sel_hi:[0,1,1] neg_lo:[0,0,1] neg_hi:[0,0,1]
	v_pk_mul_f32 v[16:17], v[14:15], v[12:13]
	v_or_b32_e32 v12, 4, v204
	v_mad_i64_i32 v[12:13], s[0:1], v12, s34, v[36:37]
	v_lshl_add_u64 v[48:49], v[12:13], 0, v[154:155]
	v_min_u32_e32 v12, s2, v61
	v_sub_u32_e32 v12, v12, v62
	v_add_u32_e32 v12, 1, v12
	v_cvt_f32_i32_e32 v62, v12
	v_cvt_pk_bf16_f32 v12, v28, v29
	v_cvt_pk_bf16_f32 v13, v46, v47
	v_cvt_pk_bf16_f32 v14, v54, v55
	v_div_scale_f32 v28, s[0:1], v62, v62, 1.0
	v_rcp_f32_e32 v29, v28
	v_cvt_pk_bf16_f32 v15, v16, v17
	global_store_dwordx4 v[48:49], v[12:15], off offset:2048 sc1
	s_nop 1
	v_fma_f32 v12, -v28, v29, 1.0
	v_fmac_f32_e32 v29, v12, v29
	v_div_scale_f32 v12, vcc, 1.0, v62, 1.0
	v_mul_f32_e32 v13, v12, v29
	v_fma_f32 v14, -v28, v13, v12
	v_fmac_f32_e32 v13, v14, v29
	v_fma_f32 v12, -v28, v13, v12
	v_lshlrev_b32_e32 v14, 16, v8
	v_and_b32_e32 v15, 0xffff0000, v8
	v_div_fmas_f32 v12, v12, v29, v13
	v_pk_add_f32 v[16:17], v[14:15], v[26:27] neg_lo:[0,1] neg_hi:[0,1]
	v_div_fixup_f32 v12, v12, v62, 1.0
	v_pk_add_f32 v[16:17], v[24:25], v[16:17]
	s_waitcnt vmcnt(7)
	v_lshlrev_b32_e32 v24, 16, v42
	v_and_b32_e32 v25, 0xffff0000, v42
	v_pk_fma_f32 v[26:27], v[12:13], v[16:17], v[14:15] op_sel_hi:[0,1,1] neg_lo:[0,0,1] neg_hi:[0,0,1]
	v_pk_mul_f32 v[24:25], v[26:27], v[24:25]
	v_lshlrev_b32_e32 v26, 16, v9
	v_and_b32_e32 v27, 0xffff0000, v9
	v_pk_add_f32 v[8:9], v[26:27], v[56:57] neg_lo:[0,1] neg_hi:[0,1]
	v_lshlrev_b32_e32 v42, 16, v10
	v_pk_add_f32 v[28:29], v[38:39], v[8:9]
	v_lshlrev_b32_e32 v8, 16, v43
	v_and_b32_e32 v9, 0xffff0000, v43
	v_pk_fma_f32 v[38:39], v[12:13], v[28:29], v[26:27] op_sel_hi:[0,1,1] neg_lo:[0,0,1] neg_hi:[0,0,1]
	v_and_b32_e32 v43, 0xffff0000, v10
	v_pk_mul_f32 v[38:39], v[38:39], v[8:9]
	v_pk_add_f32 v[8:9], v[42:43], v[58:59] neg_lo:[0,1] neg_hi:[0,1]
	s_nop 0
	v_pk_add_f32 v[46:47], v[52:53], v[8:9]
	v_lshlrev_b32_e32 v8, 16, v44
	v_and_b32_e32 v9, 0xffff0000, v44
	v_pk_fma_f32 v[48:49], v[12:13], v[46:47], v[42:43] op_sel_hi:[0,1,1] neg_lo:[0,0,1] neg_hi:[0,0,1]
	v_lshlrev_b32_e32 v52, 16, v11
	v_and_b32_e32 v53, 0xffff0000, v11
	v_pk_mul_f32 v[48:49], v[48:49], v[8:9]
	v_pk_add_f32 v[8:9], v[52:53], v[68:69] neg_lo:[0,1] neg_hi:[0,1]
	s_nop 0
	v_pk_add_f32 v[40:41], v[40:41], v[8:9]
	v_lshlrev_b32_e32 v8, 16, v45
	v_and_b32_e32 v9, 0xffff0000, v45
	v_pk_fma_f32 v[10:11], v[12:13], v[40:41], v[52:53] op_sel_hi:[0,1,1] neg_lo:[0,0,1] neg_hi:[0,0,1]
	v_pk_mul_f32 v[12:13], v[10:11], v[8:9]
	v_or_b32_e32 v8, 5, v204
	v_mad_i64_i32 v[8:9], s[0:1], v8, s34, v[36:37]
	v_lshl_add_u64 v[44:45], v[8:9], 0, v[154:155]
	v_min_u32_e32 v8, s2, v60
	v_sub_u32_e32 v8, v8, v61
	v_add_u32_e32 v8, 1, v8
	v_cvt_f32_i32_e32 v54, v8
	v_cvt_pk_bf16_f32 v8, v24, v25
	v_cvt_pk_bf16_f32 v9, v38, v39
	v_cvt_pk_bf16_f32 v10, v48, v49
	v_div_scale_f32 v24, s[0:1], v54, v54, 1.0
	v_rcp_f32_e32 v25, v24
	v_cvt_pk_bf16_f32 v11, v12, v13
	global_store_dwordx4 v[44:45], v[8:11], off offset:2048 sc1
	s_nop 1
	v_fma_f32 v8, -v24, v25, 1.0
	v_fmac_f32_e32 v25, v8, v25
	v_div_scale_f32 v8, vcc, 1.0, v54, 1.0
	v_mul_f32_e32 v9, v8, v25
	v_fma_f32 v10, -v24, v9, v8
	v_fmac_f32_e32 v9, v10, v25
	v_fma_f32 v8, -v24, v9, v8
	v_lshlrev_b32_e32 v10, 16, v4
	v_and_b32_e32 v11, 0xffff0000, v4
	v_div_fmas_f32 v8, v8, v25, v9
	v_pk_add_f32 v[12:13], v[10:11], v[18:19] neg_lo:[0,1] neg_hi:[0,1]
	v_div_fixup_f32 v8, v8, v54, 1.0
	v_pk_add_f32 v[12:13], v[16:17], v[12:13]
	s_waitcnt vmcnt(7)
	v_lshlrev_b32_e32 v16, 16, v32
	v_and_b32_e32 v17, 0xffff0000, v32
	v_pk_fma_f32 v[10:11], v[8:9], v[12:13], v[10:11] op_sel_hi:[0,1,1] neg_lo:[0,0,1] neg_hi:[0,0,1]
	v_lshlrev_b32_e32 v4, 16, v5
	v_and_b32_e32 v5, 0xffff0000, v5
	v_pk_mul_f32 v[10:11], v[10:11], v[16:17]
	v_pk_add_f32 v[16:17], v[4:5], v[30:31] neg_lo:[0,1] neg_hi:[0,1]
	v_lshlrev_b32_e32 v18, 16, v33
	v_pk_add_f32 v[16:17], v[28:29], v[16:17]
	v_and_b32_e32 v19, 0xffff0000, v33
	v_pk_fma_f32 v[4:5], v[8:9], v[16:17], v[4:5] op_sel_hi:[0,1,1] neg_lo:[0,0,1] neg_hi:[0,0,1]
	v_pk_mul_f32 v[18:19], v[4:5], v[18:19]
	v_lshlrev_b32_e32 v4, 16, v6
	v_and_b32_e32 v5, 0xffff0000, v6
	v_pk_add_f32 v[24:25], v[4:5], v[50:51] neg_lo:[0,1] neg_hi:[0,1]
	v_lshlrev_b32_e32 v28, 16, v34
	v_pk_add_f32 v[24:25], v[46:47], v[24:25]
	v_and_b32_e32 v29, 0xffff0000, v34
	v_pk_fma_f32 v[4:5], v[8:9], v[24:25], v[4:5] op_sel_hi:[0,1,1] neg_lo:[0,0,1] neg_hi:[0,0,1]
	v_pk_mul_f32 v[28:29], v[4:5], v[28:29]
	v_lshlrev_b32_e32 v4, 16, v7
	v_and_b32_e32 v5, 0xffff0000, v7
	v_pk_add_f32 v[6:7], v[4:5], v[64:65] neg_lo:[0,1] neg_hi:[0,1]
	s_nop 0
	v_pk_add_f32 v[30:31], v[40:41], v[6:7]
	v_lshlrev_b32_e32 v6, 16, v35
	v_and_b32_e32 v7, 0xffff0000, v35
	v_pk_fma_f32 v[4:5], v[8:9], v[30:31], v[4:5] op_sel_hi:[0,1,1] neg_lo:[0,0,1] neg_hi:[0,0,1]
	v_pk_mul_f32 v[8:9], v[4:5], v[6:7]
	v_or_b32_e32 v4, 6, v204
	v_mad_i64_i32 v[4:5], s[0:1], v4, s34, v[36:37]
	v_lshl_add_u64 v[32:33], v[4:5], 0, v[154:155]
	v_add_u32_e32 v4, 8, v206
	v_min_u32_e32 v4, s2, v4
	v_sub_u32_e32 v4, v4, v60
	v_add_u32_e32 v4, 1, v4
	v_cvt_f32_i32_e32 v34, v4
	v_cvt_pk_bf16_f32 v4, v10, v11
	v_cvt_pk_bf16_f32 v5, v18, v19
	v_cvt_pk_bf16_f32 v6, v28, v29
	v_div_scale_f32 v10, s[0:1], v34, v34, 1.0
	v_rcp_f32_e32 v11, v10
	v_cvt_pk_bf16_f32 v7, v8, v9
	global_store_dwordx4 v[32:33], v[4:7], off offset:2048 sc1
	s_nop 1
	v_fma_f32 v4, -v10, v11, 1.0
	v_fmac_f32_e32 v11, v4, v11
	v_div_scale_f32 v4, vcc, 1.0, v34, 1.0
	v_mul_f32_e32 v5, v4, v11
	v_fma_f32 v6, -v10, v5, v4
	v_fmac_f32_e32 v5, v6, v11
	v_fma_f32 v4, -v10, v5, v4
	v_lshlrev_b32_e32 v6, 16, v0
	v_and_b32_e32 v7, 0xffff0000, v0
	v_div_fmas_f32 v4, v4, v11, v5
	v_pk_add_f32 v[8:9], v[6:7], v[14:15] neg_lo:[0,1] neg_hi:[0,1]
	v_div_fixup_f32 v4, v4, v34, 1.0
	v_pk_add_f32 v[8:9], v[12:13], v[8:9]
	v_lshlrev_b32_e32 v0, 16, v1
	v_and_b32_e32 v1, 0xffff0000, v1
	v_pk_fma_f32 v[6:7], v[4:5], v[8:9], v[6:7] op_sel_hi:[0,1,1] neg_lo:[0,0,1] neg_hi:[0,0,1]
	v_pk_add_f32 v[8:9], v[0:1], v[26:27] neg_lo:[0,1] neg_hi:[0,1]
	s_waitcnt vmcnt(7)
	v_lshlrev_b32_e32 v10, 16, v20
	v_and_b32_e32 v11, 0xffff0000, v20
	v_pk_add_f32 v[8:9], v[16:17], v[8:9]
	v_pk_mul_f32 v[6:7], v[6:7], v[10:11]
	v_lshlrev_b32_e32 v10, 16, v21
	v_and_b32_e32 v11, 0xffff0000, v21
	v_pk_fma_f32 v[0:1], v[4:5], v[8:9], v[0:1] op_sel_hi:[0,1,1] neg_lo:[0,0,1] neg_hi:[0,0,1]
	v_pk_mul_f32 v[8:9], v[0:1], v[10:11]
	v_lshlrev_b32_e32 v0, 16, v2
	v_and_b32_e32 v1, 0xffff0000, v2
	v_pk_add_f32 v[10:11], v[0:1], v[42:43] neg_lo:[0,1] neg_hi:[0,1]
	v_lshlrev_b32_e32 v12, 16, v22
	v_pk_add_f32 v[10:11], v[24:25], v[10:11]
	v_and_b32_e32 v13, 0xffff0000, v22
	v_pk_fma_f32 v[0:1], v[4:5], v[10:11], v[0:1] op_sel_hi:[0,1,1] neg_lo:[0,0,1] neg_hi:[0,0,1]
	v_pk_mul_f32 v[10:11], v[0:1], v[12:13]
	v_lshlrev_b32_e32 v0, 16, v3
	v_and_b32_e32 v1, 0xffff0000, v3
	v_pk_add_f32 v[2:3], v[0:1], v[52:53] neg_lo:[0,1] neg_hi:[0,1]
	v_lshlrev_b32_e32 v12, 16, v23
	v_pk_add_f32 v[2:3], v[30:31], v[2:3]
	v_and_b32_e32 v13, 0xffff0000, v23
	v_pk_fma_f32 v[0:1], v[4:5], v[2:3], v[0:1] op_sel_hi:[0,1,1] neg_lo:[0,0,1] neg_hi:[0,0,1]
	v_pk_mul_f32 v[4:5], v[0:1], v[12:13]
	v_or_b32_e32 v0, 7, v204
	v_mad_i64_i32 v[0:1], s[0:1], v0, s34, v[36:37]
	v_lshl_add_u64 v[12:13], v[0:1], 0, v[154:155]
	v_cvt_pk_bf16_f32 v0, v6, v7
	v_cvt_pk_bf16_f32 v1, v8, v9
	v_cvt_pk_bf16_f32 v2, v10, v11
	v_cvt_pk_bf16_f32 v3, v4, v5
	global_store_dwordx4 v[12:13], v[0:3], off offset:2048 sc1
	s_branch .LBB0_148

.LBB0_310:
	global_load_dwordx4 v[60:63], v[72:73], off
	global_load_dwordx4 v[44:47], v[72:73], off offset:1024
	global_load_dwordx4 v[28:31], v[72:73], off offset:2048
	global_load_dwordx4 v[0:3], v[72:73], off offset:3072
	v_add_co_u32_e32 v4, vcc, 0x1000, v72
	s_add_i32 s0, s0, s30
	s_nop 0
	v_addc_co_u32_e32 v5, vcc, 0, v73, vcc
	global_load_dwordx4 v[64:67], v[4:5], off
	global_load_dwordx4 v[40:43], v[4:5], off offset:1024
	global_load_dwordx4 v[24:27], v[4:5], off offset:2048
	s_nop 0
	global_load_dwordx4 v[4:7], v[4:5], off offset:3072
	v_add_co_u32_e32 v8, vcc, s69, v72
	s_cmpk_lt_i32 s0, 0x4000
	s_nop 0
	v_addc_co_u32_e32 v9, vcc, 0, v73, vcc
	v_add_co_u32_e32 v10, vcc, s64, v72
	s_waitcnt vmcnt(7)
	v_pk_mul_f32 v[52:53], v[62:63], v[62:63]
	v_addc_co_u32_e32 v11, vcc, 0, v73, vcc
	global_load_dwordx4 v[56:59], v[10:11], off offset:-4096
	global_load_dwordx4 v[36:39], v[8:9], off offset:1024
	global_load_dwordx4 v[20:23], v[8:9], off offset:2048
	global_load_dwordx4 v[12:15], v[8:9], off offset:3072
	global_load_dwordx4 v[48:51], v[10:11], off
	global_load_dwordx4 v[32:35], v[10:11], off offset:1024
	global_load_dwordx4 v[16:19], v[10:11], off offset:2048
	s_nop 0
	global_load_dwordx4 v[8:11], v[10:11], off offset:3072
	v_pk_mul_f32 v[54:55], v[60:61], v[60:61]
	v_lshl_add_u64 v[72:73], v[72:73], 0, s[66:67]
	v_pk_mov_b32 v[74:75], v[54:55], v[52:53] op_sel:[1,0]
	v_mov_b32_e32 v55, v53
	v_pk_add_f32 v[52:53], v[74:75], v[54:55]
	s_waitcnt vmcnt(14)
	v_pk_mul_f32 v[54:55], v[46:47], v[46:47]
	v_pk_mul_f32 v[74:75], v[44:45], v[44:45]
	v_pk_add_f32 v[52:53], v[52:53], v[52:53] op_sel:[0,1] op_sel_hi:[1,0]
	v_pk_mov_b32 v[76:77], v[74:75], v[54:55] op_sel:[1,0]
	v_mov_b32_e32 v75, v55
	v_pk_add_f32 v[54:55], v[76:77], v[74:75]
	s_waitcnt vmcnt(12)
	v_mul_f32_e32 v74, v0, v0
	v_mul_f32_e32 v75, v1, v1
	v_pk_add_f32 v[54:55], v[54:55], v[54:55] op_sel:[0,1] op_sel_hi:[1,0]
	v_mov_b32_e32 v53, v74
	v_mov_b32_e32 v55, v75
	v_pk_add_f32 v[52:53], v[52:53], v[54:55]
	v_mul_f32_e32 v54, v29, v29
	v_mul_f32_e32 v74, v31, v31
	v_mul_f32_e32 v76, v2, v2
	v_mul_f32_e32 v77, v3, v3
	v_pk_fma_f32 v[54:55], v[28:29], v[28:29], v[54:55] op_sel_hi:[1,1,0]
	v_pk_fma_f32 v[74:75], v[30:31], v[30:31], v[74:75] op_sel_hi:[1,1,0]
	v_mov_b32_e32 v55, v76
	v_mov_b32_e32 v75, v77
	v_pk_add_f32 v[54:55], v[54:55], v[74:75]
	s_nop 0
	v_pk_add_f32 v[74:75], v[52:53], v[54:55]
	s_waitcnt vmcnt(11)
	v_pk_mul_f32 v[52:53], v[66:67], v[66:67]
	v_pk_mul_f32 v[54:55], v[64:65], v[64:65]
	s_nop 0
	v_pk_mov_b32 v[76:77], v[54:55], v[52:53] op_sel:[1,0]
	v_mov_b32_e32 v55, v53
	v_pk_add_f32 v[52:53], v[76:77], v[54:55]
	s_waitcnt vmcnt(10)
	v_pk_mul_f32 v[54:55], v[42:43], v[42:43]
	v_pk_mul_f32 v[76:77], v[40:41], v[40:41]
	v_pk_add_f32 v[52:53], v[52:53], v[52:53] op_sel:[0,1] op_sel_hi:[1,0]
	v_pk_mov_b32 v[78:79], v[76:77], v[54:55] op_sel:[1,0]
	v_mov_b32_e32 v77, v55
	v_pk_add_f32 v[54:55], v[78:79], v[76:77]
	s_waitcnt vmcnt(8)
	v_mul_f32_e32 v76, v4, v4
	v_mul_f32_e32 v77, v5, v5
	v_pk_add_f32 v[54:55], v[54:55], v[54:55] op_sel:[0,1] op_sel_hi:[1,0]
	v_mov_b32_e32 v53, v76
	v_mov_b32_e32 v55, v77
	v_pk_add_f32 v[52:53], v[52:53], v[54:55]
	v_mul_f32_e32 v54, v25, v25
	v_mul_f32_e32 v76, v27, v27
	v_mul_f32_e32 v78, v6, v6
	v_mul_f32_e32 v79, v7, v7
	v_pk_fma_f32 v[54:55], v[24:25], v[24:25], v[54:55] op_sel_hi:[1,1,0]
	v_pk_fma_f32 v[76:77], v[26:27], v[26:27], v[76:77] op_sel_hi:[1,1,0]
	v_mov_b32_e32 v55, v78
	v_mov_b32_e32 v77, v79
	v_pk_add_f32 v[54:55], v[54:55], v[76:77]
	s_nop 0
	v_pk_add_f32 v[80:81], v[52:53], v[54:55]
	s_waitcnt vmcnt(7)
	v_pk_mul_f32 v[52:53], v[58:59], v[58:59]
	v_pk_mul_f32 v[54:55], v[56:57], v[56:57]
	s_nop 0
	v_pk_mov_b32 v[76:77], v[54:55], v[52:53] op_sel:[1,0]
	v_mov_b32_e32 v55, v53
	v_pk_add_f32 v[52:53], v[76:77], v[54:55]
	s_waitcnt vmcnt(6)
	v_pk_mul_f32 v[54:55], v[38:39], v[38:39]
	v_pk_mul_f32 v[76:77], v[36:37], v[36:37]
	v_pk_add_f32 v[52:53], v[52:53], v[52:53] op_sel:[0,1] op_sel_hi:[1,0]
	v_pk_mov_b32 v[78:79], v[76:77], v[54:55] op_sel:[1,0]
	v_mov_b32_e32 v77, v55
	v_pk_add_f32 v[54:55], v[78:79], v[76:77]
	s_waitcnt vmcnt(4)
	v_mul_f32_e32 v76, v12, v12
	v_mul_f32_e32 v77, v13, v13
	v_pk_add_f32 v[54:55], v[54:55], v[54:55] op_sel:[0,1] op_sel_hi:[1,0]
	v_mov_b32_e32 v53, v76
	v_mov_b32_e32 v55, v77
	v_pk_add_f32 v[52:53], v[52:53], v[54:55]
	v_mul_f32_e32 v54, v21, v21
	v_mul_f32_e32 v76, v23, v23
	v_mul_f32_e32 v78, v14, v14
	v_mul_f32_e32 v79, v15, v15
	v_pk_fma_f32 v[54:55], v[20:21], v[20:21], v[54:55] op_sel_hi:[1,1,0]
	v_pk_fma_f32 v[76:77], v[22:23], v[22:23], v[76:77] op_sel_hi:[1,1,0]
	v_mov_b32_e32 v55, v78
	v_mov_b32_e32 v77, v79
	v_pk_add_f32 v[54:55], v[54:55], v[76:77]
	s_nop 0
	v_pk_add_f32 v[76:77], v[52:53], v[54:55]
	s_waitcnt vmcnt(3)
	v_pk_mul_f32 v[52:53], v[50:51], v[50:51]
	v_pk_mul_f32 v[54:55], v[48:49], v[48:49]
	s_nop 0
	v_pk_mov_b32 v[78:79], v[54:55], v[52:53] op_sel:[1,0]
	v_mov_b32_e32 v55, v53
	v_pk_add_f32 v[52:53], v[78:79], v[54:55]
	s_waitcnt vmcnt(2)
	v_pk_mul_f32 v[54:55], v[34:35], v[34:35]
	v_pk_mul_f32 v[78:79], v[32:33], v[32:33]
	v_pk_add_f32 v[52:53], v[52:53], v[52:53] op_sel:[0,1] op_sel_hi:[1,0]
	v_pk_mov_b32 v[88:89], v[78:79], v[54:55] op_sel:[1,0]
	v_mov_b32_e32 v79, v55
	v_pk_add_f32 v[54:55], v[88:89], v[78:79]
	s_waitcnt vmcnt(0)
	v_mul_f32_e32 v78, v8, v8
	v_mul_f32_e32 v79, v9, v9
	v_pk_add_f32 v[54:55], v[54:55], v[54:55] op_sel:[0,1] op_sel_hi:[1,0]
	v_mov_b32_e32 v53, v78
	v_mov_b32_e32 v55, v79
	v_pk_add_f32 v[52:53], v[52:53], v[54:55]
	v_mul_f32_e32 v54, v17, v17
	v_mul_f32_e32 v78, v19, v19
	v_mul_f32_e32 v88, v10, v10
	v_mul_f32_e32 v89, v11, v11
	v_pk_fma_f32 v[54:55], v[16:17], v[16:17], v[54:55] op_sel_hi:[1,1,0]
	v_pk_fma_f32 v[78:79], v[18:19], v[18:19], v[78:79] op_sel_hi:[1,1,0]
	v_mov_b32_e32 v55, v88
	v_mov_b32_e32 v79, v89
	v_pk_add_f32 v[54:55], v[54:55], v[78:79]
	v_mov_b32_e32 v88, v80
	v_pk_add_f32 v[78:79], v[52:53], v[54:55]
	global_load_dwordx4 v[52:55], v[68:69], off
	v_mov_b32_e32 v89, v74
	v_mov_b32_e32 v74, v81
	v_pk_add_f32 v[74:75], v[88:89], v[74:75]
	ds_bpermute_b32 v81, v82, v75
	ds_bpermute_b32 v80, v82, v74
	s_waitcnt lgkmcnt(0)
	v_pk_add_f32 v[74:75], v[74:75], v[80:81]
	ds_bpermute_b32 v81, v83, v75
	ds_bpermute_b32 v80, v83, v74
	s_waitcnt lgkmcnt(0)
	v_pk_add_f32 v[74:75], v[74:75], v[80:81]
	ds_bpermute_b32 v81, v84, v75
	ds_bpermute_b32 v80, v84, v74
	s_waitcnt lgkmcnt(0)
	v_pk_add_f32 v[74:75], v[74:75], v[80:81]
	ds_bpermute_b32 v81, v85, v75
	ds_bpermute_b32 v80, v85, v74
	s_waitcnt lgkmcnt(0)
	v_pk_add_f32 v[74:75], v[74:75], v[80:81]
	ds_bpermute_b32 v81, v86, v75
	ds_bpermute_b32 v80, v86, v74
	s_waitcnt lgkmcnt(0)
	v_pk_add_f32 v[74:75], v[74:75], v[80:81]
	ds_bpermute_b32 v81, v87, v75
	ds_bpermute_b32 v80, v87, v74
	s_waitcnt lgkmcnt(0)
	v_pk_add_f32 v[74:75], v[74:75], v[80:81]
	v_mov_b64_e32 v[80:81], s[68:69]
	v_pk_fma_f32 v[88:89], v[74:75], s[74:75], v[80:81] op_sel_hi:[1,0,0]
	s_nop 0
	v_mul_f32_e32 v74, 0x4b800000, v89
	v_cmp_gt_f32_e64 s[38:39], s19, v89
	v_cmp_gt_f32_e32 vcc, s19, v88
	s_nop 0
	v_cndmask_b32_e64 v74, v89, v74, s[38:39]
	v_rsq_f32_e32 v74, v74
	s_nop 0
	v_mul_f32_e32 v75, 0x45800000, v74
	v_cndmask_b32_e64 v74, v74, v75, s[38:39]
	v_pk_mul_f32 v[60:61], v[60:61], v[74:75] op_sel_hi:[1,0]
	v_pk_mul_f32 v[62:63], v[62:63], v[74:75] op_sel_hi:[1,0]
	v_pk_mul_f32 v[44:45], v[44:45], v[74:75] op_sel_hi:[1,0]
	v_pk_mul_f32 v[46:47], v[46:47], v[74:75] op_sel_hi:[1,0]
	v_pk_mul_f32 v[28:29], v[28:29], v[74:75] op_sel_hi:[1,0]
	v_pk_mul_f32 v[30:31], v[30:31], v[74:75] op_sel_hi:[1,0]
	v_pk_mul_f32 v[0:1], v[0:1], v[74:75] op_sel_hi:[1,0]
	v_pk_mul_f32 v[2:3], v[2:3], v[74:75] op_sel_hi:[1,0]
	s_waitcnt vmcnt(0)
	v_pk_mul_f32 v[60:61], v[52:53], v[60:61]
	v_pk_mul_f32 v[62:63], v[54:55], v[62:63]
	v_cvt_pk_bf16_f32 v60, v60, v61
	v_cvt_pk_bf16_f32 v61, v62, v63
	global_store_dwordx2 v[70:71], v[60:61], off sc1
	v_mul_f32_e32 v60, 0x4b800000, v88
	v_cndmask_b32_e32 v60, v88, v60, vcc
	v_rsq_f32_e32 v60, v60
	s_nop 0
	v_mul_f32_e32 v61, 0x45800000, v60
	v_cndmask_b32_e32 v60, v60, v61, vcc
	v_pk_mul_f32 v[62:63], v[64:65], v[60:61] op_sel_hi:[1,0]
	v_pk_mul_f32 v[64:65], v[66:67], v[60:61] op_sel_hi:[1,0]
	v_pk_mul_f32 v[62:63], v[52:53], v[62:63]
	v_pk_mul_f32 v[64:65], v[54:55], v[64:65]
	v_cvt_pk_bf16_f32 v62, v62, v63
	v_cvt_pk_bf16_f32 v63, v64, v65
	global_store_dwordx2 v[70:71], v[62:63], off offset:2048 sc1
	v_mov_b32_e32 v62, v78
	v_mov_b32_e32 v63, v76
	v_mov_b32_e32 v76, v79
	v_pk_add_f32 v[62:63], v[62:63], v[76:77]
	ds_bpermute_b32 v65, v82, v63
	ds_bpermute_b32 v64, v82, v62
	s_waitcnt lgkmcnt(0)
	v_pk_add_f32 v[62:63], v[62:63], v[64:65]
	ds_bpermute_b32 v65, v83, v63
	ds_bpermute_b32 v64, v83, v62
	s_waitcnt lgkmcnt(0)
	v_pk_add_f32 v[62:63], v[62:63], v[64:65]
	ds_bpermute_b32 v65, v84, v63
	ds_bpermute_b32 v64, v84, v62
	s_waitcnt lgkmcnt(0)
	v_pk_add_f32 v[62:63], v[62:63], v[64:65]
	ds_bpermute_b32 v65, v85, v63
	ds_bpermute_b32 v64, v85, v62
	s_waitcnt lgkmcnt(0)
	v_pk_add_f32 v[62:63], v[62:63], v[64:65]
	ds_bpermute_b32 v65, v86, v63
	ds_bpermute_b32 v64, v86, v62
	s_waitcnt lgkmcnt(0)
	v_pk_add_f32 v[62:63], v[62:63], v[64:65]
	ds_bpermute_b32 v65, v87, v63
	ds_bpermute_b32 v64, v87, v62
	s_waitcnt lgkmcnt(0)
	v_pk_add_f32 v[62:63], v[62:63], v[64:65]
	s_nop 0
	v_pk_fma_f32 v[64:65], v[62:63], s[74:75], v[80:81] op_sel_hi:[1,0,0]
	s_nop 0
	v_mul_f32_e32 v61, 0x4b800000, v65
	v_cmp_gt_f32_e64 s[38:39], s19, v65
	v_cmp_gt_f32_e32 vcc, s19, v64
	s_nop 0
	v_cndmask_b32_e64 v61, v65, v61, s[38:39]
	v_rsq_f32_e32 v61, v61
	s_nop 0
	v_mul_f32_e32 v62, 0x45800000, v61
	v_cndmask_b32_e64 v62, v61, v62, s[38:39]
	v_pk_mul_f32 v[56:57], v[56:57], v[62:63] op_sel_hi:[1,0]
	v_pk_mul_f32 v[40:41], v[40:41], v[60:61] op_sel_hi:[1,0]
	v_pk_mul_f32 v[56:57], v[52:53], v[56:57]
	v_pk_mul_f32 v[42:43], v[42:43], v[60:61] op_sel_hi:[1,0]
	v_cvt_pk_bf16_f32 v66, v56, v57
	v_pk_mul_f32 v[56:57], v[58:59], v[62:63] op_sel_hi:[1,0]
	v_mul_f32_e32 v58, 0x4b800000, v64
	v_cndmask_b32_e32 v58, v64, v58, vcc
	v_rsq_f32_e32 v58, v58
	v_pk_mul_f32 v[56:57], v[54:55], v[56:57]
	v_pk_mul_f32 v[36:37], v[36:37], v[62:63] op_sel_hi:[1,0]
	v_cvt_pk_bf16_f32 v67, v56, v57
	v_mul_f32_e32 v59, 0x45800000, v58
	v_cndmask_b32_e32 v58, v58, v59, vcc
	v_pk_mul_f32 v[48:49], v[48:49], v[58:59] op_sel_hi:[1,0]
	v_pk_mul_f32 v[50:51], v[50:51], v[58:59] op_sel_hi:[1,0]
	v_add_co_u32_e64 v56, s[38:39], s46, v70
	v_pk_mul_f32 v[48:49], v[52:53], v[48:49]
	v_pk_mul_f32 v[50:51], v[54:55], v[50:51]
	v_addc_co_u32_e64 v57, s[38:39], 0, v71, s[38:39]
	v_cvt_pk_bf16_f32 v48, v48, v49
	v_cvt_pk_bf16_f32 v49, v50, v51
	global_store_dwordx2 v[56:57], v[66:67], off sc1
	global_store_dwordx2 v[56:57], v[48:49], off offset:2048 sc1
	global_load_dwordx4 v[48:51], v[68:69], off offset:1024
	v_pk_mul_f32 v[38:39], v[38:39], v[62:63] op_sel_hi:[1,0]
	v_pk_mul_f32 v[32:33], v[32:33], v[58:59] op_sel_hi:[1,0]
	v_pk_mul_f32 v[34:35], v[34:35], v[58:59] op_sel_hi:[1,0]
	v_pk_mul_f32 v[24:25], v[24:25], v[60:61] op_sel_hi:[1,0]
	v_pk_mul_f32 v[26:27], v[26:27], v[60:61] op_sel_hi:[1,0]
	v_pk_mul_f32 v[20:21], v[20:21], v[62:63] op_sel_hi:[1,0]
	v_pk_mul_f32 v[22:23], v[22:23], v[62:63] op_sel_hi:[1,0]
	v_pk_mul_f32 v[16:17], v[16:17], v[58:59] op_sel_hi:[1,0]
	v_pk_mul_f32 v[18:19], v[18:19], v[58:59] op_sel_hi:[1,0]
	s_waitcnt vmcnt(0)
	v_pk_mul_f32 v[44:45], v[48:49], v[44:45]
	v_pk_mul_f32 v[46:47], v[50:51], v[46:47]
	v_pk_mul_f32 v[40:41], v[48:49], v[40:41]
	v_pk_mul_f32 v[42:43], v[50:51], v[42:43]
	v_pk_mul_f32 v[36:37], v[48:49], v[36:37]
	v_pk_mul_f32 v[38:39], v[50:51], v[38:39]
	v_pk_mul_f32 v[32:33], v[48:49], v[32:33]
	v_pk_mul_f32 v[34:35], v[50:51], v[34:35]
	v_cvt_pk_bf16_f32 v44, v44, v45
	v_cvt_pk_bf16_f32 v45, v46, v47
	v_cvt_pk_bf16_f32 v40, v40, v41
	v_cvt_pk_bf16_f32 v41, v42, v43
	v_cvt_pk_bf16_f32 v36, v36, v37
	v_cvt_pk_bf16_f32 v37, v38, v39
	v_cvt_pk_bf16_f32 v32, v32, v33
	v_cvt_pk_bf16_f32 v33, v34, v35
	global_store_dwordx2 v[70:71], v[44:45], off offset:512 sc1
	global_store_dwordx2 v[70:71], v[40:41], off offset:2560 sc1
	global_store_dwordx2 v[56:57], v[36:37], off offset:512 sc1
	global_store_dwordx2 v[56:57], v[32:33], off offset:2560 sc1
	global_load_dwordx4 v[32:35], v[68:69], off offset:2048
	s_waitcnt vmcnt(0)
	v_pk_mul_f32 v[28:29], v[28:29], v[32:33]
	v_pk_mul_f32 v[30:31], v[30:31], v[34:35]
	v_pk_mul_f32 v[24:25], v[24:25], v[32:33]
	v_pk_mul_f32 v[26:27], v[26:27], v[34:35]
	v_pk_mul_f32 v[20:21], v[20:21], v[32:33]
	v_pk_mul_f32 v[22:23], v[22:23], v[34:35]
	v_pk_mul_f32 v[16:17], v[16:17], v[32:33]
	v_pk_mul_f32 v[18:19], v[18:19], v[34:35]
	v_cvt_pk_bf16_f32 v28, v28, v29
	v_cvt_pk_bf16_f32 v29, v30, v31
	v_cvt_pk_bf16_f32 v24, v24, v25
	v_cvt_pk_bf16_f32 v25, v26, v27
	v_cvt_pk_bf16_f32 v20, v20, v21
	v_cvt_pk_bf16_f32 v21, v22, v23
	v_cvt_pk_bf16_f32 v16, v16, v17
	v_cvt_pk_bf16_f32 v17, v18, v19
	global_store_dwordx2 v[70:71], v[28:29], off offset:1024 sc1
	global_store_dwordx2 v[70:71], v[24:25], off offset:3072 sc1
	global_store_dwordx2 v[56:57], v[20:21], off offset:1024 sc1
	global_store_dwordx2 v[56:57], v[16:17], off offset:3072 sc1
	global_load_dwordx4 v[16:19], v[68:69], off offset:3072
	s_waitcnt vmcnt(0)
	v_pk_mul_f32 v[0:1], v[0:1], v[16:17]
	v_pk_mul_f32 v[2:3], v[2:3], v[18:19]
	v_cvt_pk_bf16_f32 v0, v0, v1
	v_cvt_pk_bf16_f32 v1, v2, v3
	global_store_dwordx2 v[70:71], v[0:1], off offset:1536 sc1
	v_pk_mul_f32 v[0:1], v[4:5], v[60:61] op_sel_hi:[1,0]
	v_pk_mul_f32 v[2:3], v[6:7], v[60:61] op_sel_hi:[1,0]
	v_pk_mul_f32 v[0:1], v[0:1], v[16:17]
	v_pk_mul_f32 v[2:3], v[2:3], v[18:19]
	v_cvt_pk_bf16_f32 v0, v0, v1
	v_cvt_pk_bf16_f32 v1, v2, v3
	global_store_dwordx2 v[70:71], v[0:1], off offset:3584 sc1
	v_pk_mul_f32 v[0:1], v[12:13], v[62:63] op_sel_hi:[1,0]
	v_pk_mul_f32 v[2:3], v[14:15], v[62:63] op_sel_hi:[1,0]
	v_pk_mul_f32 v[0:1], v[0:1], v[16:17]
	v_pk_mul_f32 v[2:3], v[2:3], v[18:19]
	v_cvt_pk_bf16_f32 v0, v0, v1
	v_cvt_pk_bf16_f32 v1, v2, v3
	global_store_dwordx2 v[56:57], v[0:1], off offset:1536 sc1
	v_pk_mul_f32 v[0:1], v[8:9], v[58:59] op_sel_hi:[1,0]
	v_pk_mul_f32 v[2:3], v[10:11], v[58:59] op_sel_hi:[1,0]
	v_pk_mul_f32 v[0:1], v[0:1], v[16:17]
	v_pk_mul_f32 v[2:3], v[2:3], v[18:19]
	v_cvt_pk_bf16_f32 v0, v0, v1
	v_cvt_pk_bf16_f32 v1, v2, v3
	v_lshl_add_u64 v[70:71], v[70:71], 0, s[70:71]
	global_store_dwordx2 v[56:57], v[0:1], off offset:3584 sc1
	s_cbranch_scc1 .LBB0_310
